# latent-scan units pre-assigned to blocks 0..95 (no queue round trip, unpaired CUs); 3-tile-deep weight conversion pipeline; LSCAN nop slots filled
# speedup vs baseline: 1.0606x; 1.0063x over previous
.LBB0_149:
	v_readlane_b32 s100, v242, 0
	s_nop 0
	s_cmpk_ge_u32 s100, 0x180
	s_cbranch_scc1 .Lwc0_ng
	s_add_u32 s100, s100, 0x600
	s_movk_i32 s67, 0x180
	s_movk_i32 s66, 0xbc0
	s_branch .Lwc0_set
.Lwc0_ng:
	s_sub_u32 s100, s100, 0x180
	s_movk_i32 s67, 0x80
	s_movk_i32 s66, 0x600
.Lwc0_set:
	s_waitcnt vmcnt(0) lgkmcnt(0)
	s_barrier
	v_readlane_b32 s0, v242, 42
	v_readlane_b32 s1, v242, 43
	v_readlane_b32 s4, v242, 3
	v_readlane_b32 s5, v242, 4
	v_lshrrev_b32_e32 v209, 6, v137
	v_and_b32_e32 v210, 63, v137
	s_sub_u32 s0, s0, 0x118
	s_subb_u32 s1, s1, 0
	v_lshrrev_b32_e32 v211, 3, v137
	v_and_b32_e32 v212, 7, v137
	v_mul_u32_u24_e32 v202, 65, v209
	v_mul_u32_u24_e32 v203, 0x208, v212
	v_add_u32_e32 v202, v202, v210
	v_add_u32_e32 v203, v203, v211
	v_lshlrev_b32_e32 v202, 2, v202
	v_lshlrev_b32_e32 v203, 2, v203
	v_lshlrev_b32_e32 v210, 2, v210
	v_lshlrev_b32_e32 v212, 4, v212
	v_add_u32_e32 v204, 0x400, v203
	v_add_u32_e32 v205, 0x80, v203
	v_add_u32_e32 v206, 0x480, v203
	s_cmp_ge_u32 s100, s66
	s_cbranch_scc1 .Lwc0_done
	s_cmpk_ge_u32 s100, 0x900
	s_cbranch_scc1 .Lwc0_t3_1
	s_cmpk_ge_u32 s100, 0x380
	s_cbranch_scc1 .Lwc0_t2_1
	s_cmpk_ge_u32 s100, 0x280
	s_cbranch_scc1 .Lwc0_t1_1
	s_movk_i32 s41, 0x78
	s_sub_u32 s99, s100, 0
	s_mul_i32 s44, s99, 0x66667
	s_lshr_b32 s44, s44, 24
	s_mul_i32 s36, s44, 40
	s_sub_u32 s99, s99, s36
	s_mul_i32 s38, s44, 0xa0000
	s_lshl_b32 s36, s99, 8
	s_add_u32 s38, s38, s36
	s_add_u32 s38, s38, 0x0
	s_lshl_b32 s36, s99, 6
	s_mov_b32 s32, 0x10000
	s_mul_i32 s36, s36, 0x800
	s_lshl_b32 s44, s44, 7
	s_add_u32 s36, s36, s44
	s_add_u32 s36, s36, 0x0
	s_mov_b32 s37, 0xa000
	s_movk_i32 s44, 0x800
	s_mov_b32 s99, 0x2800
	s_branch .Lwc0_tj_1
.Lwc0_t1_1:
	s_movk_i32 s41, 0x80
	s_sub_u32 s99, s100, 640
	s_mul_i32 s44, s99, 0x100000
	s_lshr_b32 s44, s44, 24
	s_mul_i32 s36, s44, 16
	s_sub_u32 s99, s99, s36
	s_mul_i32 s38, s44, 0x40000
	s_lshl_b32 s36, s99, 8
	s_add_u32 s38, s38, s36
	s_add_u32 s38, s38, 0x0
	s_lshl_b32 s36, s99, 6
	s_mov_b32 s32, 0x10000
	s_mul_i32 s36, s36, 0x800
	s_lshl_b32 s44, s44, 7
	s_add_u32 s36, s36, s44
	s_add_u32 s36, s36, 0xa00000
	s_mov_b32 s37, 0x4000
	s_movk_i32 s44, 0x800
	s_mov_b32 s99, 0x1000
	s_branch .Lwc0_tj_1
.Lwc0_t2_1:
	s_movk_i32 s41, 0xf0
	s_sub_u32 s99, s100, 896
	s_mul_i32 s44, s99, 0x2e8bb
	s_lshr_b32 s44, s44, 24
	s_mul_i32 s36, s44, 88
	s_sub_u32 s99, s99, s36
	s_mul_i32 s38, s44, 0x160000
	s_lshl_b32 s36, s99, 8
	s_add_u32 s38, s38, s36
	s_add_u32 s38, s38, 0x0
	s_cmpk_ge_u32 s99, 44
	s_cselect_b32 s36, 44, 0
	s_cselect_b32 s37, 32, 0
	s_sub_u32 s36, s99, s36
	s_lshl_b32 s36, s36, 7
	s_add_u32 s36, s36, s37
	s_mov_b32 s32, 0x20000
	s_mul_i32 s36, s36, 0x800
	s_lshl_b32 s44, s44, 7
	s_add_u32 s36, s36, s44
	s_add_u32 s36, s36, 0xe00000
	s_mov_b32 s37, 0x16000
	s_movk_i32 s44, 0x800
	s_mov_b32 s99, 0x5800
	s_branch .Lwc0_tj_1
.Lwc0_t3_1:
	s_movk_i32 s41, 0xf8
	s_sub_u32 s99, s100, 2304
	s_mul_i32 s44, s99, 0x100000
	s_lshr_b32 s44, s44, 24
	s_mul_i32 s36, s44, 16
	s_sub_u32 s99, s99, s36
	s_mul_i32 s38, s44, 0x40000
	s_lshl_b32 s36, s99, 8
	s_add_u32 s38, s38, s36
	s_add_u32 s38, s38, 0x0
	s_lshl_b32 s36, s99, 6
	s_mov_b32 s32, 0x2c000
	s_mul_i32 s36, s36, 0x1600
	s_lshl_b32 s44, s44, 7
	s_add_u32 s36, s36, s44
	s_add_u32 s36, s36, 0x2400000
	s_mov_b32 s37, 0x4000
	s_movk_i32 s44, 0x1600
	s_mov_b32 s99, 0x1000
.Lwc0_tj_1:
	s_load_dwordx2 s[2:3], s[0:1], s41
	s_add_u32 s52, s4, s36
	s_addc_u32 s53, s5, 0
	v_mad_u32_u24 v207, v209, s99, v210
	v_writelane_b32 v213, s52, 8
	v_writelane_b32 v213, s53, 9
	v_writelane_b32 v213, s32, 10
	v_writelane_b32 v213, s44, 11
	s_add_u32 s100, s100, s67
	s_waitcnt lgkmcnt(0)
	s_add_u32 s38, s2, s38
	s_addc_u32 s39, s3, 0
	global_load_dword v138, v207, s[38:39]
	s_add_u32 s38, s38, s37
	s_addc_u32 s39, s39, 0
	global_load_dword v139, v207, s[38:39]
	s_add_u32 s38, s38, s37
	s_addc_u32 s39, s39, 0
	global_load_dword v140, v207, s[38:39]
	s_add_u32 s38, s38, s37
	s_addc_u32 s39, s39, 0
	global_load_dword v141, v207, s[38:39]
	s_add_u32 s38, s38, s37
	s_addc_u32 s39, s39, 0
	global_load_dword v142, v207, s[38:39]
	s_add_u32 s38, s38, s37
	s_addc_u32 s39, s39, 0
	global_load_dword v143, v207, s[38:39]
	s_add_u32 s38, s38, s37
	s_addc_u32 s39, s39, 0
	global_load_dword v144, v207, s[38:39]
	s_add_u32 s38, s38, s37
	s_addc_u32 s39, s39, 0
	global_load_dword v145, v207, s[38:39]
	s_add_u32 s38, s38, s37
	s_addc_u32 s39, s39, 0
	global_load_dword v146, v207, s[38:39]
	s_add_u32 s38, s38, s37
	s_addc_u32 s39, s39, 0
	global_load_dword v147, v207, s[38:39]
	s_add_u32 s38, s38, s37
	s_addc_u32 s39, s39, 0
	global_load_dword v148, v207, s[38:39]
	s_add_u32 s38, s38, s37
	s_addc_u32 s39, s39, 0
	global_load_dword v149, v207, s[38:39]
	s_add_u32 s38, s38, s37
	s_addc_u32 s39, s39, 0
	global_load_dword v150, v207, s[38:39]
	s_add_u32 s38, s38, s37
	s_addc_u32 s39, s39, 0
	global_load_dword v151, v207, s[38:39]
	s_add_u32 s38, s38, s37
	s_addc_u32 s39, s39, 0
	global_load_dword v152, v207, s[38:39]
	s_add_u32 s38, s38, s37
	s_addc_u32 s39, s39, 0
	global_load_dword v153, v207, s[38:39]
	s_cmp_ge_u32 s100, s66
	s_cbranch_scc1 .Lwc0_p1
	s_cmpk_ge_u32 s100, 0x900
	s_cbranch_scc1 .Lwc0_t3_2
	s_cmpk_ge_u32 s100, 0x380
	s_cbranch_scc1 .Lwc0_t2_2
	s_cmpk_ge_u32 s100, 0x280
	s_cbranch_scc1 .Lwc0_t1_2
	s_movk_i32 s41, 0x78
	s_sub_u32 s99, s100, 0
	s_mul_i32 s44, s99, 0x66667
	s_lshr_b32 s44, s44, 24
	s_mul_i32 s36, s44, 40
	s_sub_u32 s99, s99, s36
	s_mul_i32 s38, s44, 0xa0000
	s_lshl_b32 s36, s99, 8
	s_add_u32 s38, s38, s36
	s_add_u32 s38, s38, 0x0
	s_lshl_b32 s36, s99, 6
	s_mov_b32 s32, 0x10000
	s_mul_i32 s36, s36, 0x800
	s_lshl_b32 s44, s44, 7
	s_add_u32 s36, s36, s44
	s_add_u32 s36, s36, 0x0
	s_mov_b32 s37, 0xa000
	s_movk_i32 s44, 0x800
	s_mov_b32 s99, 0x2800
	s_branch .Lwc0_tj_2

.Lwc0_tj_2:
	s_load_dwordx2 s[2:3], s[0:1], s41
	s_add_u32 s52, s4, s36
	s_addc_u32 s53, s5, 0
	v_mad_u32_u24 v207, v209, s99, v210
	v_writelane_b32 v213, s52, 12
	v_writelane_b32 v213, s53, 13
	v_writelane_b32 v213, s32, 14
	v_writelane_b32 v213, s44, 15
	s_add_u32 s100, s100, s67
	s_waitcnt lgkmcnt(0)
	s_add_u32 s38, s2, s38
	s_addc_u32 s39, s3, 0
	global_load_dword v154, v207, s[38:39]
	s_add_u32 s38, s38, s37
	s_addc_u32 s39, s39, 0
	global_load_dword v155, v207, s[38:39]
	s_add_u32 s38, s38, s37
	s_addc_u32 s39, s39, 0
	global_load_dword v156, v207, s[38:39]
	s_add_u32 s38, s38, s37
	s_addc_u32 s39, s39, 0
	global_load_dword v157, v207, s[38:39]
	s_add_u32 s38, s38, s37
	s_addc_u32 s39, s39, 0
	global_load_dword v158, v207, s[38:39]
	s_add_u32 s38, s38, s37
	s_addc_u32 s39, s39, 0
	global_load_dword v159, v207, s[38:39]
	s_add_u32 s38, s38, s37
	s_addc_u32 s39, s39, 0
	global_load_dword v160, v207, s[38:39]
	s_add_u32 s38, s38, s37
	s_addc_u32 s39, s39, 0
	global_load_dword v161, v207, s[38:39]
	s_add_u32 s38, s38, s37
	s_addc_u32 s39, s39, 0
	global_load_dword v162, v207, s[38:39]
	s_add_u32 s38, s38, s37
	s_addc_u32 s39, s39, 0
	global_load_dword v163, v207, s[38:39]
	s_add_u32 s38, s38, s37
	s_addc_u32 s39, s39, 0
	global_load_dword v164, v207, s[38:39]
	s_add_u32 s38, s38, s37
	s_addc_u32 s39, s39, 0
	global_load_dword v165, v207, s[38:39]
	s_add_u32 s38, s38, s37
	s_addc_u32 s39, s39, 0
	global_load_dword v166, v207, s[38:39]
	s_add_u32 s38, s38, s37
	s_addc_u32 s39, s39, 0
	global_load_dword v167, v207, s[38:39]
	s_add_u32 s38, s38, s37
	s_addc_u32 s39, s39, 0
	global_load_dword v168, v207, s[38:39]
	s_add_u32 s38, s38, s37
	s_addc_u32 s39, s39, 0
	global_load_dword v169, v207, s[38:39]
	s_cmp_ge_u32 s100, s66
	s_cbranch_scc1 .Lwc0_p2
	s_cmpk_ge_u32 s100, 0x900
	s_cbranch_scc1 .Lwc0_t3_3
	s_cmpk_ge_u32 s100, 0x380
	s_cbranch_scc1 .Lwc0_t2_3
	s_cmpk_ge_u32 s100, 0x280
	s_cbranch_scc1 .Lwc0_t1_3
	s_movk_i32 s41, 0x78
	s_sub_u32 s99, s100, 0
	s_mul_i32 s44, s99, 0x66667
	s_lshr_b32 s44, s44, 24
	s_mul_i32 s36, s44, 40
	s_sub_u32 s99, s99, s36
	s_mul_i32 s38, s44, 0xa0000
	s_lshl_b32 s36, s99, 8
	s_add_u32 s38, s38, s36
	s_add_u32 s38, s38, 0x0
	s_lshl_b32 s36, s99, 6
	s_mov_b32 s32, 0x10000
	s_mul_i32 s36, s36, 0x800
	s_lshl_b32 s44, s44, 7
	s_add_u32 s36, s36, s44
	s_add_u32 s36, s36, 0x0
	s_mov_b32 s37, 0xa000
	s_movk_i32 s44, 0x800
	s_mov_b32 s99, 0x2800
	s_branch .Lwc0_tj_3

.Lwc0_tj_3:
	s_load_dwordx2 s[2:3], s[0:1], s41
	s_add_u32 s52, s4, s36
	s_addc_u32 s53, s5, 0
	v_mad_u32_u24 v207, v209, s99, v210
	v_writelane_b32 v213, s52, 16
	v_writelane_b32 v213, s53, 17
	v_writelane_b32 v213, s32, 18
	v_writelane_b32 v213, s44, 19
	s_add_u32 s100, s100, s67
	s_waitcnt lgkmcnt(0)
	s_add_u32 s38, s2, s38
	s_addc_u32 s39, s3, 0
	global_load_dword v170, v207, s[38:39]
	s_add_u32 s38, s38, s37
	s_addc_u32 s39, s39, 0
	global_load_dword v171, v207, s[38:39]
	s_add_u32 s38, s38, s37
	s_addc_u32 s39, s39, 0
	global_load_dword v172, v207, s[38:39]
	s_add_u32 s38, s38, s37
	s_addc_u32 s39, s39, 0
	global_load_dword v173, v207, s[38:39]
	s_add_u32 s38, s38, s37
	s_addc_u32 s39, s39, 0
	global_load_dword v174, v207, s[38:39]
	s_add_u32 s38, s38, s37
	s_addc_u32 s39, s39, 0
	global_load_dword v175, v207, s[38:39]
	s_add_u32 s38, s38, s37
	s_addc_u32 s39, s39, 0
	global_load_dword v176, v207, s[38:39]
	s_add_u32 s38, s38, s37
	s_addc_u32 s39, s39, 0
	global_load_dword v177, v207, s[38:39]
	s_add_u32 s38, s38, s37
	s_addc_u32 s39, s39, 0
	global_load_dword v178, v207, s[38:39]
	s_add_u32 s38, s38, s37
	s_addc_u32 s39, s39, 0
	global_load_dword v179, v207, s[38:39]
	s_add_u32 s38, s38, s37
	s_addc_u32 s39, s39, 0
	global_load_dword v180, v207, s[38:39]
	s_add_u32 s38, s38, s37
	s_addc_u32 s39, s39, 0
	global_load_dword v181, v207, s[38:39]
	s_add_u32 s38, s38, s37
	s_addc_u32 s39, s39, 0
	global_load_dword v182, v207, s[38:39]
	s_add_u32 s38, s38, s37
	s_addc_u32 s39, s39, 0
	global_load_dword v183, v207, s[38:39]
	s_add_u32 s38, s38, s37
	s_addc_u32 s39, s39, 0
	global_load_dword v184, v207, s[38:39]
	s_add_u32 s38, s38, s37
	s_addc_u32 s39, s39, 0
	global_load_dword v185, v207, s[38:39]
.Lwc0_loop:
	s_waitcnt vmcnt(32)
	v_readlane_b32 s52, v213, 8
	v_readlane_b32 s53, v213, 9
	v_readlane_b32 s32, v213, 10
	v_readlane_b32 s35, v213, 11
	ds_write_b32 v202, v138 offset:0
	ds_write_b32 v202, v139 offset:1040
	ds_write_b32 v202, v140 offset:2080
	ds_write_b32 v202, v141 offset:3120
	ds_write_b32 v202, v142 offset:4160
	ds_write_b32 v202, v143 offset:5200
	ds_write_b32 v202, v144 offset:6240
	ds_write_b32 v202, v145 offset:7280
	ds_write_b32 v202, v146 offset:8320
	ds_write_b32 v202, v147 offset:9360
	ds_write_b32 v202, v148 offset:10400
	ds_write_b32 v202, v149 offset:11440
	ds_write_b32 v202, v150 offset:12480
	ds_write_b32 v202, v151 offset:13520
	ds_write_b32 v202, v152 offset:14560
	ds_write_b32 v202, v153 offset:15600
	v_mad_u32_u24 v208, v211, s35, v212
	s_waitcnt lgkmcnt(0)
	s_barrier
	ds_read2_b32 v[186:187], v203 offset1:65
	ds_read2_b32 v[188:189], v203 offset0:130 offset1:195
	ds_read2_b32 v[190:191], v204 offset0:4 offset1:69
	ds_read2_b32 v[192:193], v204 offset0:134 offset1:199
	ds_read2_b32 v[194:195], v205 offset1:65
	ds_read2_b32 v[196:197], v205 offset0:130 offset1:195
	ds_read2_b32 v[198:199], v206 offset0:4 offset1:69
	ds_read2_b32 v[200:201], v206 offset0:134 offset1:199
	s_add_u32 s96, s52, s32
	s_addc_u32 s97, s53, 0
	s_waitcnt lgkmcnt(0)
	s_barrier
	v_cvt_pk_bf16_f32 v186, v186, v187
	v_cvt_pk_bf16_f32 v187, v188, v189
	v_cvt_pk_bf16_f32 v188, v190, v191
	v_cvt_pk_bf16_f32 v189, v192, v193
	v_cvt_pk_bf16_f32 v194, v194, v195
	v_cvt_pk_bf16_f32 v195, v196, v197
	v_cvt_pk_bf16_f32 v196, v198, v199
	v_cvt_pk_bf16_f32 v197, v200, v201
	global_store_dwordx4 v208, v[186:189], s[52:53]
	global_store_dwordx4 v208, v[194:197], s[96:97]
	s_cmp_ge_u32 s100, s66
	s_cbranch_scc1 .Lwc0_tail0
	s_cmpk_ge_u32 s100, 0x900
	s_cbranch_scc1 .Lwc0_t3_4
	s_cmpk_ge_u32 s100, 0x380
	s_cbranch_scc1 .Lwc0_t2_4
	s_cmpk_ge_u32 s100, 0x280
	s_cbranch_scc1 .Lwc0_t1_4
	s_movk_i32 s41, 0x78
	s_sub_u32 s99, s100, 0
	s_mul_i32 s44, s99, 0x66667
	s_lshr_b32 s44, s44, 24
	s_mul_i32 s36, s44, 40
	s_sub_u32 s99, s99, s36
	s_mul_i32 s38, s44, 0xa0000
	s_lshl_b32 s36, s99, 8
	s_add_u32 s38, s38, s36
	s_add_u32 s38, s38, 0x0
	s_lshl_b32 s36, s99, 6
	s_mov_b32 s32, 0x10000
	s_mul_i32 s36, s36, 0x800
	s_lshl_b32 s44, s44, 7
	s_add_u32 s36, s36, s44
	s_add_u32 s36, s36, 0x0
	s_mov_b32 s37, 0xa000
	s_movk_i32 s44, 0x800
	s_mov_b32 s99, 0x2800
	s_branch .Lwc0_tj_4

.Lwc0_tj_4:
	s_load_dwordx2 s[2:3], s[0:1], s41
	s_add_u32 s52, s4, s36
	s_addc_u32 s53, s5, 0
	v_mad_u32_u24 v207, v209, s99, v210
	v_writelane_b32 v213, s52, 8
	v_writelane_b32 v213, s53, 9
	v_writelane_b32 v213, s32, 10
	v_writelane_b32 v213, s44, 11
	s_add_u32 s100, s100, s67
	s_waitcnt lgkmcnt(0)
	s_add_u32 s38, s2, s38
	s_addc_u32 s39, s3, 0
	global_load_dword v138, v207, s[38:39]
	s_add_u32 s38, s38, s37
	s_addc_u32 s39, s39, 0
	global_load_dword v139, v207, s[38:39]
	s_add_u32 s38, s38, s37
	s_addc_u32 s39, s39, 0
	global_load_dword v140, v207, s[38:39]
	s_add_u32 s38, s38, s37
	s_addc_u32 s39, s39, 0
	global_load_dword v141, v207, s[38:39]
	s_add_u32 s38, s38, s37
	s_addc_u32 s39, s39, 0
	global_load_dword v142, v207, s[38:39]
	s_add_u32 s38, s38, s37
	s_addc_u32 s39, s39, 0
	global_load_dword v143, v207, s[38:39]
	s_add_u32 s38, s38, s37
	s_addc_u32 s39, s39, 0
	global_load_dword v144, v207, s[38:39]
	s_add_u32 s38, s38, s37
	s_addc_u32 s39, s39, 0
	global_load_dword v145, v207, s[38:39]
	s_add_u32 s38, s38, s37
	s_addc_u32 s39, s39, 0
	global_load_dword v146, v207, s[38:39]
	s_add_u32 s38, s38, s37
	s_addc_u32 s39, s39, 0
	global_load_dword v147, v207, s[38:39]
	s_add_u32 s38, s38, s37
	s_addc_u32 s39, s39, 0
	global_load_dword v148, v207, s[38:39]
	s_add_u32 s38, s38, s37
	s_addc_u32 s39, s39, 0
	global_load_dword v149, v207, s[38:39]
	s_add_u32 s38, s38, s37
	s_addc_u32 s39, s39, 0
	global_load_dword v150, v207, s[38:39]
	s_add_u32 s38, s38, s37
	s_addc_u32 s39, s39, 0
	global_load_dword v151, v207, s[38:39]
	s_add_u32 s38, s38, s37
	s_addc_u32 s39, s39, 0
	global_load_dword v152, v207, s[38:39]
	s_add_u32 s38, s38, s37
	s_addc_u32 s39, s39, 0
	global_load_dword v153, v207, s[38:39]
	s_waitcnt vmcnt(32)
	v_readlane_b32 s52, v213, 12
	v_readlane_b32 s53, v213, 13
	v_readlane_b32 s32, v213, 14
	v_readlane_b32 s35, v213, 15
	ds_write_b32 v202, v154 offset:0
	ds_write_b32 v202, v155 offset:1040
	ds_write_b32 v202, v156 offset:2080
	ds_write_b32 v202, v157 offset:3120
	ds_write_b32 v202, v158 offset:4160
	ds_write_b32 v202, v159 offset:5200
	ds_write_b32 v202, v160 offset:6240
	ds_write_b32 v202, v161 offset:7280
	ds_write_b32 v202, v162 offset:8320
	ds_write_b32 v202, v163 offset:9360
	ds_write_b32 v202, v164 offset:10400
	ds_write_b32 v202, v165 offset:11440
	ds_write_b32 v202, v166 offset:12480
	ds_write_b32 v202, v167 offset:13520
	ds_write_b32 v202, v168 offset:14560
	ds_write_b32 v202, v169 offset:15600
	v_mad_u32_u24 v208, v211, s35, v212
	s_waitcnt lgkmcnt(0)
	s_barrier
	ds_read2_b32 v[186:187], v203 offset1:65
	ds_read2_b32 v[188:189], v203 offset0:130 offset1:195
	ds_read2_b32 v[190:191], v204 offset0:4 offset1:69
	ds_read2_b32 v[192:193], v204 offset0:134 offset1:199
	ds_read2_b32 v[194:195], v205 offset1:65
	ds_read2_b32 v[196:197], v205 offset0:130 offset1:195
	ds_read2_b32 v[198:199], v206 offset0:4 offset1:69
	ds_read2_b32 v[200:201], v206 offset0:134 offset1:199
	s_add_u32 s96, s52, s32
	s_addc_u32 s97, s53, 0
	s_waitcnt lgkmcnt(0)
	s_barrier
	v_cvt_pk_bf16_f32 v186, v186, v187
	v_cvt_pk_bf16_f32 v187, v188, v189
	v_cvt_pk_bf16_f32 v188, v190, v191
	v_cvt_pk_bf16_f32 v189, v192, v193
	v_cvt_pk_bf16_f32 v194, v194, v195
	v_cvt_pk_bf16_f32 v195, v196, v197
	v_cvt_pk_bf16_f32 v196, v198, v199
	v_cvt_pk_bf16_f32 v197, v200, v201
	global_store_dwordx4 v208, v[186:189], s[52:53]
	global_store_dwordx4 v208, v[194:197], s[96:97]
	s_cmp_ge_u32 s100, s66
	s_cbranch_scc1 .Lwc0_tail1
	s_cmpk_ge_u32 s100, 0x900
	s_cbranch_scc1 .Lwc0_t3_5
	s_cmpk_ge_u32 s100, 0x380
	s_cbranch_scc1 .Lwc0_t2_5
	s_cmpk_ge_u32 s100, 0x280
	s_cbranch_scc1 .Lwc0_t1_5
	s_movk_i32 s41, 0x78
	s_sub_u32 s99, s100, 0
	s_mul_i32 s44, s99, 0x66667
	s_lshr_b32 s44, s44, 24
	s_mul_i32 s36, s44, 40
	s_sub_u32 s99, s99, s36
	s_mul_i32 s38, s44, 0xa0000
	s_lshl_b32 s36, s99, 8
	s_add_u32 s38, s38, s36
	s_add_u32 s38, s38, 0x0
	s_lshl_b32 s36, s99, 6
	s_mov_b32 s32, 0x10000
	s_mul_i32 s36, s36, 0x800
	s_lshl_b32 s44, s44, 7
	s_add_u32 s36, s36, s44
	s_add_u32 s36, s36, 0x0
	s_mov_b32 s37, 0xa000
	s_movk_i32 s44, 0x800
	s_mov_b32 s99, 0x2800
	s_branch .Lwc0_tj_5

.Lwc0_tj_5:
	s_load_dwordx2 s[2:3], s[0:1], s41
	s_add_u32 s52, s4, s36
	s_addc_u32 s53, s5, 0
	v_mad_u32_u24 v207, v209, s99, v210
	v_writelane_b32 v213, s52, 12
	v_writelane_b32 v213, s53, 13
	v_writelane_b32 v213, s32, 14
	v_writelane_b32 v213, s44, 15
	s_add_u32 s100, s100, s67
	s_waitcnt lgkmcnt(0)
	s_add_u32 s38, s2, s38
	s_addc_u32 s39, s3, 0
	global_load_dword v154, v207, s[38:39]
	s_add_u32 s38, s38, s37
	s_addc_u32 s39, s39, 0
	global_load_dword v155, v207, s[38:39]
	s_add_u32 s38, s38, s37
	s_addc_u32 s39, s39, 0
	global_load_dword v156, v207, s[38:39]
	s_add_u32 s38, s38, s37
	s_addc_u32 s39, s39, 0
	global_load_dword v157, v207, s[38:39]
	s_add_u32 s38, s38, s37
	s_addc_u32 s39, s39, 0
	global_load_dword v158, v207, s[38:39]
	s_add_u32 s38, s38, s37
	s_addc_u32 s39, s39, 0
	global_load_dword v159, v207, s[38:39]
	s_add_u32 s38, s38, s37
	s_addc_u32 s39, s39, 0
	global_load_dword v160, v207, s[38:39]
	s_add_u32 s38, s38, s37
	s_addc_u32 s39, s39, 0
	global_load_dword v161, v207, s[38:39]
	s_add_u32 s38, s38, s37
	s_addc_u32 s39, s39, 0
	global_load_dword v162, v207, s[38:39]
	s_add_u32 s38, s38, s37
	s_addc_u32 s39, s39, 0
	global_load_dword v163, v207, s[38:39]
	s_add_u32 s38, s38, s37
	s_addc_u32 s39, s39, 0
	global_load_dword v164, v207, s[38:39]
	s_add_u32 s38, s38, s37
	s_addc_u32 s39, s39, 0
	global_load_dword v165, v207, s[38:39]
	s_add_u32 s38, s38, s37
	s_addc_u32 s39, s39, 0
	global_load_dword v166, v207, s[38:39]
	s_add_u32 s38, s38, s37
	s_addc_u32 s39, s39, 0
	global_load_dword v167, v207, s[38:39]
	s_add_u32 s38, s38, s37
	s_addc_u32 s39, s39, 0
	global_load_dword v168, v207, s[38:39]
	s_add_u32 s38, s38, s37
	s_addc_u32 s39, s39, 0
	global_load_dword v169, v207, s[38:39]
	s_waitcnt vmcnt(32)
	v_readlane_b32 s52, v213, 16
	v_readlane_b32 s53, v213, 17
	v_readlane_b32 s32, v213, 18
	v_readlane_b32 s35, v213, 19
	ds_write_b32 v202, v170 offset:0
	ds_write_b32 v202, v171 offset:1040
	ds_write_b32 v202, v172 offset:2080
	ds_write_b32 v202, v173 offset:3120
	ds_write_b32 v202, v174 offset:4160
	ds_write_b32 v202, v175 offset:5200
	ds_write_b32 v202, v176 offset:6240
	ds_write_b32 v202, v177 offset:7280
	ds_write_b32 v202, v178 offset:8320
	ds_write_b32 v202, v179 offset:9360
	ds_write_b32 v202, v180 offset:10400
	ds_write_b32 v202, v181 offset:11440
	ds_write_b32 v202, v182 offset:12480
	ds_write_b32 v202, v183 offset:13520
	ds_write_b32 v202, v184 offset:14560
	ds_write_b32 v202, v185 offset:15600
	v_mad_u32_u24 v208, v211, s35, v212
	s_waitcnt lgkmcnt(0)
	s_barrier
	ds_read2_b32 v[186:187], v203 offset1:65
	ds_read2_b32 v[188:189], v203 offset0:130 offset1:195
	ds_read2_b32 v[190:191], v204 offset0:4 offset1:69
	ds_read2_b32 v[192:193], v204 offset0:134 offset1:199
	ds_read2_b32 v[194:195], v205 offset1:65
	ds_read2_b32 v[196:197], v205 offset0:130 offset1:195
	ds_read2_b32 v[198:199], v206 offset0:4 offset1:69
	ds_read2_b32 v[200:201], v206 offset0:134 offset1:199
	s_add_u32 s96, s52, s32
	s_addc_u32 s97, s53, 0
	s_waitcnt lgkmcnt(0)
	s_barrier
	v_cvt_pk_bf16_f32 v186, v186, v187
	v_cvt_pk_bf16_f32 v187, v188, v189
	v_cvt_pk_bf16_f32 v188, v190, v191
	v_cvt_pk_bf16_f32 v189, v192, v193
	v_cvt_pk_bf16_f32 v194, v194, v195
	v_cvt_pk_bf16_f32 v195, v196, v197
	v_cvt_pk_bf16_f32 v196, v198, v199
	v_cvt_pk_bf16_f32 v197, v200, v201
	global_store_dwordx4 v208, v[186:189], s[52:53]
	global_store_dwordx4 v208, v[194:197], s[96:97]
	s_cmp_ge_u32 s100, s66
	s_cbranch_scc1 .Lwc0_tail2
	s_cmpk_ge_u32 s100, 0x900
	s_cbranch_scc1 .Lwc0_t3_6
	s_cmpk_ge_u32 s100, 0x380
	s_cbranch_scc1 .Lwc0_t2_6
	s_cmpk_ge_u32 s100, 0x280
	s_cbranch_scc1 .Lwc0_t1_6
	s_movk_i32 s41, 0x78
	s_sub_u32 s99, s100, 0
	s_mul_i32 s44, s99, 0x66667
	s_lshr_b32 s44, s44, 24
	s_mul_i32 s36, s44, 40
	s_sub_u32 s99, s99, s36
	s_mul_i32 s38, s44, 0xa0000
	s_lshl_b32 s36, s99, 8
	s_add_u32 s38, s38, s36
	s_add_u32 s38, s38, 0x0
	s_lshl_b32 s36, s99, 6
	s_mov_b32 s32, 0x10000
	s_mul_i32 s36, s36, 0x800
	s_lshl_b32 s44, s44, 7
	s_add_u32 s36, s36, s44
	s_add_u32 s36, s36, 0x0
	s_mov_b32 s37, 0xa000
	s_movk_i32 s44, 0x800
	s_mov_b32 s99, 0x2800
	s_branch .Lwc0_tj_6

.Lwc0_tj_6:
	s_load_dwordx2 s[2:3], s[0:1], s41
	s_add_u32 s52, s4, s36
	s_addc_u32 s53, s5, 0
	v_mad_u32_u24 v207, v209, s99, v210
	v_writelane_b32 v213, s52, 16
	v_writelane_b32 v213, s53, 17
	v_writelane_b32 v213, s32, 18
	v_writelane_b32 v213, s44, 19
	s_add_u32 s100, s100, s67
	s_waitcnt lgkmcnt(0)
	s_add_u32 s38, s2, s38
	s_addc_u32 s39, s3, 0
	global_load_dword v170, v207, s[38:39]
	s_add_u32 s38, s38, s37
	s_addc_u32 s39, s39, 0
	global_load_dword v171, v207, s[38:39]
	s_add_u32 s38, s38, s37
	s_addc_u32 s39, s39, 0
	global_load_dword v172, v207, s[38:39]
	s_add_u32 s38, s38, s37
	s_addc_u32 s39, s39, 0
	global_load_dword v173, v207, s[38:39]
	s_add_u32 s38, s38, s37
	s_addc_u32 s39, s39, 0
	global_load_dword v174, v207, s[38:39]
	s_add_u32 s38, s38, s37
	s_addc_u32 s39, s39, 0
	global_load_dword v175, v207, s[38:39]
	s_add_u32 s38, s38, s37
	s_addc_u32 s39, s39, 0
	global_load_dword v176, v207, s[38:39]
	s_add_u32 s38, s38, s37
	s_addc_u32 s39, s39, 0
	global_load_dword v177, v207, s[38:39]
	s_add_u32 s38, s38, s37
	s_addc_u32 s39, s39, 0
	global_load_dword v178, v207, s[38:39]
	s_add_u32 s38, s38, s37
	s_addc_u32 s39, s39, 0
	global_load_dword v179, v207, s[38:39]
	s_add_u32 s38, s38, s37
	s_addc_u32 s39, s39, 0
	global_load_dword v180, v207, s[38:39]
	s_add_u32 s38, s38, s37
	s_addc_u32 s39, s39, 0
	global_load_dword v181, v207, s[38:39]
	s_add_u32 s38, s38, s37
	s_addc_u32 s39, s39, 0
	global_load_dword v182, v207, s[38:39]
	s_add_u32 s38, s38, s37
	s_addc_u32 s39, s39, 0
	global_load_dword v183, v207, s[38:39]
	s_add_u32 s38, s38, s37
	s_addc_u32 s39, s39, 0
	global_load_dword v184, v207, s[38:39]
	s_add_u32 s38, s38, s37
	s_addc_u32 s39, s39, 0
	global_load_dword v185, v207, s[38:39]
	s_branch .Lwc0_loop
.Lwc0_tail0:
	s_waitcnt vmcnt(0)
	v_readlane_b32 s52, v213, 12
	v_readlane_b32 s53, v213, 13
	v_readlane_b32 s32, v213, 14
	v_readlane_b32 s35, v213, 15
	ds_write_b32 v202, v154 offset:0
	ds_write_b32 v202, v155 offset:1040
	ds_write_b32 v202, v156 offset:2080
	ds_write_b32 v202, v157 offset:3120
	ds_write_b32 v202, v158 offset:4160
	ds_write_b32 v202, v159 offset:5200
	ds_write_b32 v202, v160 offset:6240
	ds_write_b32 v202, v161 offset:7280
	ds_write_b32 v202, v162 offset:8320
	ds_write_b32 v202, v163 offset:9360
	ds_write_b32 v202, v164 offset:10400
	ds_write_b32 v202, v165 offset:11440
	ds_write_b32 v202, v166 offset:12480
	ds_write_b32 v202, v167 offset:13520
	ds_write_b32 v202, v168 offset:14560
	ds_write_b32 v202, v169 offset:15600
	v_mad_u32_u24 v208, v211, s35, v212
	s_waitcnt lgkmcnt(0)
	s_barrier
	ds_read2_b32 v[186:187], v203 offset1:65
	ds_read2_b32 v[188:189], v203 offset0:130 offset1:195
	ds_read2_b32 v[190:191], v204 offset0:4 offset1:69
	ds_read2_b32 v[192:193], v204 offset0:134 offset1:199
	ds_read2_b32 v[194:195], v205 offset1:65
	ds_read2_b32 v[196:197], v205 offset0:130 offset1:195
	ds_read2_b32 v[198:199], v206 offset0:4 offset1:69
	ds_read2_b32 v[200:201], v206 offset0:134 offset1:199
	s_add_u32 s96, s52, s32
	s_addc_u32 s97, s53, 0
	s_waitcnt lgkmcnt(0)
	s_barrier
	v_cvt_pk_bf16_f32 v186, v186, v187
	v_cvt_pk_bf16_f32 v187, v188, v189
	v_cvt_pk_bf16_f32 v188, v190, v191
	v_cvt_pk_bf16_f32 v189, v192, v193
	v_cvt_pk_bf16_f32 v194, v194, v195
	v_cvt_pk_bf16_f32 v195, v196, v197
	v_cvt_pk_bf16_f32 v196, v198, v199
	v_cvt_pk_bf16_f32 v197, v200, v201
	global_store_dwordx4 v208, v[186:189], s[52:53]
	global_store_dwordx4 v208, v[194:197], s[96:97]
	v_readlane_b32 s52, v213, 16
	v_readlane_b32 s53, v213, 17
	v_readlane_b32 s32, v213, 18
	v_readlane_b32 s35, v213, 19
	ds_write_b32 v202, v170 offset:0
	ds_write_b32 v202, v171 offset:1040
	ds_write_b32 v202, v172 offset:2080
	ds_write_b32 v202, v173 offset:3120
	ds_write_b32 v202, v174 offset:4160
	ds_write_b32 v202, v175 offset:5200
	ds_write_b32 v202, v176 offset:6240
	ds_write_b32 v202, v177 offset:7280
	ds_write_b32 v202, v178 offset:8320
	ds_write_b32 v202, v179 offset:9360
	ds_write_b32 v202, v180 offset:10400
	ds_write_b32 v202, v181 offset:11440
	ds_write_b32 v202, v182 offset:12480
	ds_write_b32 v202, v183 offset:13520
	ds_write_b32 v202, v184 offset:14560
	ds_write_b32 v202, v185 offset:15600
	v_mad_u32_u24 v208, v211, s35, v212
	s_waitcnt lgkmcnt(0)
	s_barrier
	ds_read2_b32 v[186:187], v203 offset1:65
	ds_read2_b32 v[188:189], v203 offset0:130 offset1:195
	ds_read2_b32 v[190:191], v204 offset0:4 offset1:69
	ds_read2_b32 v[192:193], v204 offset0:134 offset1:199
	ds_read2_b32 v[194:195], v205 offset1:65
	ds_read2_b32 v[196:197], v205 offset0:130 offset1:195
	ds_read2_b32 v[198:199], v206 offset0:4 offset1:69
	ds_read2_b32 v[200:201], v206 offset0:134 offset1:199
	s_add_u32 s96, s52, s32
	s_addc_u32 s97, s53, 0
	s_waitcnt lgkmcnt(0)
	s_barrier
	v_cvt_pk_bf16_f32 v186, v186, v187
	v_cvt_pk_bf16_f32 v187, v188, v189
	v_cvt_pk_bf16_f32 v188, v190, v191
	v_cvt_pk_bf16_f32 v189, v192, v193
	v_cvt_pk_bf16_f32 v194, v194, v195
	v_cvt_pk_bf16_f32 v195, v196, v197
	v_cvt_pk_bf16_f32 v196, v198, v199
	v_cvt_pk_bf16_f32 v197, v200, v201
	global_store_dwordx4 v208, v[186:189], s[52:53]
	global_store_dwordx4 v208, v[194:197], s[96:97]
	s_branch .Lwc0_done
.Lwc0_tail1:
	s_waitcnt vmcnt(0)
	v_readlane_b32 s52, v213, 16
	v_readlane_b32 s53, v213, 17
	v_readlane_b32 s32, v213, 18
	v_readlane_b32 s35, v213, 19
	ds_write_b32 v202, v170 offset:0
	ds_write_b32 v202, v171 offset:1040
	ds_write_b32 v202, v172 offset:2080
	ds_write_b32 v202, v173 offset:3120
	ds_write_b32 v202, v174 offset:4160
	ds_write_b32 v202, v175 offset:5200
	ds_write_b32 v202, v176 offset:6240
	ds_write_b32 v202, v177 offset:7280
	ds_write_b32 v202, v178 offset:8320
	ds_write_b32 v202, v179 offset:9360
	ds_write_b32 v202, v180 offset:10400
	ds_write_b32 v202, v181 offset:11440
	ds_write_b32 v202, v182 offset:12480
	ds_write_b32 v202, v183 offset:13520
	ds_write_b32 v202, v184 offset:14560
	ds_write_b32 v202, v185 offset:15600
	v_mad_u32_u24 v208, v211, s35, v212
	s_waitcnt lgkmcnt(0)
	s_barrier
	ds_read2_b32 v[186:187], v203 offset1:65
	ds_read2_b32 v[188:189], v203 offset0:130 offset1:195
	ds_read2_b32 v[190:191], v204 offset0:4 offset1:69
	ds_read2_b32 v[192:193], v204 offset0:134 offset1:199
	ds_read2_b32 v[194:195], v205 offset1:65
	ds_read2_b32 v[196:197], v205 offset0:130 offset1:195
	ds_read2_b32 v[198:199], v206 offset0:4 offset1:69
	ds_read2_b32 v[200:201], v206 offset0:134 offset1:199
	s_add_u32 s96, s52, s32
	s_addc_u32 s97, s53, 0
	s_waitcnt lgkmcnt(0)
	s_barrier
	v_cvt_pk_bf16_f32 v186, v186, v187
	v_cvt_pk_bf16_f32 v187, v188, v189
	v_cvt_pk_bf16_f32 v188, v190, v191
	v_cvt_pk_bf16_f32 v189, v192, v193
	v_cvt_pk_bf16_f32 v194, v194, v195
	v_cvt_pk_bf16_f32 v195, v196, v197
	v_cvt_pk_bf16_f32 v196, v198, v199
	v_cvt_pk_bf16_f32 v197, v200, v201
	global_store_dwordx4 v208, v[186:189], s[52:53]
	global_store_dwordx4 v208, v[194:197], s[96:97]
	v_readlane_b32 s52, v213, 8
	v_readlane_b32 s53, v213, 9
	v_readlane_b32 s32, v213, 10
	v_readlane_b32 s35, v213, 11
	ds_write_b32 v202, v138 offset:0
	ds_write_b32 v202, v139 offset:1040
	ds_write_b32 v202, v140 offset:2080
	ds_write_b32 v202, v141 offset:3120
	ds_write_b32 v202, v142 offset:4160
	ds_write_b32 v202, v143 offset:5200
	ds_write_b32 v202, v144 offset:6240
	ds_write_b32 v202, v145 offset:7280
	ds_write_b32 v202, v146 offset:8320
	ds_write_b32 v202, v147 offset:9360
	ds_write_b32 v202, v148 offset:10400
	ds_write_b32 v202, v149 offset:11440
	ds_write_b32 v202, v150 offset:12480
	ds_write_b32 v202, v151 offset:13520
	ds_write_b32 v202, v152 offset:14560
	ds_write_b32 v202, v153 offset:15600
	v_mad_u32_u24 v208, v211, s35, v212
	s_waitcnt lgkmcnt(0)
	s_barrier
	ds_read2_b32 v[186:187], v203 offset1:65
	ds_read2_b32 v[188:189], v203 offset0:130 offset1:195
	ds_read2_b32 v[190:191], v204 offset0:4 offset1:69
	ds_read2_b32 v[192:193], v204 offset0:134 offset1:199
	ds_read2_b32 v[194:195], v205 offset1:65
	ds_read2_b32 v[196:197], v205 offset0:130 offset1:195
	ds_read2_b32 v[198:199], v206 offset0:4 offset1:69
	ds_read2_b32 v[200:201], v206 offset0:134 offset1:199
	s_add_u32 s96, s52, s32
	s_addc_u32 s97, s53, 0
	s_waitcnt lgkmcnt(0)
	s_barrier
	v_cvt_pk_bf16_f32 v186, v186, v187
	v_cvt_pk_bf16_f32 v187, v188, v189
	v_cvt_pk_bf16_f32 v188, v190, v191
	v_cvt_pk_bf16_f32 v189, v192, v193
	v_cvt_pk_bf16_f32 v194, v194, v195
	v_cvt_pk_bf16_f32 v195, v196, v197
	v_cvt_pk_bf16_f32 v196, v198, v199
	v_cvt_pk_bf16_f32 v197, v200, v201
	global_store_dwordx4 v208, v[186:189], s[52:53]
	global_store_dwordx4 v208, v[194:197], s[96:97]
	s_branch .Lwc0_done
.Lwc0_tail2:
	s_waitcnt vmcnt(0)
	v_readlane_b32 s52, v213, 8
	v_readlane_b32 s53, v213, 9
	v_readlane_b32 s32, v213, 10
	v_readlane_b32 s35, v213, 11
	ds_write_b32 v202, v138 offset:0
	ds_write_b32 v202, v139 offset:1040
	ds_write_b32 v202, v140 offset:2080
	ds_write_b32 v202, v141 offset:3120
	ds_write_b32 v202, v142 offset:4160
	ds_write_b32 v202, v143 offset:5200
	ds_write_b32 v202, v144 offset:6240
	ds_write_b32 v202, v145 offset:7280
	ds_write_b32 v202, v146 offset:8320
	ds_write_b32 v202, v147 offset:9360
	ds_write_b32 v202, v148 offset:10400
	ds_write_b32 v202, v149 offset:11440
	ds_write_b32 v202, v150 offset:12480
	ds_write_b32 v202, v151 offset:13520
	ds_write_b32 v202, v152 offset:14560
	ds_write_b32 v202, v153 offset:15600
	v_mad_u32_u24 v208, v211, s35, v212
	s_waitcnt lgkmcnt(0)
	s_barrier
	ds_read2_b32 v[186:187], v203 offset1:65
	ds_read2_b32 v[188:189], v203 offset0:130 offset1:195
	ds_read2_b32 v[190:191], v204 offset0:4 offset1:69
	ds_read2_b32 v[192:193], v204 offset0:134 offset1:199
	ds_read2_b32 v[194:195], v205 offset1:65
	ds_read2_b32 v[196:197], v205 offset0:130 offset1:195
	ds_read2_b32 v[198:199], v206 offset0:4 offset1:69
	ds_read2_b32 v[200:201], v206 offset0:134 offset1:199
	s_add_u32 s96, s52, s32
	s_addc_u32 s97, s53, 0
	s_waitcnt lgkmcnt(0)
	s_barrier
	v_cvt_pk_bf16_f32 v186, v186, v187
	v_cvt_pk_bf16_f32 v187, v188, v189
	v_cvt_pk_bf16_f32 v188, v190, v191
	v_cvt_pk_bf16_f32 v189, v192, v193
	v_cvt_pk_bf16_f32 v194, v194, v195
	v_cvt_pk_bf16_f32 v195, v196, v197
	v_cvt_pk_bf16_f32 v196, v198, v199
	v_cvt_pk_bf16_f32 v197, v200, v201
	global_store_dwordx4 v208, v[186:189], s[52:53]
	global_store_dwordx4 v208, v[194:197], s[96:97]
	v_readlane_b32 s52, v213, 12
	v_readlane_b32 s53, v213, 13
	v_readlane_b32 s32, v213, 14
	v_readlane_b32 s35, v213, 15
	ds_write_b32 v202, v154 offset:0
	ds_write_b32 v202, v155 offset:1040
	ds_write_b32 v202, v156 offset:2080
	ds_write_b32 v202, v157 offset:3120
	ds_write_b32 v202, v158 offset:4160
	ds_write_b32 v202, v159 offset:5200
	ds_write_b32 v202, v160 offset:6240
	ds_write_b32 v202, v161 offset:7280
	ds_write_b32 v202, v162 offset:8320
	ds_write_b32 v202, v163 offset:9360
	ds_write_b32 v202, v164 offset:10400
	ds_write_b32 v202, v165 offset:11440
	ds_write_b32 v202, v166 offset:12480
	ds_write_b32 v202, v167 offset:13520
	ds_write_b32 v202, v168 offset:14560
	ds_write_b32 v202, v169 offset:15600
	v_mad_u32_u24 v208, v211, s35, v212
	s_waitcnt lgkmcnt(0)
	s_barrier
	ds_read2_b32 v[186:187], v203 offset1:65
	ds_read2_b32 v[188:189], v203 offset0:130 offset1:195
	ds_read2_b32 v[190:191], v204 offset0:4 offset1:69
	ds_read2_b32 v[192:193], v204 offset0:134 offset1:199
	ds_read2_b32 v[194:195], v205 offset1:65
	ds_read2_b32 v[196:197], v205 offset0:130 offset1:195
	ds_read2_b32 v[198:199], v206 offset0:4 offset1:69
	ds_read2_b32 v[200:201], v206 offset0:134 offset1:199
	s_add_u32 s96, s52, s32
	s_addc_u32 s97, s53, 0
	s_waitcnt lgkmcnt(0)
	s_barrier
	v_cvt_pk_bf16_f32 v186, v186, v187
	v_cvt_pk_bf16_f32 v187, v188, v189
	v_cvt_pk_bf16_f32 v188, v190, v191
	v_cvt_pk_bf16_f32 v189, v192, v193
	v_cvt_pk_bf16_f32 v194, v194, v195
	v_cvt_pk_bf16_f32 v195, v196, v197
	v_cvt_pk_bf16_f32 v196, v198, v199
	v_cvt_pk_bf16_f32 v197, v200, v201
	global_store_dwordx4 v208, v[186:189], s[52:53]
	global_store_dwordx4 v208, v[194:197], s[96:97]
	s_branch .Lwc0_done

.Lwc0_p1:
	s_waitcnt vmcnt(0)
	v_readlane_b32 s52, v213, 8
	v_readlane_b32 s53, v213, 9
	v_readlane_b32 s32, v213, 10
	v_readlane_b32 s35, v213, 11
	ds_write_b32 v202, v138 offset:0
	ds_write_b32 v202, v139 offset:1040
	ds_write_b32 v202, v140 offset:2080
	ds_write_b32 v202, v141 offset:3120
	ds_write_b32 v202, v142 offset:4160
	ds_write_b32 v202, v143 offset:5200
	ds_write_b32 v202, v144 offset:6240
	ds_write_b32 v202, v145 offset:7280
	ds_write_b32 v202, v146 offset:8320
	ds_write_b32 v202, v147 offset:9360
	ds_write_b32 v202, v148 offset:10400
	ds_write_b32 v202, v149 offset:11440
	ds_write_b32 v202, v150 offset:12480
	ds_write_b32 v202, v151 offset:13520
	ds_write_b32 v202, v152 offset:14560
	ds_write_b32 v202, v153 offset:15600
	v_mad_u32_u24 v208, v211, s35, v212
	s_waitcnt lgkmcnt(0)
	s_barrier
	ds_read2_b32 v[186:187], v203 offset1:65
	ds_read2_b32 v[188:189], v203 offset0:130 offset1:195
	ds_read2_b32 v[190:191], v204 offset0:4 offset1:69
	ds_read2_b32 v[192:193], v204 offset0:134 offset1:199
	ds_read2_b32 v[194:195], v205 offset1:65
	ds_read2_b32 v[196:197], v205 offset0:130 offset1:195
	ds_read2_b32 v[198:199], v206 offset0:4 offset1:69
	ds_read2_b32 v[200:201], v206 offset0:134 offset1:199
	s_add_u32 s96, s52, s32
	s_addc_u32 s97, s53, 0
	s_waitcnt lgkmcnt(0)
	s_barrier
	v_cvt_pk_bf16_f32 v186, v186, v187
	v_cvt_pk_bf16_f32 v187, v188, v189
	v_cvt_pk_bf16_f32 v188, v190, v191
	v_cvt_pk_bf16_f32 v189, v192, v193
	v_cvt_pk_bf16_f32 v194, v194, v195
	v_cvt_pk_bf16_f32 v195, v196, v197
	v_cvt_pk_bf16_f32 v196, v198, v199
	v_cvt_pk_bf16_f32 v197, v200, v201
	global_store_dwordx4 v208, v[186:189], s[52:53]
	global_store_dwordx4 v208, v[194:197], s[96:97]

.LBB0_378:
	s_cmp_lg_u32 s50, s33
	s_mov_b64 s[2:3], -1
	s_cbranch_scc0 .LBB0_381
	s_sub_i32 s2, s60, s33
	s_cmpk_lt_i32 s2, 0xbe4
	s_cselect_b64 s[2:3], -1, 0
	s_and_b64 s[0:1], s[0:1], s[2:3]
	s_andn2_b64 vcc, exec, s[0:1]
	s_mov_b32 s8, s20
	s_mov_b32 s33, s19
	s_mov_b32 s34, s28
	s_cbranch_vccnz .LBB0_380
	s_sub_u32 s100, s60, 0x100
	s_movk_i32 s67, 0x100
	s_movk_i32 s66, 0xbc0
	s_waitcnt vmcnt(0) lgkmcnt(0)
	s_barrier
	v_readlane_b32 s0, v242, 42
	v_readlane_b32 s1, v242, 43
	v_readlane_b32 s4, v242, 3
	v_readlane_b32 s5, v242, 4
	v_lshrrev_b32_e32 v209, 6, v137
	v_and_b32_e32 v210, 63, v137
	s_sub_u32 s0, s0, 0x118
	s_subb_u32 s1, s1, 0
	v_lshrrev_b32_e32 v211, 3, v137
	v_and_b32_e32 v212, 7, v137
	v_mul_u32_u24_e32 v202, 65, v209
	v_mul_u32_u24_e32 v203, 0x208, v212
	v_add_u32_e32 v202, v202, v210
	v_add_u32_e32 v203, v203, v211
	v_lshlrev_b32_e32 v202, 2, v202
	v_lshlrev_b32_e32 v203, 2, v203
	v_lshlrev_b32_e32 v210, 2, v210
	v_lshlrev_b32_e32 v212, 4, v212
	v_add_u32_e32 v204, 0x400, v203
	v_add_u32_e32 v205, 0x80, v203
	v_add_u32_e32 v206, 0x480, v203
	s_cmp_ge_u32 s100, s66
	s_cbranch_scc1 .Lwc1_done
	s_cmpk_ge_u32 s100, 0x900
	s_cbranch_scc1 .Lwc1_t3_1
	s_cmpk_ge_u32 s100, 0x380
	s_cbranch_scc1 .Lwc1_t2_1
	s_cmpk_ge_u32 s100, 0x280
	s_cbranch_scc1 .Lwc1_t1_1
	s_movk_i32 s41, 0x78
	s_sub_u32 s99, s100, 0
	s_mul_i32 s44, s99, 0x66667
	s_lshr_b32 s44, s44, 24
	s_mul_i32 s36, s44, 40
	s_sub_u32 s99, s99, s36
	s_mul_i32 s38, s44, 0xa0000
	s_lshl_b32 s36, s99, 8
	s_add_u32 s38, s38, s36
	s_add_u32 s38, s38, 0xa00000
	s_lshl_b32 s36, s99, 6
	s_mov_b32 s32, 0x10000
	s_mul_i32 s36, s36, 0x800
	s_lshl_b32 s44, s44, 7
	s_add_u32 s36, s36, s44
	s_add_u32 s36, s36, 0x500000
	s_mov_b32 s37, 0xa000
	s_movk_i32 s44, 0x800
	s_mov_b32 s99, 0x2800
	s_branch .Lwc1_tj_1
.Lwc1_t1_1:
	s_movk_i32 s41, 0x80
	s_sub_u32 s99, s100, 640
	s_mul_i32 s44, s99, 0x100000
	s_lshr_b32 s44, s44, 24
	s_mul_i32 s36, s44, 16
	s_sub_u32 s99, s99, s36
	s_mul_i32 s38, s44, 0x40000
	s_lshl_b32 s36, s99, 8
	s_add_u32 s38, s38, s36
	s_add_u32 s38, s38, 0x400000
	s_lshl_b32 s36, s99, 6
	s_mov_b32 s32, 0x10000
	s_mul_i32 s36, s36, 0x800
	s_lshl_b32 s44, s44, 7
	s_add_u32 s36, s36, s44
	s_add_u32 s36, s36, 0xc00000
	s_mov_b32 s37, 0x4000
	s_movk_i32 s44, 0x800
	s_mov_b32 s99, 0x1000
	s_branch .Lwc1_tj_1
.Lwc1_t2_1:
	s_movk_i32 s41, 0xf0
	s_sub_u32 s99, s100, 896
	s_mul_i32 s44, s99, 0x2e8bb
	s_lshr_b32 s44, s44, 24
	s_mul_i32 s36, s44, 88
	s_sub_u32 s99, s99, s36
	s_mul_i32 s38, s44, 0x160000
	s_lshl_b32 s36, s99, 8
	s_add_u32 s38, s38, s36
	s_add_u32 s38, s38, 0x1600000
	s_cmpk_ge_u32 s99, 44
	s_cselect_b32 s36, 44, 0
	s_cselect_b32 s37, 32, 0
	s_sub_u32 s36, s99, s36
	s_lshl_b32 s36, s36, 7
	s_add_u32 s36, s36, s37
	s_mov_b32 s32, 0x20000
	s_mul_i32 s36, s36, 0x800
	s_lshl_b32 s44, s44, 7
	s_add_u32 s36, s36, s44
	s_add_u32 s36, s36, 0x1900000
	s_mov_b32 s37, 0x16000
	s_movk_i32 s44, 0x800
	s_mov_b32 s99, 0x5800
	s_branch .Lwc1_tj_1
.Lwc1_t3_1:
	s_movk_i32 s41, 0xf8
	s_sub_u32 s99, s100, 2304
	s_mul_i32 s44, s99, 0x100000
	s_lshr_b32 s44, s44, 24
	s_mul_i32 s36, s44, 16
	s_sub_u32 s99, s99, s36
	s_mul_i32 s38, s44, 0x40000
	s_lshl_b32 s36, s99, 8
	s_add_u32 s38, s38, s36
	s_add_u32 s38, s38, 0xb00000
	s_lshl_b32 s36, s99, 6
	s_mov_b32 s32, 0x2c000
	s_mul_i32 s36, s36, 0x1600
	s_lshl_b32 s44, s44, 7
	s_add_u32 s36, s36, s44
	s_add_u32 s36, s36, 0x2980000
	s_mov_b32 s37, 0x4000
	s_movk_i32 s44, 0x1600
	s_mov_b32 s99, 0x1000
.Lwc1_tj_1:
	s_load_dwordx2 s[2:3], s[0:1], s41
	s_add_u32 s52, s4, s36
	s_addc_u32 s53, s5, 0
	v_mad_u32_u24 v207, v209, s99, v210
	v_writelane_b32 v213, s52, 8
	v_writelane_b32 v213, s53, 9
	v_writelane_b32 v213, s32, 10
	v_writelane_b32 v213, s44, 11
	s_add_u32 s100, s100, s67
	s_waitcnt lgkmcnt(0)
	s_add_u32 s38, s2, s38
	s_addc_u32 s39, s3, 0
	global_load_dword v138, v207, s[38:39]
	s_add_u32 s38, s38, s37
	s_addc_u32 s39, s39, 0
	global_load_dword v139, v207, s[38:39]
	s_add_u32 s38, s38, s37
	s_addc_u32 s39, s39, 0
	global_load_dword v140, v207, s[38:39]
	s_add_u32 s38, s38, s37
	s_addc_u32 s39, s39, 0
	global_load_dword v141, v207, s[38:39]
	s_add_u32 s38, s38, s37
	s_addc_u32 s39, s39, 0
	global_load_dword v142, v207, s[38:39]
	s_add_u32 s38, s38, s37
	s_addc_u32 s39, s39, 0
	global_load_dword v143, v207, s[38:39]
	s_add_u32 s38, s38, s37
	s_addc_u32 s39, s39, 0
	global_load_dword v144, v207, s[38:39]
	s_add_u32 s38, s38, s37
	s_addc_u32 s39, s39, 0
	global_load_dword v145, v207, s[38:39]
	s_add_u32 s38, s38, s37
	s_addc_u32 s39, s39, 0
	global_load_dword v146, v207, s[38:39]
	s_add_u32 s38, s38, s37
	s_addc_u32 s39, s39, 0
	global_load_dword v147, v207, s[38:39]
	s_add_u32 s38, s38, s37
	s_addc_u32 s39, s39, 0
	global_load_dword v148, v207, s[38:39]
	s_add_u32 s38, s38, s37
	s_addc_u32 s39, s39, 0
	global_load_dword v149, v207, s[38:39]
	s_add_u32 s38, s38, s37
	s_addc_u32 s39, s39, 0
	global_load_dword v150, v207, s[38:39]
	s_add_u32 s38, s38, s37
	s_addc_u32 s39, s39, 0
	global_load_dword v151, v207, s[38:39]
	s_add_u32 s38, s38, s37
	s_addc_u32 s39, s39, 0
	global_load_dword v152, v207, s[38:39]
	s_add_u32 s38, s38, s37
	s_addc_u32 s39, s39, 0
	global_load_dword v153, v207, s[38:39]
	s_cmp_ge_u32 s100, s66
	s_cbranch_scc1 .Lwc1_p1
	s_cmpk_ge_u32 s100, 0x900
	s_cbranch_scc1 .Lwc1_t3_2
	s_cmpk_ge_u32 s100, 0x380
	s_cbranch_scc1 .Lwc1_t2_2
	s_cmpk_ge_u32 s100, 0x280
	s_cbranch_scc1 .Lwc1_t1_2
	s_movk_i32 s41, 0x78
	s_sub_u32 s99, s100, 0
	s_mul_i32 s44, s99, 0x66667
	s_lshr_b32 s44, s44, 24
	s_mul_i32 s36, s44, 40
	s_sub_u32 s99, s99, s36
	s_mul_i32 s38, s44, 0xa0000
	s_lshl_b32 s36, s99, 8
	s_add_u32 s38, s38, s36
	s_add_u32 s38, s38, 0xa00000
	s_lshl_b32 s36, s99, 6
	s_mov_b32 s32, 0x10000
	s_mul_i32 s36, s36, 0x800
	s_lshl_b32 s44, s44, 7
	s_add_u32 s36, s36, s44
	s_add_u32 s36, s36, 0x500000
	s_mov_b32 s37, 0xa000
	s_movk_i32 s44, 0x800
	s_mov_b32 s99, 0x2800
	s_branch .Lwc1_tj_2

.Lwc1_tj_2:
	s_load_dwordx2 s[2:3], s[0:1], s41
	s_add_u32 s52, s4, s36
	s_addc_u32 s53, s5, 0
	v_mad_u32_u24 v207, v209, s99, v210
	v_writelane_b32 v213, s52, 12
	v_writelane_b32 v213, s53, 13
	v_writelane_b32 v213, s32, 14
	v_writelane_b32 v213, s44, 15
	s_add_u32 s100, s100, s67
	s_waitcnt lgkmcnt(0)
	s_add_u32 s38, s2, s38
	s_addc_u32 s39, s3, 0
	global_load_dword v154, v207, s[38:39]
	s_add_u32 s38, s38, s37
	s_addc_u32 s39, s39, 0
	global_load_dword v155, v207, s[38:39]
	s_add_u32 s38, s38, s37
	s_addc_u32 s39, s39, 0
	global_load_dword v156, v207, s[38:39]
	s_add_u32 s38, s38, s37
	s_addc_u32 s39, s39, 0
	global_load_dword v157, v207, s[38:39]
	s_add_u32 s38, s38, s37
	s_addc_u32 s39, s39, 0
	global_load_dword v158, v207, s[38:39]
	s_add_u32 s38, s38, s37
	s_addc_u32 s39, s39, 0
	global_load_dword v159, v207, s[38:39]
	s_add_u32 s38, s38, s37
	s_addc_u32 s39, s39, 0
	global_load_dword v160, v207, s[38:39]
	s_add_u32 s38, s38, s37
	s_addc_u32 s39, s39, 0
	global_load_dword v161, v207, s[38:39]
	s_add_u32 s38, s38, s37
	s_addc_u32 s39, s39, 0
	global_load_dword v162, v207, s[38:39]
	s_add_u32 s38, s38, s37
	s_addc_u32 s39, s39, 0
	global_load_dword v163, v207, s[38:39]
	s_add_u32 s38, s38, s37
	s_addc_u32 s39, s39, 0
	global_load_dword v164, v207, s[38:39]
	s_add_u32 s38, s38, s37
	s_addc_u32 s39, s39, 0
	global_load_dword v165, v207, s[38:39]
	s_add_u32 s38, s38, s37
	s_addc_u32 s39, s39, 0
	global_load_dword v166, v207, s[38:39]
	s_add_u32 s38, s38, s37
	s_addc_u32 s39, s39, 0
	global_load_dword v167, v207, s[38:39]
	s_add_u32 s38, s38, s37
	s_addc_u32 s39, s39, 0
	global_load_dword v168, v207, s[38:39]
	s_add_u32 s38, s38, s37
	s_addc_u32 s39, s39, 0
	global_load_dword v169, v207, s[38:39]
	s_cmp_ge_u32 s100, s66
	s_cbranch_scc1 .Lwc1_p2
	s_cmpk_ge_u32 s100, 0x900
	s_cbranch_scc1 .Lwc1_t3_3
	s_cmpk_ge_u32 s100, 0x380
	s_cbranch_scc1 .Lwc1_t2_3
	s_cmpk_ge_u32 s100, 0x280
	s_cbranch_scc1 .Lwc1_t1_3
	s_movk_i32 s41, 0x78
	s_sub_u32 s99, s100, 0
	s_mul_i32 s44, s99, 0x66667
	s_lshr_b32 s44, s44, 24
	s_mul_i32 s36, s44, 40
	s_sub_u32 s99, s99, s36
	s_mul_i32 s38, s44, 0xa0000
	s_lshl_b32 s36, s99, 8
	s_add_u32 s38, s38, s36
	s_add_u32 s38, s38, 0xa00000
	s_lshl_b32 s36, s99, 6
	s_mov_b32 s32, 0x10000
	s_mul_i32 s36, s36, 0x800
	s_lshl_b32 s44, s44, 7
	s_add_u32 s36, s36, s44
	s_add_u32 s36, s36, 0x500000
	s_mov_b32 s37, 0xa000
	s_movk_i32 s44, 0x800
	s_mov_b32 s99, 0x2800
	s_branch .Lwc1_tj_3

.Lwc1_loop:
	s_waitcnt vmcnt(32)
	v_readlane_b32 s52, v213, 8
	v_readlane_b32 s53, v213, 9
	v_readlane_b32 s32, v213, 10
	v_readlane_b32 s35, v213, 11
	ds_write_b32 v202, v138 offset:0
	ds_write_b32 v202, v139 offset:1040
	ds_write_b32 v202, v140 offset:2080
	ds_write_b32 v202, v141 offset:3120
	ds_write_b32 v202, v142 offset:4160
	ds_write_b32 v202, v143 offset:5200
	ds_write_b32 v202, v144 offset:6240
	ds_write_b32 v202, v145 offset:7280
	ds_write_b32 v202, v146 offset:8320
	ds_write_b32 v202, v147 offset:9360
	ds_write_b32 v202, v148 offset:10400
	ds_write_b32 v202, v149 offset:11440
	ds_write_b32 v202, v150 offset:12480
	ds_write_b32 v202, v151 offset:13520
	ds_write_b32 v202, v152 offset:14560
	ds_write_b32 v202, v153 offset:15600
	v_mad_u32_u24 v208, v211, s35, v212
	s_waitcnt lgkmcnt(0)
	s_barrier
	ds_read2_b32 v[186:187], v203 offset1:65
	ds_read2_b32 v[188:189], v203 offset0:130 offset1:195
	ds_read2_b32 v[190:191], v204 offset0:4 offset1:69
	ds_read2_b32 v[192:193], v204 offset0:134 offset1:199
	ds_read2_b32 v[194:195], v205 offset1:65
	ds_read2_b32 v[196:197], v205 offset0:130 offset1:195
	ds_read2_b32 v[198:199], v206 offset0:4 offset1:69
	ds_read2_b32 v[200:201], v206 offset0:134 offset1:199
	s_add_u32 s96, s52, s32
	s_addc_u32 s97, s53, 0
	s_waitcnt lgkmcnt(0)
	s_barrier
	v_cvt_pk_bf16_f32 v186, v186, v187
	v_cvt_pk_bf16_f32 v187, v188, v189
	v_cvt_pk_bf16_f32 v188, v190, v191
	v_cvt_pk_bf16_f32 v189, v192, v193
	v_cvt_pk_bf16_f32 v194, v194, v195
	v_cvt_pk_bf16_f32 v195, v196, v197
	v_cvt_pk_bf16_f32 v196, v198, v199
	v_cvt_pk_bf16_f32 v197, v200, v201
	global_store_dwordx4 v208, v[186:189], s[52:53]
	global_store_dwordx4 v208, v[194:197], s[96:97]
	s_cmp_ge_u32 s100, s66
	s_cbranch_scc1 .Lwc1_tail0
	s_cmpk_ge_u32 s100, 0x900
	s_cbranch_scc1 .Lwc1_t3_4
	s_cmpk_ge_u32 s100, 0x380
	s_cbranch_scc1 .Lwc1_t2_4
	s_cmpk_ge_u32 s100, 0x280
	s_cbranch_scc1 .Lwc1_t1_4
	s_movk_i32 s41, 0x78
	s_sub_u32 s99, s100, 0
	s_mul_i32 s44, s99, 0x66667
	s_lshr_b32 s44, s44, 24
	s_mul_i32 s36, s44, 40
	s_sub_u32 s99, s99, s36
	s_mul_i32 s38, s44, 0xa0000
	s_lshl_b32 s36, s99, 8
	s_add_u32 s38, s38, s36
	s_add_u32 s38, s38, 0xa00000
	s_lshl_b32 s36, s99, 6
	s_mov_b32 s32, 0x10000
	s_mul_i32 s36, s36, 0x800
	s_lshl_b32 s44, s44, 7
	s_add_u32 s36, s36, s44
	s_add_u32 s36, s36, 0x500000
	s_mov_b32 s37, 0xa000
	s_movk_i32 s44, 0x800
	s_mov_b32 s99, 0x2800
	s_branch .Lwc1_tj_4

.Lwc1_tj_4:
	s_load_dwordx2 s[2:3], s[0:1], s41
	s_add_u32 s52, s4, s36
	s_addc_u32 s53, s5, 0
	v_mad_u32_u24 v207, v209, s99, v210
	v_writelane_b32 v213, s52, 8
	v_writelane_b32 v213, s53, 9
	v_writelane_b32 v213, s32, 10
	v_writelane_b32 v213, s44, 11
	s_add_u32 s100, s100, s67
	s_waitcnt lgkmcnt(0)
	s_add_u32 s38, s2, s38
	s_addc_u32 s39, s3, 0
	global_load_dword v138, v207, s[38:39]
	s_add_u32 s38, s38, s37
	s_addc_u32 s39, s39, 0
	global_load_dword v139, v207, s[38:39]
	s_add_u32 s38, s38, s37
	s_addc_u32 s39, s39, 0
	global_load_dword v140, v207, s[38:39]
	s_add_u32 s38, s38, s37
	s_addc_u32 s39, s39, 0
	global_load_dword v141, v207, s[38:39]
	s_add_u32 s38, s38, s37
	s_addc_u32 s39, s39, 0
	global_load_dword v142, v207, s[38:39]
	s_add_u32 s38, s38, s37
	s_addc_u32 s39, s39, 0
	global_load_dword v143, v207, s[38:39]
	s_add_u32 s38, s38, s37
	s_addc_u32 s39, s39, 0
	global_load_dword v144, v207, s[38:39]
	s_add_u32 s38, s38, s37
	s_addc_u32 s39, s39, 0
	global_load_dword v145, v207, s[38:39]
	s_add_u32 s38, s38, s37
	s_addc_u32 s39, s39, 0
	global_load_dword v146, v207, s[38:39]
	s_add_u32 s38, s38, s37
	s_addc_u32 s39, s39, 0
	global_load_dword v147, v207, s[38:39]
	s_add_u32 s38, s38, s37
	s_addc_u32 s39, s39, 0
	global_load_dword v148, v207, s[38:39]
	s_add_u32 s38, s38, s37
	s_addc_u32 s39, s39, 0
	global_load_dword v149, v207, s[38:39]
	s_add_u32 s38, s38, s37
	s_addc_u32 s39, s39, 0
	global_load_dword v150, v207, s[38:39]
	s_add_u32 s38, s38, s37
	s_addc_u32 s39, s39, 0
	global_load_dword v151, v207, s[38:39]
	s_add_u32 s38, s38, s37
	s_addc_u32 s39, s39, 0
	global_load_dword v152, v207, s[38:39]
	s_add_u32 s38, s38, s37
	s_addc_u32 s39, s39, 0
	global_load_dword v153, v207, s[38:39]
	s_waitcnt vmcnt(32)
	v_readlane_b32 s52, v213, 12
	v_readlane_b32 s53, v213, 13
	v_readlane_b32 s32, v213, 14
	v_readlane_b32 s35, v213, 15
	ds_write_b32 v202, v154 offset:0
	ds_write_b32 v202, v155 offset:1040
	ds_write_b32 v202, v156 offset:2080
	ds_write_b32 v202, v157 offset:3120
	ds_write_b32 v202, v158 offset:4160
	ds_write_b32 v202, v159 offset:5200
	ds_write_b32 v202, v160 offset:6240
	ds_write_b32 v202, v161 offset:7280
	ds_write_b32 v202, v162 offset:8320
	ds_write_b32 v202, v163 offset:9360
	ds_write_b32 v202, v164 offset:10400
	ds_write_b32 v202, v165 offset:11440
	ds_write_b32 v202, v166 offset:12480
	ds_write_b32 v202, v167 offset:13520
	ds_write_b32 v202, v168 offset:14560
	ds_write_b32 v202, v169 offset:15600
	v_mad_u32_u24 v208, v211, s35, v212
	s_waitcnt lgkmcnt(0)
	s_barrier
	ds_read2_b32 v[186:187], v203 offset1:65
	ds_read2_b32 v[188:189], v203 offset0:130 offset1:195
	ds_read2_b32 v[190:191], v204 offset0:4 offset1:69
	ds_read2_b32 v[192:193], v204 offset0:134 offset1:199
	ds_read2_b32 v[194:195], v205 offset1:65
	ds_read2_b32 v[196:197], v205 offset0:130 offset1:195
	ds_read2_b32 v[198:199], v206 offset0:4 offset1:69
	ds_read2_b32 v[200:201], v206 offset0:134 offset1:199
	s_add_u32 s96, s52, s32
	s_addc_u32 s97, s53, 0
	s_waitcnt lgkmcnt(0)
	s_barrier
	v_cvt_pk_bf16_f32 v186, v186, v187
	v_cvt_pk_bf16_f32 v187, v188, v189
	v_cvt_pk_bf16_f32 v188, v190, v191
	v_cvt_pk_bf16_f32 v189, v192, v193
	v_cvt_pk_bf16_f32 v194, v194, v195
	v_cvt_pk_bf16_f32 v195, v196, v197
	v_cvt_pk_bf16_f32 v196, v198, v199
	v_cvt_pk_bf16_f32 v197, v200, v201
	global_store_dwordx4 v208, v[186:189], s[52:53]
	global_store_dwordx4 v208, v[194:197], s[96:97]
	s_cmp_ge_u32 s100, s66
	s_cbranch_scc1 .Lwc1_tail1
	s_cmpk_ge_u32 s100, 0x900
	s_cbranch_scc1 .Lwc1_t3_5
	s_cmpk_ge_u32 s100, 0x380
	s_cbranch_scc1 .Lwc1_t2_5
	s_cmpk_ge_u32 s100, 0x280
	s_cbranch_scc1 .Lwc1_t1_5
	s_movk_i32 s41, 0x78
	s_sub_u32 s99, s100, 0
	s_mul_i32 s44, s99, 0x66667
	s_lshr_b32 s44, s44, 24
	s_mul_i32 s36, s44, 40
	s_sub_u32 s99, s99, s36
	s_mul_i32 s38, s44, 0xa0000
	s_lshl_b32 s36, s99, 8
	s_add_u32 s38, s38, s36
	s_add_u32 s38, s38, 0xa00000
	s_lshl_b32 s36, s99, 6
	s_mov_b32 s32, 0x10000
	s_mul_i32 s36, s36, 0x800
	s_lshl_b32 s44, s44, 7
	s_add_u32 s36, s36, s44
	s_add_u32 s36, s36, 0x500000
	s_mov_b32 s37, 0xa000
	s_movk_i32 s44, 0x800
	s_mov_b32 s99, 0x2800
	s_branch .Lwc1_tj_5

.Lwc1_tj_5:
	s_load_dwordx2 s[2:3], s[0:1], s41
	s_add_u32 s52, s4, s36
	s_addc_u32 s53, s5, 0
	v_mad_u32_u24 v207, v209, s99, v210
	v_writelane_b32 v213, s52, 12
	v_writelane_b32 v213, s53, 13
	v_writelane_b32 v213, s32, 14
	v_writelane_b32 v213, s44, 15
	s_add_u32 s100, s100, s67
	s_waitcnt lgkmcnt(0)
	s_add_u32 s38, s2, s38
	s_addc_u32 s39, s3, 0
	global_load_dword v154, v207, s[38:39]
	s_add_u32 s38, s38, s37
	s_addc_u32 s39, s39, 0
	global_load_dword v155, v207, s[38:39]
	s_add_u32 s38, s38, s37
	s_addc_u32 s39, s39, 0
	global_load_dword v156, v207, s[38:39]
	s_add_u32 s38, s38, s37
	s_addc_u32 s39, s39, 0
	global_load_dword v157, v207, s[38:39]
	s_add_u32 s38, s38, s37
	s_addc_u32 s39, s39, 0
	global_load_dword v158, v207, s[38:39]
	s_add_u32 s38, s38, s37
	s_addc_u32 s39, s39, 0
	global_load_dword v159, v207, s[38:39]
	s_add_u32 s38, s38, s37
	s_addc_u32 s39, s39, 0
	global_load_dword v160, v207, s[38:39]
	s_add_u32 s38, s38, s37
	s_addc_u32 s39, s39, 0
	global_load_dword v161, v207, s[38:39]
	s_add_u32 s38, s38, s37
	s_addc_u32 s39, s39, 0
	global_load_dword v162, v207, s[38:39]
	s_add_u32 s38, s38, s37
	s_addc_u32 s39, s39, 0
	global_load_dword v163, v207, s[38:39]
	s_add_u32 s38, s38, s37
	s_addc_u32 s39, s39, 0
	global_load_dword v164, v207, s[38:39]
	s_add_u32 s38, s38, s37
	s_addc_u32 s39, s39, 0
	global_load_dword v165, v207, s[38:39]
	s_add_u32 s38, s38, s37
	s_addc_u32 s39, s39, 0
	global_load_dword v166, v207, s[38:39]
	s_add_u32 s38, s38, s37
	s_addc_u32 s39, s39, 0
	global_load_dword v167, v207, s[38:39]
	s_add_u32 s38, s38, s37
	s_addc_u32 s39, s39, 0
	global_load_dword v168, v207, s[38:39]
	s_add_u32 s38, s38, s37
	s_addc_u32 s39, s39, 0
	global_load_dword v169, v207, s[38:39]
	s_waitcnt vmcnt(32)
	v_readlane_b32 s52, v213, 16
	v_readlane_b32 s53, v213, 17
	v_readlane_b32 s32, v213, 18
	v_readlane_b32 s35, v213, 19
	ds_write_b32 v202, v170 offset:0
	ds_write_b32 v202, v171 offset:1040
	ds_write_b32 v202, v172 offset:2080
	ds_write_b32 v202, v173 offset:3120
	ds_write_b32 v202, v174 offset:4160
	ds_write_b32 v202, v175 offset:5200
	ds_write_b32 v202, v176 offset:6240
	ds_write_b32 v202, v177 offset:7280
	ds_write_b32 v202, v178 offset:8320
	ds_write_b32 v202, v179 offset:9360
	ds_write_b32 v202, v180 offset:10400
	ds_write_b32 v202, v181 offset:11440
	ds_write_b32 v202, v182 offset:12480
	ds_write_b32 v202, v183 offset:13520
	ds_write_b32 v202, v184 offset:14560
	ds_write_b32 v202, v185 offset:15600
	v_mad_u32_u24 v208, v211, s35, v212
	s_waitcnt lgkmcnt(0)
	s_barrier
	ds_read2_b32 v[186:187], v203 offset1:65
	ds_read2_b32 v[188:189], v203 offset0:130 offset1:195
	ds_read2_b32 v[190:191], v204 offset0:4 offset1:69
	ds_read2_b32 v[192:193], v204 offset0:134 offset1:199
	ds_read2_b32 v[194:195], v205 offset1:65
	ds_read2_b32 v[196:197], v205 offset0:130 offset1:195
	ds_read2_b32 v[198:199], v206 offset0:4 offset1:69
	ds_read2_b32 v[200:201], v206 offset0:134 offset1:199
	s_add_u32 s96, s52, s32
	s_addc_u32 s97, s53, 0
	s_waitcnt lgkmcnt(0)
	s_barrier
	v_cvt_pk_bf16_f32 v186, v186, v187
	v_cvt_pk_bf16_f32 v187, v188, v189
	v_cvt_pk_bf16_f32 v188, v190, v191
	v_cvt_pk_bf16_f32 v189, v192, v193
	v_cvt_pk_bf16_f32 v194, v194, v195
	v_cvt_pk_bf16_f32 v195, v196, v197
	v_cvt_pk_bf16_f32 v196, v198, v199
	v_cvt_pk_bf16_f32 v197, v200, v201
	global_store_dwordx4 v208, v[186:189], s[52:53]
	global_store_dwordx4 v208, v[194:197], s[96:97]
	s_cmp_ge_u32 s100, s66
	s_cbranch_scc1 .Lwc1_tail2
	s_cmpk_ge_u32 s100, 0x900
	s_cbranch_scc1 .Lwc1_t3_6
	s_cmpk_ge_u32 s100, 0x380
	s_cbranch_scc1 .Lwc1_t2_6
	s_cmpk_ge_u32 s100, 0x280
	s_cbranch_scc1 .Lwc1_t1_6
	s_movk_i32 s41, 0x78
	s_sub_u32 s99, s100, 0
	s_mul_i32 s44, s99, 0x66667
	s_lshr_b32 s44, s44, 24
	s_mul_i32 s36, s44, 40
	s_sub_u32 s99, s99, s36
	s_mul_i32 s38, s44, 0xa0000
	s_lshl_b32 s36, s99, 8
	s_add_u32 s38, s38, s36
	s_add_u32 s38, s38, 0xa00000
	s_lshl_b32 s36, s99, 6
	s_mov_b32 s32, 0x10000
	s_mul_i32 s36, s36, 0x800
	s_lshl_b32 s44, s44, 7
	s_add_u32 s36, s36, s44
	s_add_u32 s36, s36, 0x500000
	s_mov_b32 s37, 0xa000
	s_movk_i32 s44, 0x800
	s_mov_b32 s99, 0x2800
	s_branch .Lwc1_tj_6

.LBB0_905:
	v_writelane_b32 v241, s44, 47
	s_nop 1
	v_writelane_b32 v241, s45, 48
	s_or_b64 exec, exec, s[0:1]
	v_readlane_b32 s0, v242, 1
	v_readlane_b32 s2, v242, 3
	v_readlane_b32 s3, v242, 4
	s_add_u32 s76, s2, 0x30f4000
	s_addc_u32 s77, s3, 0
	s_add_u32 s4, s2, 0x2ff4000
	v_writelane_b32 v241, s4, 49
	s_addc_u32 s4, s3, 0
	v_writelane_b32 v241, s4, 50
	s_add_u32 s4, s2, 0x3034000
	v_writelane_b32 v241, s4, 51
	s_addc_u32 s4, s3, 0
	v_writelane_b32 v241, s4, 52
	s_add_u32 s4, s2, 0x3074000
	v_writelane_b32 v241, s4, 21
	s_addc_u32 s4, s3, 0
	v_writelane_b32 v241, s4, 22
	s_add_u32 s4, s2, 0x30b4000
	v_writelane_b32 v241, s4, 23
	s_addc_u32 s4, s3, 0
	s_add_u32 s70, s2, 0xddc8100
	s_addc_u32 s71, s3, 0
	v_readlane_b32 s1, v242, 2
	s_add_u32 s33, s0, 0x4800000
	v_writelane_b32 v241, s4, 24
	s_addc_u32 s67, s1, 0
	v_readlane_b32 s0, v242, 60
	v_readlane_b32 s4, v241, 0
	v_readlane_b32 s5, v241, 1
	v_readlane_b32 s6, v241, 2
	v_readlane_b32 s7, v241, 3
	v_readlane_b32 s8, v241, 4
	v_readlane_b32 s9, v241, 5
	v_readlane_b32 s10, v241, 6
	v_readlane_b32 s11, v241, 7
	v_readlane_b32 s12, v241, 8
	v_readlane_b32 s13, v241, 9
	v_readlane_b32 s14, v241, 10
	v_readlane_b32 s15, v241, 11
	v_writelane_b32 v241, s88, 16
	v_mbcnt_lo_u32_b32 v136, -1, 0
	s_cmp_lg_u64 s[12:13], 0
	v_writelane_b32 v241, s89, 17
	v_mbcnt_hi_u32_b32 v139, -1, v136
	v_writelane_b32 v241, s33, 15
	s_cselect_b64 s[72:73], -1, 0
	s_add_i32 s58, 0, 0x12000
	s_waitcnt lgkmcnt(0)
	v_and_b32_e32 v0, 64, v139
	v_writelane_b32 v241, s67, 20
	v_readlane_b32 s99, v242, 0
	s_mov_b32 s100, -1
	s_cmpk_lt_u32 s99, 96
	s_cselect_b32 s100, s99, s100
	v_mov_b32_e32 v144, s100
	s_mov_b32 s45, 0
	v_mov_b32_e32 v89, 0
	s_mov_b32 s59, 0x1c000
	s_movk_i32 s40, 0xfefe
	s_movk_i32 s41, 0x180
	s_movk_i32 s48, 0x580
	s_movk_i32 s49, 0x600
	s_add_i32 s69, 0, 0x6000
	s_add_i32 s96, 0, 0x500
	s_add_i32 s97, 0, 0x6500
	v_mov_b32_e32 v138, s58
	v_xor_b32_e32 v140, 16, v139
	v_add_u32_e32 v141, 64, v0
	v_xor_b32_e32 v142, 32, v139
	v_mov_b32_e32 v143, 0xf149f2ca
	v_writelane_b32 v241, s72, 18
	v_readfirstlane_b32 s99, v137
	s_cmp_lg_u32 s99, 64
	s_cbranch_scc1 .Lxbi3_skip
	buffer_inv sc1
	s_waitcnt vmcnt(0)

.LBB0_913:
	s_or_b64 exec, exec, s[4:5]
	s_waitcnt vmcnt(0)
	v_readfirstlane_b32 s4, v1
	s_nop 1
	v_add_u32_e32 v144, s4, v0
	v_add_u32_e32 v144, 0x60, v144

.LBB0_922:
	s_or_b64 exec, exec, s[2:3]
	s_waitcnt vmcnt(0)
	v_readfirstlane_b32 s2, v1
	s_nop 1
	v_add_u32_e32 v144, s2, v0
	v_add_u32_e32 v144, 0x60, v144

.Lls0_loop:
	s_waitcnt lgkmcnt(5)
	v_pk_mul_f32 v[4:5], v[0:1], v[28:29] neg_lo:[0,1] neg_hi:[0,1]
	ds_read_b128 v[68:71], v88 offset:3584
	v_pk_fma_f32 v[4:5], v[2:3], v[30:31], v[4:5] neg_lo:[0,1,0] neg_hi:[0,1,0]
	ds_read_b128 v[64:67], v88 offset:3328
	v_pk_mul_f32 v[8:9], v[24:25], v[16:17] op_sel_hi:[1,0]
	v_add_f32_e32 v4, v4, v5
	ds_read_b128 v[60:63], v88 offset:3072
	v_pk_mul_f32 v[10:11], v[26:27], v[16:17] op_sel_hi:[1,0]
	v_add_f32_dpp v4, v4, v4 quad_perm:[1,0,3,2] row_mask:0xf bank_mask:0xf bound_ctrl:1
	ds_read_b128 v[72:75], v88 offset:3840
	v_pk_fma_f32 v[8:9], v[0:1], v[20:21], v[8:9]
	v_add_f32_dpp v4, v4, v4 quad_perm:[2,3,0,1] row_mask:0xf bank_mask:0xf bound_ctrl:1
	v_pk_fma_f32 v[10:11], v[2:3], v[22:23], v[10:11]
	v_add_f32_dpp v198, v198, v198 row_ror:8 row_mask:0xf bank_mask:0x3 bound_ctrl:1
	v_add_f32_dpp v4, v4, v4 row_ror:4 row_mask:0xf bank_mask:0xf bound_ctrl:1
	ds_read_b128 v[76:79], v88 offset:4096
	v_add_f32_dpp v198, v206, v206 row_ror:8 row_mask:0xf bank_mask:0xc bound_ctrl:1
	v_add_f32_dpp v4, v4, v4 row_ror:8 row_mask:0xf bank_mask:0xf bound_ctrl:1
	v_pk_fma_f32 v[0:1], v[4:5], v[32:33], v[8:9] op_sel_hi:[0,1,1]
	v_pk_fma_f32 v[2:3], v[4:5], v[34:35], v[10:11] op_sel_hi:[0,1,1]
	v_pk_mul_f32 v[6:7], v[0:1], v[36:37]
	v_pk_fma_f32 v[6:7], v[2:3], v[38:39], v[6:7]
	v_add_f32_e32 v182, v6, v7
	ds_read2st64_b32 v[18:19], v90 offset0:17 offset1:23
	s_cmp_lt_u32 s28, 15
	s_cbranch_scc0 .Lls0_skip0
	global_load_dwordx4 v[104:107], v174, s[12:13]
	global_load_dwordx2 v[146:147], v175, s[14:15]
	global_load_dwordx2 v[148:149], v175, s[16:17]
	global_load_dwordx2 v[150:151], v175, s[18:19]
	global_load_dwordx4 v[108:111], v180, s[20:21]
	global_load_dword v170, v181, s[20:21]
	v_add_u32_e32 v174, s25, v174
	v_add_u32_e32 v175, s26, v175
	v_add_u32_e32 v180, s27, v180
	v_add_u32_e32 v181, s27, v181
.Lls0_back0:
	v_add_f32_dpp v199, v199, v199 row_ror:8 row_mask:0xf bank_mask:0x3 bound_ctrl:1
	v_add_f32_dpp v199, v207, v207 row_ror:8 row_mask:0xf bank_mask:0xc bound_ctrl:1
	s_waitcnt lgkmcnt(6)
	v_pk_mul_f32 v[4:5], v[0:1], v[48:49] neg_lo:[0,1] neg_hi:[0,1]
	ds_read_b128 v[92:95], v88 offset:5120
	v_pk_fma_f32 v[4:5], v[2:3], v[50:51], v[4:5] neg_lo:[0,1,0] neg_hi:[0,1,0]
	ds_read_b128 v[84:87], v88 offset:4864
	v_pk_mul_f32 v[8:9], v[44:45], v[16:17] op_sel:[0,1] op_sel_hi:[1,1]
	v_add_f32_e32 v4, v4, v5
	ds_read_b128 v[80:83], v88 offset:4608
	v_pk_mul_f32 v[10:11], v[46:47], v[16:17] op_sel:[0,1] op_sel_hi:[1,1]
	v_add_f32_dpp v4, v4, v4 quad_perm:[1,0,3,2] row_mask:0xf bank_mask:0xf bound_ctrl:1
	ds_read_b128 v[96:99], v88 offset:5376
	v_pk_fma_f32 v[8:9], v[0:1], v[40:41], v[8:9]
	v_add_f32_dpp v4, v4, v4 quad_perm:[2,3,0,1] row_mask:0xf bank_mask:0xf bound_ctrl:1
	v_pk_fma_f32 v[10:11], v[2:3], v[42:43], v[10:11]
	v_add_f32_dpp v200, v200, v200 row_ror:8 row_mask:0xf bank_mask:0x3 bound_ctrl:1
	v_add_f32_dpp v4, v4, v4 row_ror:4 row_mask:0xf bank_mask:0xf bound_ctrl:1
	ds_read_b128 v[100:103], v88 offset:5632
	v_add_f32_dpp v200, v208, v208 row_ror:8 row_mask:0xf bank_mask:0xc bound_ctrl:1
	v_add_f32_dpp v4, v4, v4 row_ror:8 row_mask:0xf bank_mask:0xf bound_ctrl:1
	v_pk_fma_f32 v[0:1], v[4:5], v[52:53], v[8:9] op_sel_hi:[0,1,1]
	v_pk_fma_f32 v[2:3], v[4:5], v[54:55], v[10:11] op_sel_hi:[0,1,1]
	v_pk_mul_f32 v[6:7], v[0:1], v[56:57]
	v_pk_fma_f32 v[6:7], v[2:3], v[58:59], v[6:7]
	v_add_f32_e32 v183, v6, v7
	v_add_f32_dpp v201, v201, v201 row_ror:8 row_mask:0xf bank_mask:0x3 bound_ctrl:1
	v_add_f32_dpp v201, v209, v209 row_ror:8 row_mask:0xf bank_mask:0xc bound_ctrl:1
	s_waitcnt lgkmcnt(5)
	v_pk_mul_f32 v[4:5], v[0:1], v[68:69] neg_lo:[0,1] neg_hi:[0,1]
	ds_read_b128 v[28:31], v88 offset:6656
	v_pk_fma_f32 v[4:5], v[2:3], v[70:71], v[4:5] neg_lo:[0,1,0] neg_hi:[0,1,0]
	ds_read_b128 v[24:27], v88 offset:6400
	v_pk_mul_f32 v[8:9], v[64:65], v[18:19] op_sel_hi:[1,0]
	v_add_f32_e32 v4, v4, v5
	ds_read_b128 v[20:23], v88 offset:6144
	v_pk_mul_f32 v[10:11], v[66:67], v[18:19] op_sel_hi:[1,0]
	v_add_f32_dpp v4, v4, v4 quad_perm:[1,0,3,2] row_mask:0xf bank_mask:0xf bound_ctrl:1
	ds_read_b128 v[32:35], v88 offset:6912
	v_pk_fma_f32 v[8:9], v[0:1], v[60:61], v[8:9]
	v_add_f32_dpp v4, v4, v4 quad_perm:[2,3,0,1] row_mask:0xf bank_mask:0xf bound_ctrl:1
	v_pk_fma_f32 v[10:11], v[2:3], v[62:63], v[10:11]
	v_add_f32_dpp v202, v202, v202 row_ror:8 row_mask:0xf bank_mask:0x3 bound_ctrl:1
	v_add_f32_dpp v4, v4, v4 row_ror:4 row_mask:0xf bank_mask:0xf bound_ctrl:1
	ds_read_b128 v[36:39], v88 offset:7168
	v_add_f32_dpp v202, v210, v210 row_ror:8 row_mask:0xf bank_mask:0xc bound_ctrl:1
	v_add_f32_dpp v4, v4, v4 row_ror:8 row_mask:0xf bank_mask:0xf bound_ctrl:1
	v_pk_fma_f32 v[0:1], v[4:5], v[72:73], v[8:9] op_sel_hi:[0,1,1]
	v_pk_fma_f32 v[2:3], v[4:5], v[74:75], v[10:11] op_sel_hi:[0,1,1]
	v_pk_mul_f32 v[6:7], v[0:1], v[76:77]
	v_pk_fma_f32 v[6:7], v[2:3], v[78:79], v[6:7]
	v_add_f32_e32 v184, v6, v7
	ds_read2st64_b32 v[16:17], v90 offset0:29 offset1:35
	v_add_f32_dpp v203, v203, v203 row_ror:8 row_mask:0xf bank_mask:0x3 bound_ctrl:1
	v_add_f32_dpp v203, v211, v211 row_ror:8 row_mask:0xf bank_mask:0xc bound_ctrl:1
	s_waitcnt lgkmcnt(6)
	v_pk_mul_f32 v[4:5], v[0:1], v[92:93] neg_lo:[0,1] neg_hi:[0,1]
	ds_read_b128 v[48:51], v88 offset:8192
	v_pk_fma_f32 v[4:5], v[2:3], v[94:95], v[4:5] neg_lo:[0,1,0] neg_hi:[0,1,0]
	ds_read_b128 v[44:47], v88 offset:7936
	v_pk_mul_f32 v[8:9], v[84:85], v[18:19] op_sel:[0,1] op_sel_hi:[1,1]
	v_add_f32_e32 v4, v4, v5
	ds_read_b128 v[40:43], v88 offset:7680
	v_pk_mul_f32 v[10:11], v[86:87], v[18:19] op_sel:[0,1] op_sel_hi:[1,1]
	v_add_f32_dpp v4, v4, v4 quad_perm:[1,0,3,2] row_mask:0xf bank_mask:0xf bound_ctrl:1
	ds_read_b128 v[52:55], v88 offset:8448
	v_pk_fma_f32 v[8:9], v[0:1], v[80:81], v[8:9]
	v_add_f32_dpp v4, v4, v4 quad_perm:[2,3,0,1] row_mask:0xf bank_mask:0xf bound_ctrl:1
	v_pk_fma_f32 v[10:11], v[2:3], v[82:83], v[10:11]
	v_add_f32_dpp v204, v204, v204 row_ror:8 row_mask:0xf bank_mask:0x3 bound_ctrl:1
	v_add_f32_dpp v4, v4, v4 row_ror:4 row_mask:0xf bank_mask:0xf bound_ctrl:1
	ds_read_b128 v[56:59], v88 offset:8704
	v_add_f32_dpp v204, v212, v212 row_ror:8 row_mask:0xf bank_mask:0xc bound_ctrl:1
	v_add_f32_dpp v4, v4, v4 row_ror:8 row_mask:0xf bank_mask:0xf bound_ctrl:1
	v_pk_fma_f32 v[0:1], v[4:5], v[96:97], v[8:9] op_sel_hi:[0,1,1]
	v_pk_fma_f32 v[2:3], v[4:5], v[98:99], v[10:11] op_sel_hi:[0,1,1]
	v_pk_mul_f32 v[6:7], v[0:1], v[100:101]
	v_pk_fma_f32 v[6:7], v[2:3], v[102:103], v[6:7]
	v_add_f32_e32 v185, v6, v7
	v_add_f32_dpp v205, v205, v205 row_ror:8 row_mask:0xf bank_mask:0x3 bound_ctrl:1
	v_add_f32_dpp v205, v213, v213 row_ror:8 row_mask:0xf bank_mask:0xc bound_ctrl:1
	s_waitcnt lgkmcnt(5)
	v_pk_mul_f32 v[4:5], v[0:1], v[28:29] neg_lo:[0,1] neg_hi:[0,1]
	ds_read_b128 v[68:71], v88 offset:9728
	v_pk_fma_f32 v[4:5], v[2:3], v[30:31], v[4:5] neg_lo:[0,1,0] neg_hi:[0,1,0]
	ds_read_b128 v[64:67], v88 offset:9472
	v_pk_mul_f32 v[8:9], v[24:25], v[16:17] op_sel_hi:[1,0]
	v_add_f32_e32 v4, v4, v5
	ds_read_b128 v[60:63], v88 offset:9216
	v_pk_mul_f32 v[10:11], v[26:27], v[16:17] op_sel_hi:[1,0]
	v_add_f32_dpp v4, v4, v4 quad_perm:[1,0,3,2] row_mask:0xf bank_mask:0xf bound_ctrl:1
	ds_read_b128 v[72:75], v88 offset:9984
	v_pk_fma_f32 v[8:9], v[0:1], v[20:21], v[8:9]
	v_add_f32_dpp v4, v4, v4 quad_perm:[2,3,0,1] row_mask:0xf bank_mask:0xf bound_ctrl:1
	v_pk_fma_f32 v[10:11], v[2:3], v[22:23], v[10:11]
	v_add_f32_dpp v198, v198, v198 row_shl:4 row_mask:0xf bank_mask:0x5 bound_ctrl:1
	v_add_f32_dpp v4, v4, v4 row_ror:4 row_mask:0xf bank_mask:0xf bound_ctrl:1
	ds_read_b128 v[76:79], v88 offset:10240
	v_add_f32_dpp v198, v202, v202 row_shr:4 row_mask:0xf bank_mask:0xa bound_ctrl:1
	v_add_f32_dpp v4, v4, v4 row_ror:8 row_mask:0xf bank_mask:0xf bound_ctrl:1
	v_pk_fma_f32 v[0:1], v[4:5], v[32:33], v[8:9] op_sel_hi:[0,1,1]
	v_pk_fma_f32 v[2:3], v[4:5], v[34:35], v[10:11] op_sel_hi:[0,1,1]
	v_pk_mul_f32 v[6:7], v[0:1], v[36:37]
	v_pk_fma_f32 v[6:7], v[2:3], v[38:39], v[6:7]
	v_add_f32_e32 v186, v6, v7
	ds_read2st64_b32 v[18:19], v90 offset0:41 offset1:47
	v_add_f32_dpp v199, v199, v199 row_shl:4 row_mask:0xf bank_mask:0x5 bound_ctrl:1
	v_add_f32_dpp v199, v203, v203 row_shr:4 row_mask:0xf bank_mask:0xa bound_ctrl:1
	s_waitcnt vmcnt(18)
	ds_write_b128 v91, v[112:115] offset:24576
	s_waitcnt lgkmcnt(7)
	v_pk_mul_f32 v[4:5], v[0:1], v[48:49] neg_lo:[0,1] neg_hi:[0,1]
	ds_read_b128 v[92:95], v88 offset:11264
	v_pk_fma_f32 v[4:5], v[2:3], v[50:51], v[4:5] neg_lo:[0,1,0] neg_hi:[0,1,0]
	ds_read_b128 v[84:87], v88 offset:11008
	v_pk_mul_f32 v[8:9], v[44:45], v[16:17] op_sel:[0,1] op_sel_hi:[1,1]
	v_add_f32_e32 v4, v4, v5
	ds_read_b128 v[80:83], v88 offset:10752
	v_pk_mul_f32 v[10:11], v[46:47], v[16:17] op_sel:[0,1] op_sel_hi:[1,1]
	v_add_f32_dpp v4, v4, v4 quad_perm:[1,0,3,2] row_mask:0xf bank_mask:0xf bound_ctrl:1
	ds_read_b128 v[96:99], v88 offset:11520
	v_pk_fma_f32 v[8:9], v[0:1], v[40:41], v[8:9]
	v_add_f32_dpp v4, v4, v4 quad_perm:[2,3,0,1] row_mask:0xf bank_mask:0xf bound_ctrl:1
	v_pk_fma_f32 v[10:11], v[2:3], v[42:43], v[10:11]
	v_add_f32_dpp v200, v200, v200 row_shl:4 row_mask:0xf bank_mask:0x5 bound_ctrl:1
	v_add_f32_dpp v4, v4, v4 row_ror:4 row_mask:0xf bank_mask:0xf bound_ctrl:1
	ds_read_b128 v[100:103], v88 offset:11776
	v_add_f32_dpp v200, v204, v204 row_shr:4 row_mask:0xf bank_mask:0xa bound_ctrl:1
	v_add_f32_dpp v4, v4, v4 row_ror:8 row_mask:0xf bank_mask:0xf bound_ctrl:1
	v_pk_fma_f32 v[0:1], v[4:5], v[52:53], v[8:9] op_sel_hi:[0,1,1]
	v_pk_fma_f32 v[2:3], v[4:5], v[54:55], v[10:11] op_sel_hi:[0,1,1]
	v_pk_mul_f32 v[6:7], v[0:1], v[56:57]
	v_pk_fma_f32 v[6:7], v[2:3], v[58:59], v[6:7]
	v_add_f32_e32 v187, v6, v7
	v_add_f32_dpp v201, v201, v201 row_shl:4 row_mask:0xf bank_mask:0x5 bound_ctrl:1
	v_add_f32_dpp v201, v205, v205 row_shr:4 row_mask:0xf bank_mask:0xa bound_ctrl:1
	ds_write_b128 v91, v[116:119] offset:25600
	ds_write_b32 v91, v171 offset:25856
	s_waitcnt lgkmcnt(8)
	v_pk_mul_f32 v[4:5], v[0:1], v[68:69] neg_lo:[0,1] neg_hi:[0,1]
	ds_read_b128 v[28:31], v88 offset:12800
	v_pk_fma_f32 v[4:5], v[2:3], v[70:71], v[4:5] neg_lo:[0,1,0] neg_hi:[0,1,0]
	ds_read_b128 v[24:27], v88 offset:12544
	v_pk_mul_f32 v[8:9], v[64:65], v[18:19] op_sel_hi:[1,0]
	v_add_f32_e32 v4, v4, v5
	ds_read_b128 v[20:23], v88 offset:12288
	v_pk_mul_f32 v[10:11], v[66:67], v[18:19] op_sel_hi:[1,0]
	v_add_f32_dpp v4, v4, v4 quad_perm:[1,0,3,2] row_mask:0xf bank_mask:0xf bound_ctrl:1
	ds_read_b128 v[32:35], v88 offset:13056
	v_pk_fma_f32 v[8:9], v[0:1], v[60:61], v[8:9]
	v_add_f32_dpp v4, v4, v4 quad_perm:[2,3,0,1] row_mask:0xf bank_mask:0xf bound_ctrl:1
	v_pk_fma_f32 v[10:11], v[2:3], v[62:63], v[10:11]
	v_add_f32_dpp v198, v198, v198 quad_perm:[1,0,3,2] row_mask:0xf bank_mask:0xf bound_ctrl:1
	v_add_f32_dpp v4, v4, v4 row_ror:4 row_mask:0xf bank_mask:0xf bound_ctrl:1
	ds_read_b128 v[36:39], v88 offset:13312
	v_add_f32_dpp v199, v199, v199 quad_perm:[1,0,3,2] row_mask:0xf bank_mask:0xf bound_ctrl:1
	v_add_f32_dpp v4, v4, v4 row_ror:8 row_mask:0xf bank_mask:0xf bound_ctrl:1
	v_pk_fma_f32 v[0:1], v[4:5], v[72:73], v[8:9] op_sel_hi:[0,1,1]
	v_pk_fma_f32 v[2:3], v[4:5], v[74:75], v[10:11] op_sel_hi:[0,1,1]
	v_pk_mul_f32 v[6:7], v[0:1], v[76:77]
	v_pk_fma_f32 v[6:7], v[2:3], v[78:79], v[6:7]
	v_add_f32_e32 v188, v6, v7
	ds_read2st64_b32 v[16:17], v90 offset0:53 offset1:59
	v_cndmask_b32_e64 v198, v198, v199, s[30:31]
	v_lshlrev_b32_e32 v176, 16, v152
	v_and_b32_e32 v177, 0xffff0000, v152
	s_waitcnt lgkmcnt(8)
	v_pk_mul_f32 v[4:5], v[0:1], v[92:93] neg_lo:[0,1] neg_hi:[0,1]
	ds_read_b128 v[48:51], v88 offset:14336
	v_pk_fma_f32 v[4:5], v[2:3], v[94:95], v[4:5] neg_lo:[0,1,0] neg_hi:[0,1,0]
	ds_read_b128 v[44:47], v88 offset:14080
	v_pk_mul_f32 v[8:9], v[84:85], v[18:19] op_sel:[0,1] op_sel_hi:[1,1]
	v_add_f32_e32 v4, v4, v5
	ds_read_b128 v[40:43], v88 offset:13824
	v_pk_mul_f32 v[10:11], v[86:87], v[18:19] op_sel:[0,1] op_sel_hi:[1,1]
	v_add_f32_dpp v4, v4, v4 quad_perm:[1,0,3,2] row_mask:0xf bank_mask:0xf bound_ctrl:1
	ds_read_b128 v[52:55], v88 offset:14592
	v_pk_fma_f32 v[8:9], v[0:1], v[80:81], v[8:9]
	v_add_f32_dpp v4, v4, v4 quad_perm:[2,3,0,1] row_mask:0xf bank_mask:0xf bound_ctrl:1
	v_pk_fma_f32 v[10:11], v[2:3], v[82:83], v[10:11]
	v_add_f32_dpp v200, v200, v200 quad_perm:[1,0,3,2] row_mask:0xf bank_mask:0xf bound_ctrl:1
	v_add_f32_dpp v4, v4, v4 row_ror:4 row_mask:0xf bank_mask:0xf bound_ctrl:1
	ds_read_b128 v[56:59], v88 offset:14848
	v_add_f32_dpp v201, v201, v201 quad_perm:[1,0,3,2] row_mask:0xf bank_mask:0xf bound_ctrl:1
	v_add_f32_dpp v4, v4, v4 row_ror:8 row_mask:0xf bank_mask:0xf bound_ctrl:1
	v_pk_fma_f32 v[0:1], v[4:5], v[96:97], v[8:9] op_sel_hi:[0,1,1]
	v_pk_fma_f32 v[2:3], v[4:5], v[98:99], v[10:11] op_sel_hi:[0,1,1]
	v_pk_mul_f32 v[6:7], v[0:1], v[100:101]
	v_pk_fma_f32 v[6:7], v[2:3], v[102:103], v[6:7]
	v_add_f32_e32 v189, v6, v7
	v_cndmask_b32_e64 v200, v200, v201, s[30:31]
	v_lshlrev_b32_e32 v178, 16, v153
	v_and_b32_e32 v179, 0xffff0000, v153
	s_waitcnt lgkmcnt(5)
	v_pk_mul_f32 v[4:5], v[0:1], v[28:29] neg_lo:[0,1] neg_hi:[0,1]
	ds_read_b128 v[68:71], v88 offset:15872
	v_pk_fma_f32 v[4:5], v[2:3], v[30:31], v[4:5] neg_lo:[0,1,0] neg_hi:[0,1,0]
	ds_read_b128 v[64:67], v88 offset:15616
	v_pk_mul_f32 v[8:9], v[24:25], v[16:17] op_sel_hi:[1,0]
	v_add_f32_e32 v4, v4, v5
	ds_read_b128 v[60:63], v88 offset:15360
	v_pk_mul_f32 v[10:11], v[26:27], v[16:17] op_sel_hi:[1,0]
	v_add_f32_dpp v4, v4, v4 quad_perm:[1,0,3,2] row_mask:0xf bank_mask:0xf bound_ctrl:1
	ds_read_b128 v[72:75], v88 offset:16128
	v_pk_fma_f32 v[8:9], v[0:1], v[20:21], v[8:9]
	v_add_f32_dpp v4, v4, v4 quad_perm:[2,3,0,1] row_mask:0xf bank_mask:0xf bound_ctrl:1
	v_pk_fma_f32 v[10:11], v[2:3], v[22:23], v[10:11]
	v_add_f32_dpp v198, v198, v198 quad_perm:[2,3,0,1] row_mask:0xf bank_mask:0xf bound_ctrl:1
	v_add_f32_dpp v4, v4, v4 row_ror:4 row_mask:0xf bank_mask:0xf bound_ctrl:1
	ds_read_b128 v[76:79], v88 offset:16384
	v_add_f32_dpp v200, v200, v200 quad_perm:[2,3,0,1] row_mask:0xf bank_mask:0xf bound_ctrl:1
	v_add_f32_dpp v4, v4, v4 row_ror:8 row_mask:0xf bank_mask:0xf bound_ctrl:1
	v_pk_fma_f32 v[0:1], v[4:5], v[32:33], v[8:9] op_sel_hi:[0,1,1]
	v_pk_fma_f32 v[2:3], v[4:5], v[34:35], v[10:11] op_sel_hi:[0,1,1]
	v_pk_mul_f32 v[6:7], v[0:1], v[36:37]
	v_pk_fma_f32 v[6:7], v[2:3], v[38:39], v[6:7]
	v_add_f32_e32 v190, v6, v7
	ds_read2st64_b32 v[18:19], v90 offset0:65 offset1:71
	v_cndmask_b32_e64 v214, v198, v200, s[34:35]
	v_cvt_pk_bf16_f32 v214, v214, v214
	ds_write_b128 v91, v[176:179] offset:24832
	v_lshlrev_b32_e32 v176, 16, v154
	s_waitcnt lgkmcnt(7)
	v_pk_mul_f32 v[4:5], v[0:1], v[48:49] neg_lo:[0,1] neg_hi:[0,1]
	ds_read_b128 v[92:95], v88 offset:17408
	v_pk_fma_f32 v[4:5], v[2:3], v[50:51], v[4:5] neg_lo:[0,1,0] neg_hi:[0,1,0]
	ds_read_b128 v[84:87], v88 offset:17152
	v_pk_mul_f32 v[8:9], v[44:45], v[16:17] op_sel:[0,1] op_sel_hi:[1,1]
	v_add_f32_e32 v4, v4, v5
	ds_read_b128 v[80:83], v88 offset:16896
	v_pk_mul_f32 v[10:11], v[46:47], v[16:17] op_sel:[0,1] op_sel_hi:[1,1]
	v_add_f32_dpp v4, v4, v4 quad_perm:[1,0,3,2] row_mask:0xf bank_mask:0xf bound_ctrl:1
	ds_read_b128 v[96:99], v88 offset:17664
	v_pk_fma_f32 v[8:9], v[0:1], v[40:41], v[8:9]
	v_add_f32_dpp v4, v4, v4 quad_perm:[2,3,0,1] row_mask:0xf bank_mask:0xf bound_ctrl:1
	v_pk_fma_f32 v[10:11], v[2:3], v[42:43], v[10:11]
	s_nop 0
	v_add_f32_dpp v4, v4, v4 row_ror:4 row_mask:0xf bank_mask:0xf bound_ctrl:1
	ds_read_b128 v[100:103], v88 offset:17920
	s_nop 0
	v_add_f32_dpp v4, v4, v4 row_ror:8 row_mask:0xf bank_mask:0xf bound_ctrl:1
	v_pk_fma_f32 v[0:1], v[4:5], v[52:53], v[8:9] op_sel_hi:[0,1,1]
	v_pk_fma_f32 v[2:3], v[4:5], v[54:55], v[10:11] op_sel_hi:[0,1,1]
	v_pk_mul_f32 v[6:7], v[0:1], v[56:57]
	v_pk_fma_f32 v[6:7], v[2:3], v[58:59], v[6:7]
	v_add_f32_e32 v191, v6, v7
	s_cmp_eq_u32 s28, 0
	s_cbranch_scc1 .Lls0_noy
	global_store_short v145, v214, s[22:23]
	v_add_u32_e32 v145, s26, v145
.Lls0_noy:
	v_and_b32_e32 v177, 0xffff0000, v154
	v_lshlrev_b32_e32 v178, 16, v155
	s_waitcnt lgkmcnt(6)
	v_pk_mul_f32 v[4:5], v[0:1], v[68:69] neg_lo:[0,1] neg_hi:[0,1]
	ds_read_b128 v[28:31], v88 offset:18944
	v_pk_fma_f32 v[4:5], v[2:3], v[70:71], v[4:5] neg_lo:[0,1,0] neg_hi:[0,1,0]
	ds_read_b128 v[24:27], v88 offset:18688
	v_pk_mul_f32 v[8:9], v[64:65], v[18:19] op_sel_hi:[1,0]
	v_add_f32_e32 v4, v4, v5
	ds_read_b128 v[20:23], v88 offset:18432
	v_pk_mul_f32 v[10:11], v[66:67], v[18:19] op_sel_hi:[1,0]
	v_add_f32_dpp v4, v4, v4 quad_perm:[1,0,3,2] row_mask:0xf bank_mask:0xf bound_ctrl:1
	ds_read_b128 v[32:35], v88 offset:19200
	v_pk_fma_f32 v[8:9], v[0:1], v[60:61], v[8:9]
	v_add_f32_dpp v4, v4, v4 quad_perm:[2,3,0,1] row_mask:0xf bank_mask:0xf bound_ctrl:1
	v_pk_fma_f32 v[10:11], v[2:3], v[62:63], v[10:11]
	s_nop 0
	v_add_f32_dpp v4, v4, v4 row_ror:4 row_mask:0xf bank_mask:0xf bound_ctrl:1
	ds_read_b128 v[36:39], v88 offset:19456
	s_nop 0
	v_add_f32_dpp v4, v4, v4 row_ror:8 row_mask:0xf bank_mask:0xf bound_ctrl:1
	v_pk_fma_f32 v[0:1], v[4:5], v[72:73], v[8:9] op_sel_hi:[0,1,1]
	v_pk_fma_f32 v[2:3], v[4:5], v[74:75], v[10:11] op_sel_hi:[0,1,1]
	v_pk_mul_f32 v[6:7], v[0:1], v[76:77]
	v_pk_fma_f32 v[6:7], v[2:3], v[78:79], v[6:7]
	v_add_f32_e32 v192, v6, v7
	ds_read2st64_b32 v[16:17], v90 offset0:77 offset1:83
	v_and_b32_e32 v179, 0xffff0000, v155
	ds_write_b128 v91, v[176:179] offset:25088
	s_waitcnt lgkmcnt(7)
	v_pk_mul_f32 v[4:5], v[0:1], v[92:93] neg_lo:[0,1] neg_hi:[0,1]
	ds_read_b128 v[48:51], v88 offset:20480
	v_pk_fma_f32 v[4:5], v[2:3], v[94:95], v[4:5] neg_lo:[0,1,0] neg_hi:[0,1,0]
	ds_read_b128 v[44:47], v88 offset:20224
	v_pk_mul_f32 v[8:9], v[84:85], v[18:19] op_sel:[0,1] op_sel_hi:[1,1]
	v_add_f32_e32 v4, v4, v5
	ds_read_b128 v[40:43], v88 offset:19968
	v_pk_mul_f32 v[10:11], v[86:87], v[18:19] op_sel:[0,1] op_sel_hi:[1,1]
	v_add_f32_dpp v4, v4, v4 quad_perm:[1,0,3,2] row_mask:0xf bank_mask:0xf bound_ctrl:1
	ds_read_b128 v[52:55], v88 offset:20736
	v_pk_fma_f32 v[8:9], v[0:1], v[80:81], v[8:9]
	v_add_f32_dpp v4, v4, v4 quad_perm:[2,3,0,1] row_mask:0xf bank_mask:0xf bound_ctrl:1
	v_pk_fma_f32 v[10:11], v[2:3], v[82:83], v[10:11]
	s_nop 0
	v_add_f32_dpp v4, v4, v4 row_ror:4 row_mask:0xf bank_mask:0xf bound_ctrl:1
	ds_read_b128 v[56:59], v88 offset:20992
	s_nop 0
	v_add_f32_dpp v4, v4, v4 row_ror:8 row_mask:0xf bank_mask:0xf bound_ctrl:1
	v_pk_fma_f32 v[0:1], v[4:5], v[96:97], v[8:9] op_sel_hi:[0,1,1]
	v_pk_fma_f32 v[2:3], v[4:5], v[98:99], v[10:11] op_sel_hi:[0,1,1]
	v_pk_mul_f32 v[6:7], v[0:1], v[100:101]
	v_pk_fma_f32 v[6:7], v[2:3], v[102:103], v[6:7]
	v_add_f32_e32 v193, v6, v7
	v_lshlrev_b32_e32 v176, 16, v156
	v_and_b32_e32 v177, 0xffff0000, v156
	s_waitcnt lgkmcnt(6)
	v_pk_mul_f32 v[4:5], v[0:1], v[28:29] neg_lo:[0,1] neg_hi:[0,1]
	ds_read_b128 v[68:71], v88 offset:22016
	v_pk_fma_f32 v[4:5], v[2:3], v[30:31], v[4:5] neg_lo:[0,1,0] neg_hi:[0,1,0]
	ds_read_b128 v[64:67], v88 offset:21760
	v_pk_mul_f32 v[8:9], v[24:25], v[16:17] op_sel_hi:[1,0]
	v_add_f32_e32 v4, v4, v5
	ds_read_b128 v[60:63], v88 offset:21504
	v_pk_mul_f32 v[10:11], v[26:27], v[16:17] op_sel_hi:[1,0]
	v_add_f32_dpp v4, v4, v4 quad_perm:[1,0,3,2] row_mask:0xf bank_mask:0xf bound_ctrl:1
	ds_read_b128 v[72:75], v88 offset:22272
	v_pk_fma_f32 v[8:9], v[0:1], v[20:21], v[8:9]
	v_add_f32_dpp v4, v4, v4 quad_perm:[2,3,0,1] row_mask:0xf bank_mask:0xf bound_ctrl:1
	v_pk_fma_f32 v[10:11], v[2:3], v[22:23], v[10:11]
	s_nop 0
	v_add_f32_dpp v4, v4, v4 row_ror:4 row_mask:0xf bank_mask:0xf bound_ctrl:1
	ds_read_b128 v[76:79], v88 offset:22528
	s_nop 0
	v_add_f32_dpp v4, v4, v4 row_ror:8 row_mask:0xf bank_mask:0xf bound_ctrl:1
	v_pk_fma_f32 v[0:1], v[4:5], v[32:33], v[8:9] op_sel_hi:[0,1,1]
	v_pk_fma_f32 v[2:3], v[4:5], v[34:35], v[10:11] op_sel_hi:[0,1,1]
	v_pk_mul_f32 v[6:7], v[0:1], v[36:37]
	v_pk_fma_f32 v[6:7], v[2:3], v[38:39], v[6:7]
	v_add_f32_e32 v194, v6, v7
	ds_read2st64_b32 v[18:19], v90 offset0:89 offset1:95
	v_lshlrev_b32_e32 v178, 16, v157
	v_and_b32_e32 v179, 0xffff0000, v157
	ds_write_b128 v91, v[176:179] offset:25344
	s_waitcnt lgkmcnt(7)
	v_pk_mul_f32 v[4:5], v[0:1], v[48:49] neg_lo:[0,1] neg_hi:[0,1]
	ds_read_b128 v[92:95], v88 offset:23552
	v_pk_fma_f32 v[4:5], v[2:3], v[50:51], v[4:5] neg_lo:[0,1,0] neg_hi:[0,1,0]
	ds_read_b128 v[84:87], v88 offset:23296
	v_pk_mul_f32 v[8:9], v[44:45], v[16:17] op_sel:[0,1] op_sel_hi:[1,1]
	v_add_f32_e32 v4, v4, v5
	ds_read_b128 v[80:83], v88 offset:23040
	v_pk_mul_f32 v[10:11], v[46:47], v[16:17] op_sel:[0,1] op_sel_hi:[1,1]
	v_add_f32_dpp v4, v4, v4 quad_perm:[1,0,3,2] row_mask:0xf bank_mask:0xf bound_ctrl:1
	ds_read_b128 v[96:99], v88 offset:23808
	v_pk_fma_f32 v[8:9], v[0:1], v[40:41], v[8:9]
	v_add_f32_dpp v4, v4, v4 quad_perm:[2,3,0,1] row_mask:0xf bank_mask:0xf bound_ctrl:1
	v_pk_fma_f32 v[10:11], v[2:3], v[42:43], v[10:11]
	s_nop 0
	v_add_f32_dpp v4, v4, v4 row_ror:4 row_mask:0xf bank_mask:0xf bound_ctrl:1
	ds_read_b128 v[100:103], v88 offset:24064
	s_nop 0
	v_add_f32_dpp v4, v4, v4 row_ror:8 row_mask:0xf bank_mask:0xf bound_ctrl:1
	v_pk_fma_f32 v[0:1], v[4:5], v[52:53], v[8:9] op_sel_hi:[0,1,1]
	v_pk_fma_f32 v[2:3], v[4:5], v[54:55], v[10:11] op_sel_hi:[0,1,1]
	v_pk_mul_f32 v[6:7], v[0:1], v[56:57]
	v_pk_fma_f32 v[6:7], v[2:3], v[58:59], v[6:7]
	v_add_f32_e32 v195, v6, v7
	s_waitcnt lgkmcnt(0)
	s_barrier
	v_pk_mul_f32 v[4:5], v[0:1], v[68:69] neg_lo:[0,1] neg_hi:[0,1]
	ds_read_b128 v[28:31], v88 offset:25088
	v_pk_fma_f32 v[4:5], v[2:3], v[70:71], v[4:5] neg_lo:[0,1,0] neg_hi:[0,1,0]
	ds_read_b128 v[24:27], v88 offset:24832
	v_pk_mul_f32 v[8:9], v[64:65], v[18:19] op_sel_hi:[1,0]
	v_add_f32_e32 v4, v4, v5
	ds_read_b128 v[20:23], v88 offset:24576
	v_pk_mul_f32 v[10:11], v[66:67], v[18:19] op_sel_hi:[1,0]
	v_add_f32_dpp v4, v4, v4 quad_perm:[1,0,3,2] row_mask:0xf bank_mask:0xf bound_ctrl:1
	ds_read_b128 v[32:35], v88 offset:25344
	v_pk_fma_f32 v[8:9], v[0:1], v[60:61], v[8:9]
	v_add_f32_dpp v4, v4, v4 quad_perm:[2,3,0,1] row_mask:0xf bank_mask:0xf bound_ctrl:1
	v_pk_fma_f32 v[10:11], v[2:3], v[62:63], v[10:11]
	s_nop 0
	v_add_f32_dpp v4, v4, v4 row_ror:4 row_mask:0xf bank_mask:0xf bound_ctrl:1
	ds_read_b128 v[36:39], v88 offset:25600
	s_nop 0
	v_add_f32_dpp v4, v4, v4 row_ror:8 row_mask:0xf bank_mask:0xf bound_ctrl:1
	v_pk_fma_f32 v[0:1], v[4:5], v[72:73], v[8:9] op_sel_hi:[0,1,1]
	v_pk_fma_f32 v[2:3], v[4:5], v[74:75], v[10:11] op_sel_hi:[0,1,1]
	v_pk_mul_f32 v[6:7], v[0:1], v[76:77]
	v_pk_fma_f32 v[6:7], v[2:3], v[78:79], v[6:7]
	v_add_f32_e32 v196, v6, v7
	ds_read2st64_b32 v[16:17], v90 offset0:101 offset1:107
	s_waitcnt lgkmcnt(6)
	v_pk_mul_f32 v[4:5], v[0:1], v[92:93] neg_lo:[0,1] neg_hi:[0,1]
	ds_read_b128 v[48:51], v88 offset:26624
	v_pk_fma_f32 v[4:5], v[2:3], v[94:95], v[4:5] neg_lo:[0,1,0] neg_hi:[0,1,0]
	ds_read_b128 v[44:47], v88 offset:26368
	v_pk_mul_f32 v[8:9], v[84:85], v[18:19] op_sel:[0,1] op_sel_hi:[1,1]
	v_add_f32_e32 v4, v4, v5
	ds_read_b128 v[40:43], v88 offset:26112
	v_pk_mul_f32 v[10:11], v[86:87], v[18:19] op_sel:[0,1] op_sel_hi:[1,1]
	v_add_f32_dpp v4, v4, v4 quad_perm:[1,0,3,2] row_mask:0xf bank_mask:0xf bound_ctrl:1
	ds_read_b128 v[52:55], v88 offset:26880
	v_pk_fma_f32 v[8:9], v[0:1], v[80:81], v[8:9]
	v_add_f32_dpp v4, v4, v4 quad_perm:[2,3,0,1] row_mask:0xf bank_mask:0xf bound_ctrl:1
	v_pk_fma_f32 v[10:11], v[2:3], v[82:83], v[10:11]
	s_nop 0
	v_add_f32_dpp v4, v4, v4 row_ror:4 row_mask:0xf bank_mask:0xf bound_ctrl:1
	ds_read_b128 v[56:59], v88 offset:27136
	s_nop 0
	v_add_f32_dpp v4, v4, v4 row_ror:8 row_mask:0xf bank_mask:0xf bound_ctrl:1
	v_pk_fma_f32 v[0:1], v[4:5], v[96:97], v[8:9] op_sel_hi:[0,1,1]
	v_pk_fma_f32 v[2:3], v[4:5], v[98:99], v[10:11] op_sel_hi:[0,1,1]
	v_pk_mul_f32 v[6:7], v[0:1], v[100:101]
	v_pk_fma_f32 v[6:7], v[2:3], v[102:103], v[6:7]
	v_add_f32_e32 v197, v6, v7
	s_waitcnt lgkmcnt(5)
	v_pk_mul_f32 v[4:5], v[0:1], v[28:29] neg_lo:[0,1] neg_hi:[0,1]
	ds_read_b128 v[68:71], v88 offset:28160
	v_pk_fma_f32 v[4:5], v[2:3], v[30:31], v[4:5] neg_lo:[0,1,0] neg_hi:[0,1,0]
	ds_read_b128 v[64:67], v88 offset:27904
	v_pk_mul_f32 v[8:9], v[24:25], v[16:17] op_sel_hi:[1,0]
	v_add_f32_e32 v4, v4, v5
	ds_read_b128 v[60:63], v88 offset:27648
	v_pk_mul_f32 v[10:11], v[26:27], v[16:17] op_sel_hi:[1,0]
	v_add_f32_dpp v4, v4, v4 quad_perm:[1,0,3,2] row_mask:0xf bank_mask:0xf bound_ctrl:1
	ds_read_b128 v[72:75], v88 offset:28416
	v_pk_fma_f32 v[8:9], v[0:1], v[20:21], v[8:9]
	v_add_f32_dpp v4, v4, v4 quad_perm:[2,3,0,1] row_mask:0xf bank_mask:0xf bound_ctrl:1
	v_pk_fma_f32 v[10:11], v[2:3], v[22:23], v[10:11]
	v_add_f32_dpp v182, v182, v182 row_ror:8 row_mask:0xf bank_mask:0x3 bound_ctrl:1
	v_add_f32_dpp v4, v4, v4 row_ror:4 row_mask:0xf bank_mask:0xf bound_ctrl:1
	ds_read_b128 v[76:79], v88 offset:28672
	v_add_f32_dpp v182, v190, v190 row_ror:8 row_mask:0xf bank_mask:0xc bound_ctrl:1
	v_add_f32_dpp v4, v4, v4 row_ror:8 row_mask:0xf bank_mask:0xf bound_ctrl:1
	v_pk_fma_f32 v[0:1], v[4:5], v[32:33], v[8:9] op_sel_hi:[0,1,1]
	v_pk_fma_f32 v[2:3], v[4:5], v[34:35], v[10:11] op_sel_hi:[0,1,1]
	v_pk_mul_f32 v[6:7], v[0:1], v[36:37]
	v_pk_fma_f32 v[6:7], v[2:3], v[38:39], v[6:7]
	v_add_f32_e32 v198, v6, v7
	ds_read2st64_b32 v[18:19], v90 offset0:113 offset1:119
	s_cmp_lt_u32 s28, 15
	s_cbranch_scc0 .Lls0_skip1
	global_load_dwordx4 v[112:115], v174, s[12:13]
	global_load_dwordx2 v[152:153], v175, s[14:15]
	global_load_dwordx2 v[154:155], v175, s[16:17]
	global_load_dwordx2 v[156:157], v175, s[18:19]
	global_load_dwordx4 v[116:119], v180, s[20:21]
	global_load_dword v171, v181, s[20:21]
	v_add_u32_e32 v174, s25, v174
	v_add_u32_e32 v175, s26, v175
	v_add_u32_e32 v180, s27, v180
	v_add_u32_e32 v181, s27, v181
.Lls0_back1:
	v_add_f32_dpp v183, v183, v183 row_ror:8 row_mask:0xf bank_mask:0x3 bound_ctrl:1
	v_add_f32_dpp v183, v191, v191 row_ror:8 row_mask:0xf bank_mask:0xc bound_ctrl:1
	s_waitcnt lgkmcnt(6)
	v_pk_mul_f32 v[4:5], v[0:1], v[48:49] neg_lo:[0,1] neg_hi:[0,1]
	ds_read_b128 v[92:95], v88 offset:29696
	v_pk_fma_f32 v[4:5], v[2:3], v[50:51], v[4:5] neg_lo:[0,1,0] neg_hi:[0,1,0]
	ds_read_b128 v[84:87], v88 offset:29440
	v_pk_mul_f32 v[8:9], v[44:45], v[16:17] op_sel:[0,1] op_sel_hi:[1,1]
	v_add_f32_e32 v4, v4, v5
	ds_read_b128 v[80:83], v88 offset:29184
	v_pk_mul_f32 v[10:11], v[46:47], v[16:17] op_sel:[0,1] op_sel_hi:[1,1]
	v_add_f32_dpp v4, v4, v4 quad_perm:[1,0,3,2] row_mask:0xf bank_mask:0xf bound_ctrl:1
	ds_read_b128 v[96:99], v88 offset:29952
	v_pk_fma_f32 v[8:9], v[0:1], v[40:41], v[8:9]
	v_add_f32_dpp v4, v4, v4 quad_perm:[2,3,0,1] row_mask:0xf bank_mask:0xf bound_ctrl:1
	v_pk_fma_f32 v[10:11], v[2:3], v[42:43], v[10:11]
	v_add_f32_dpp v184, v184, v184 row_ror:8 row_mask:0xf bank_mask:0x3 bound_ctrl:1
	v_add_f32_dpp v4, v4, v4 row_ror:4 row_mask:0xf bank_mask:0xf bound_ctrl:1
	ds_read_b128 v[100:103], v88 offset:30208
	v_add_f32_dpp v184, v192, v192 row_ror:8 row_mask:0xf bank_mask:0xc bound_ctrl:1
	v_add_f32_dpp v4, v4, v4 row_ror:8 row_mask:0xf bank_mask:0xf bound_ctrl:1
	v_pk_fma_f32 v[0:1], v[4:5], v[52:53], v[8:9] op_sel_hi:[0,1,1]
	v_pk_fma_f32 v[2:3], v[4:5], v[54:55], v[10:11] op_sel_hi:[0,1,1]
	v_pk_mul_f32 v[6:7], v[0:1], v[56:57]
	v_pk_fma_f32 v[6:7], v[2:3], v[58:59], v[6:7]
	v_add_f32_e32 v199, v6, v7
	v_add_f32_dpp v185, v185, v185 row_ror:8 row_mask:0xf bank_mask:0x3 bound_ctrl:1
	v_add_f32_dpp v185, v193, v193 row_ror:8 row_mask:0xf bank_mask:0xc bound_ctrl:1
	s_waitcnt lgkmcnt(5)
	v_pk_mul_f32 v[4:5], v[0:1], v[68:69] neg_lo:[0,1] neg_hi:[0,1]
	ds_read_b128 v[28:31], v88 offset:31232
	v_pk_fma_f32 v[4:5], v[2:3], v[70:71], v[4:5] neg_lo:[0,1,0] neg_hi:[0,1,0]
	ds_read_b128 v[24:27], v88 offset:30976
	v_pk_mul_f32 v[8:9], v[64:65], v[18:19] op_sel_hi:[1,0]
	v_add_f32_e32 v4, v4, v5
	ds_read_b128 v[20:23], v88 offset:30720
	v_pk_mul_f32 v[10:11], v[66:67], v[18:19] op_sel_hi:[1,0]
	v_add_f32_dpp v4, v4, v4 quad_perm:[1,0,3,2] row_mask:0xf bank_mask:0xf bound_ctrl:1
	ds_read_b128 v[32:35], v88 offset:31488
	v_pk_fma_f32 v[8:9], v[0:1], v[60:61], v[8:9]
	v_add_f32_dpp v4, v4, v4 quad_perm:[2,3,0,1] row_mask:0xf bank_mask:0xf bound_ctrl:1
	v_pk_fma_f32 v[10:11], v[2:3], v[62:63], v[10:11]
	v_add_f32_dpp v186, v186, v186 row_ror:8 row_mask:0xf bank_mask:0x3 bound_ctrl:1
	v_add_f32_dpp v4, v4, v4 row_ror:4 row_mask:0xf bank_mask:0xf bound_ctrl:1
	ds_read_b128 v[36:39], v88 offset:31744
	v_add_f32_dpp v186, v194, v194 row_ror:8 row_mask:0xf bank_mask:0xc bound_ctrl:1
	v_add_f32_dpp v4, v4, v4 row_ror:8 row_mask:0xf bank_mask:0xf bound_ctrl:1
	v_pk_fma_f32 v[0:1], v[4:5], v[72:73], v[8:9] op_sel_hi:[0,1,1]
	v_pk_fma_f32 v[2:3], v[4:5], v[74:75], v[10:11] op_sel_hi:[0,1,1]
	v_pk_mul_f32 v[6:7], v[0:1], v[76:77]
	v_pk_fma_f32 v[6:7], v[2:3], v[78:79], v[6:7]
	v_add_f32_e32 v200, v6, v7
	ds_read2st64_b32 v[16:17], v90 offset0:125 offset1:131
	v_add_f32_dpp v187, v187, v187 row_ror:8 row_mask:0xf bank_mask:0x3 bound_ctrl:1
	v_add_f32_dpp v187, v195, v195 row_ror:8 row_mask:0xf bank_mask:0xc bound_ctrl:1
	s_waitcnt lgkmcnt(6)
	v_pk_mul_f32 v[4:5], v[0:1], v[92:93] neg_lo:[0,1] neg_hi:[0,1]
	ds_read_b128 v[48:51], v88 offset:32768
	v_pk_fma_f32 v[4:5], v[2:3], v[94:95], v[4:5] neg_lo:[0,1,0] neg_hi:[0,1,0]
	ds_read_b128 v[44:47], v88 offset:32512
	v_pk_mul_f32 v[8:9], v[84:85], v[18:19] op_sel:[0,1] op_sel_hi:[1,1]
	v_add_f32_e32 v4, v4, v5
	ds_read_b128 v[40:43], v88 offset:32256
	v_pk_mul_f32 v[10:11], v[86:87], v[18:19] op_sel:[0,1] op_sel_hi:[1,1]
	v_add_f32_dpp v4, v4, v4 quad_perm:[1,0,3,2] row_mask:0xf bank_mask:0xf bound_ctrl:1
	ds_read_b128 v[52:55], v88 offset:33024
	v_pk_fma_f32 v[8:9], v[0:1], v[80:81], v[8:9]
	v_add_f32_dpp v4, v4, v4 quad_perm:[2,3,0,1] row_mask:0xf bank_mask:0xf bound_ctrl:1
	v_pk_fma_f32 v[10:11], v[2:3], v[82:83], v[10:11]
	v_add_f32_dpp v188, v188, v188 row_ror:8 row_mask:0xf bank_mask:0x3 bound_ctrl:1
	v_add_f32_dpp v4, v4, v4 row_ror:4 row_mask:0xf bank_mask:0xf bound_ctrl:1
	ds_read_b128 v[56:59], v88 offset:33280
	v_add_f32_dpp v188, v196, v196 row_ror:8 row_mask:0xf bank_mask:0xc bound_ctrl:1
	v_add_f32_dpp v4, v4, v4 row_ror:8 row_mask:0xf bank_mask:0xf bound_ctrl:1
	v_pk_fma_f32 v[0:1], v[4:5], v[96:97], v[8:9] op_sel_hi:[0,1,1]
	v_pk_fma_f32 v[2:3], v[4:5], v[98:99], v[10:11] op_sel_hi:[0,1,1]
	v_pk_mul_f32 v[6:7], v[0:1], v[100:101]
	v_pk_fma_f32 v[6:7], v[2:3], v[102:103], v[6:7]
	v_add_f32_e32 v201, v6, v7
	v_add_f32_dpp v189, v189, v189 row_ror:8 row_mask:0xf bank_mask:0x3 bound_ctrl:1
	v_add_f32_dpp v189, v197, v197 row_ror:8 row_mask:0xf bank_mask:0xc bound_ctrl:1
	s_waitcnt lgkmcnt(5)
	v_pk_mul_f32 v[4:5], v[0:1], v[28:29] neg_lo:[0,1] neg_hi:[0,1]
	ds_read_b128 v[68:71], v88 offset:34304
	v_pk_fma_f32 v[4:5], v[2:3], v[30:31], v[4:5] neg_lo:[0,1,0] neg_hi:[0,1,0]
	ds_read_b128 v[64:67], v88 offset:34048
	v_pk_mul_f32 v[8:9], v[24:25], v[16:17] op_sel_hi:[1,0]
	v_add_f32_e32 v4, v4, v5
	ds_read_b128 v[60:63], v88 offset:33792
	v_pk_mul_f32 v[10:11], v[26:27], v[16:17] op_sel_hi:[1,0]
	v_add_f32_dpp v4, v4, v4 quad_perm:[1,0,3,2] row_mask:0xf bank_mask:0xf bound_ctrl:1
	ds_read_b128 v[72:75], v88 offset:34560
	v_pk_fma_f32 v[8:9], v[0:1], v[20:21], v[8:9]
	v_add_f32_dpp v4, v4, v4 quad_perm:[2,3,0,1] row_mask:0xf bank_mask:0xf bound_ctrl:1
	v_pk_fma_f32 v[10:11], v[2:3], v[22:23], v[10:11]
	v_add_f32_dpp v182, v182, v182 row_shl:4 row_mask:0xf bank_mask:0x5 bound_ctrl:1
	v_add_f32_dpp v4, v4, v4 row_ror:4 row_mask:0xf bank_mask:0xf bound_ctrl:1
	ds_read_b128 v[76:79], v88 offset:34816
	v_add_f32_dpp v182, v186, v186 row_shr:4 row_mask:0xf bank_mask:0xa bound_ctrl:1
	v_add_f32_dpp v4, v4, v4 row_ror:8 row_mask:0xf bank_mask:0xf bound_ctrl:1
	v_pk_fma_f32 v[0:1], v[4:5], v[32:33], v[8:9] op_sel_hi:[0,1,1]
	v_pk_fma_f32 v[2:3], v[4:5], v[34:35], v[10:11] op_sel_hi:[0,1,1]
	v_pk_mul_f32 v[6:7], v[0:1], v[36:37]
	v_pk_fma_f32 v[6:7], v[2:3], v[38:39], v[6:7]
	v_add_f32_e32 v202, v6, v7
	ds_read2st64_b32 v[18:19], v90 offset0:137 offset1:143
	v_add_f32_dpp v183, v183, v183 row_shl:4 row_mask:0xf bank_mask:0x5 bound_ctrl:1
	v_add_f32_dpp v183, v187, v187 row_shr:4 row_mask:0xf bank_mask:0xa bound_ctrl:1
	s_waitcnt vmcnt(18)
	ds_write_b128 v91, v[120:123] offset:0
	s_waitcnt lgkmcnt(7)
	v_pk_mul_f32 v[4:5], v[0:1], v[48:49] neg_lo:[0,1] neg_hi:[0,1]
	ds_read_b128 v[92:95], v88 offset:35840
	v_pk_fma_f32 v[4:5], v[2:3], v[50:51], v[4:5] neg_lo:[0,1,0] neg_hi:[0,1,0]
	ds_read_b128 v[84:87], v88 offset:35584
	v_pk_mul_f32 v[8:9], v[44:45], v[16:17] op_sel:[0,1] op_sel_hi:[1,1]
	v_add_f32_e32 v4, v4, v5
	ds_read_b128 v[80:83], v88 offset:35328
	v_pk_mul_f32 v[10:11], v[46:47], v[16:17] op_sel:[0,1] op_sel_hi:[1,1]
	v_add_f32_dpp v4, v4, v4 quad_perm:[1,0,3,2] row_mask:0xf bank_mask:0xf bound_ctrl:1
	ds_read_b128 v[96:99], v88 offset:36096
	v_pk_fma_f32 v[8:9], v[0:1], v[40:41], v[8:9]
	v_add_f32_dpp v4, v4, v4 quad_perm:[2,3,0,1] row_mask:0xf bank_mask:0xf bound_ctrl:1
	v_pk_fma_f32 v[10:11], v[2:3], v[42:43], v[10:11]
	v_add_f32_dpp v184, v184, v184 row_shl:4 row_mask:0xf bank_mask:0x5 bound_ctrl:1
	v_add_f32_dpp v4, v4, v4 row_ror:4 row_mask:0xf bank_mask:0xf bound_ctrl:1
	ds_read_b128 v[100:103], v88 offset:36352
	v_add_f32_dpp v184, v188, v188 row_shr:4 row_mask:0xf bank_mask:0xa bound_ctrl:1
	v_add_f32_dpp v4, v4, v4 row_ror:8 row_mask:0xf bank_mask:0xf bound_ctrl:1
	v_pk_fma_f32 v[0:1], v[4:5], v[52:53], v[8:9] op_sel_hi:[0,1,1]
	v_pk_fma_f32 v[2:3], v[4:5], v[54:55], v[10:11] op_sel_hi:[0,1,1]
	v_pk_mul_f32 v[6:7], v[0:1], v[56:57]
	v_pk_fma_f32 v[6:7], v[2:3], v[58:59], v[6:7]
	v_add_f32_e32 v203, v6, v7
	v_add_f32_dpp v185, v185, v185 row_shl:4 row_mask:0xf bank_mask:0x5 bound_ctrl:1
	v_add_f32_dpp v185, v189, v189 row_shr:4 row_mask:0xf bank_mask:0xa bound_ctrl:1
	ds_write_b128 v91, v[124:127] offset:1024
	ds_write_b32 v91, v172 offset:1280
	s_waitcnt lgkmcnt(8)
	v_pk_mul_f32 v[4:5], v[0:1], v[68:69] neg_lo:[0,1] neg_hi:[0,1]
	ds_read_b128 v[28:31], v88 offset:37376
	v_pk_fma_f32 v[4:5], v[2:3], v[70:71], v[4:5] neg_lo:[0,1,0] neg_hi:[0,1,0]
	ds_read_b128 v[24:27], v88 offset:37120
	v_pk_mul_f32 v[8:9], v[64:65], v[18:19] op_sel_hi:[1,0]
	v_add_f32_e32 v4, v4, v5
	ds_read_b128 v[20:23], v88 offset:36864
	v_pk_mul_f32 v[10:11], v[66:67], v[18:19] op_sel_hi:[1,0]
	v_add_f32_dpp v4, v4, v4 quad_perm:[1,0,3,2] row_mask:0xf bank_mask:0xf bound_ctrl:1
	ds_read_b128 v[32:35], v88 offset:37632
	v_pk_fma_f32 v[8:9], v[0:1], v[60:61], v[8:9]
	v_add_f32_dpp v4, v4, v4 quad_perm:[2,3,0,1] row_mask:0xf bank_mask:0xf bound_ctrl:1
	v_pk_fma_f32 v[10:11], v[2:3], v[62:63], v[10:11]
	v_add_f32_dpp v182, v182, v182 quad_perm:[1,0,3,2] row_mask:0xf bank_mask:0xf bound_ctrl:1
	v_add_f32_dpp v4, v4, v4 row_ror:4 row_mask:0xf bank_mask:0xf bound_ctrl:1
	ds_read_b128 v[36:39], v88 offset:37888
	v_add_f32_dpp v183, v183, v183 quad_perm:[1,0,3,2] row_mask:0xf bank_mask:0xf bound_ctrl:1
	v_add_f32_dpp v4, v4, v4 row_ror:8 row_mask:0xf bank_mask:0xf bound_ctrl:1
	v_pk_fma_f32 v[0:1], v[4:5], v[72:73], v[8:9] op_sel_hi:[0,1,1]
	v_pk_fma_f32 v[2:3], v[4:5], v[74:75], v[10:11] op_sel_hi:[0,1,1]
	v_pk_mul_f32 v[6:7], v[0:1], v[76:77]
	v_pk_fma_f32 v[6:7], v[2:3], v[78:79], v[6:7]
	v_add_f32_e32 v204, v6, v7
	ds_read2st64_b32 v[16:17], v90 offset0:149 offset1:155
	v_cndmask_b32_e64 v182, v182, v183, s[30:31]
	v_lshlrev_b32_e32 v176, 16, v158
	v_and_b32_e32 v177, 0xffff0000, v158
	s_waitcnt lgkmcnt(8)
	v_pk_mul_f32 v[4:5], v[0:1], v[92:93] neg_lo:[0,1] neg_hi:[0,1]
	ds_read_b128 v[48:51], v88 offset:38912
	v_pk_fma_f32 v[4:5], v[2:3], v[94:95], v[4:5] neg_lo:[0,1,0] neg_hi:[0,1,0]
	ds_read_b128 v[44:47], v88 offset:38656
	v_pk_mul_f32 v[8:9], v[84:85], v[18:19] op_sel:[0,1] op_sel_hi:[1,1]
	v_add_f32_e32 v4, v4, v5
	ds_read_b128 v[40:43], v88 offset:38400
	v_pk_mul_f32 v[10:11], v[86:87], v[18:19] op_sel:[0,1] op_sel_hi:[1,1]
	v_add_f32_dpp v4, v4, v4 quad_perm:[1,0,3,2] row_mask:0xf bank_mask:0xf bound_ctrl:1
	ds_read_b128 v[52:55], v88 offset:39168
	v_pk_fma_f32 v[8:9], v[0:1], v[80:81], v[8:9]
	v_add_f32_dpp v4, v4, v4 quad_perm:[2,3,0,1] row_mask:0xf bank_mask:0xf bound_ctrl:1
	v_pk_fma_f32 v[10:11], v[2:3], v[82:83], v[10:11]
	v_add_f32_dpp v184, v184, v184 quad_perm:[1,0,3,2] row_mask:0xf bank_mask:0xf bound_ctrl:1
	v_add_f32_dpp v4, v4, v4 row_ror:4 row_mask:0xf bank_mask:0xf bound_ctrl:1
	ds_read_b128 v[56:59], v88 offset:39424
	v_add_f32_dpp v185, v185, v185 quad_perm:[1,0,3,2] row_mask:0xf bank_mask:0xf bound_ctrl:1
	v_add_f32_dpp v4, v4, v4 row_ror:8 row_mask:0xf bank_mask:0xf bound_ctrl:1
	v_pk_fma_f32 v[0:1], v[4:5], v[96:97], v[8:9] op_sel_hi:[0,1,1]
	v_pk_fma_f32 v[2:3], v[4:5], v[98:99], v[10:11] op_sel_hi:[0,1,1]
	v_pk_mul_f32 v[6:7], v[0:1], v[100:101]
	v_pk_fma_f32 v[6:7], v[2:3], v[102:103], v[6:7]
	v_add_f32_e32 v205, v6, v7
	v_cndmask_b32_e64 v184, v184, v185, s[30:31]
	v_lshlrev_b32_e32 v178, 16, v159
	v_and_b32_e32 v179, 0xffff0000, v159
	s_waitcnt lgkmcnt(5)
	v_pk_mul_f32 v[4:5], v[0:1], v[28:29] neg_lo:[0,1] neg_hi:[0,1]
	ds_read_b128 v[68:71], v88 offset:40448
	v_pk_fma_f32 v[4:5], v[2:3], v[30:31], v[4:5] neg_lo:[0,1,0] neg_hi:[0,1,0]
	ds_read_b128 v[64:67], v88 offset:40192
	v_pk_mul_f32 v[8:9], v[24:25], v[16:17] op_sel_hi:[1,0]
	v_add_f32_e32 v4, v4, v5
	ds_read_b128 v[60:63], v88 offset:39936
	v_pk_mul_f32 v[10:11], v[26:27], v[16:17] op_sel_hi:[1,0]
	v_add_f32_dpp v4, v4, v4 quad_perm:[1,0,3,2] row_mask:0xf bank_mask:0xf bound_ctrl:1
	ds_read_b128 v[72:75], v88 offset:40704
	v_pk_fma_f32 v[8:9], v[0:1], v[20:21], v[8:9]
	v_add_f32_dpp v4, v4, v4 quad_perm:[2,3,0,1] row_mask:0xf bank_mask:0xf bound_ctrl:1
	v_pk_fma_f32 v[10:11], v[2:3], v[22:23], v[10:11]
	v_add_f32_dpp v182, v182, v182 quad_perm:[2,3,0,1] row_mask:0xf bank_mask:0xf bound_ctrl:1
	v_add_f32_dpp v4, v4, v4 row_ror:4 row_mask:0xf bank_mask:0xf bound_ctrl:1
	ds_read_b128 v[76:79], v88 offset:40960
	v_add_f32_dpp v184, v184, v184 quad_perm:[2,3,0,1] row_mask:0xf bank_mask:0xf bound_ctrl:1
	v_add_f32_dpp v4, v4, v4 row_ror:8 row_mask:0xf bank_mask:0xf bound_ctrl:1
	v_pk_fma_f32 v[0:1], v[4:5], v[32:33], v[8:9] op_sel_hi:[0,1,1]
	v_pk_fma_f32 v[2:3], v[4:5], v[34:35], v[10:11] op_sel_hi:[0,1,1]
	v_pk_mul_f32 v[6:7], v[0:1], v[36:37]
	v_pk_fma_f32 v[6:7], v[2:3], v[38:39], v[6:7]
	v_add_f32_e32 v206, v6, v7
	ds_read2st64_b32 v[18:19], v90 offset0:161 offset1:167
	v_cndmask_b32_e64 v214, v182, v184, s[34:35]
	v_cvt_pk_bf16_f32 v214, v214, v214
	ds_write_b128 v91, v[176:179] offset:256
	v_lshlrev_b32_e32 v176, 16, v160
	s_waitcnt lgkmcnt(7)
	v_pk_mul_f32 v[4:5], v[0:1], v[48:49] neg_lo:[0,1] neg_hi:[0,1]
	ds_read_b128 v[92:95], v88 offset:41984
	v_pk_fma_f32 v[4:5], v[2:3], v[50:51], v[4:5] neg_lo:[0,1,0] neg_hi:[0,1,0]
	ds_read_b128 v[84:87], v88 offset:41728
	v_pk_mul_f32 v[8:9], v[44:45], v[16:17] op_sel:[0,1] op_sel_hi:[1,1]
	v_add_f32_e32 v4, v4, v5
	ds_read_b128 v[80:83], v88 offset:41472
	v_pk_mul_f32 v[10:11], v[46:47], v[16:17] op_sel:[0,1] op_sel_hi:[1,1]
	v_add_f32_dpp v4, v4, v4 quad_perm:[1,0,3,2] row_mask:0xf bank_mask:0xf bound_ctrl:1
	ds_read_b128 v[96:99], v88 offset:42240
	v_pk_fma_f32 v[8:9], v[0:1], v[40:41], v[8:9]
	v_add_f32_dpp v4, v4, v4 quad_perm:[2,3,0,1] row_mask:0xf bank_mask:0xf bound_ctrl:1
	v_pk_fma_f32 v[10:11], v[2:3], v[42:43], v[10:11]
	s_nop 0
	v_add_f32_dpp v4, v4, v4 row_ror:4 row_mask:0xf bank_mask:0xf bound_ctrl:1
	ds_read_b128 v[100:103], v88 offset:42496
	s_nop 0
	v_add_f32_dpp v4, v4, v4 row_ror:8 row_mask:0xf bank_mask:0xf bound_ctrl:1
	v_pk_fma_f32 v[0:1], v[4:5], v[52:53], v[8:9] op_sel_hi:[0,1,1]
	v_pk_fma_f32 v[2:3], v[4:5], v[54:55], v[10:11] op_sel_hi:[0,1,1]
	v_pk_mul_f32 v[6:7], v[0:1], v[56:57]
	v_pk_fma_f32 v[6:7], v[2:3], v[58:59], v[6:7]
	v_add_f32_e32 v207, v6, v7
	global_store_short v145, v214, s[22:23]
	v_add_u32_e32 v145, s26, v145
	v_and_b32_e32 v177, 0xffff0000, v160
	v_lshlrev_b32_e32 v178, 16, v161
	s_waitcnt lgkmcnt(6)
	v_pk_mul_f32 v[4:5], v[0:1], v[68:69] neg_lo:[0,1] neg_hi:[0,1]
	ds_read_b128 v[28:31], v88 offset:43520
	v_pk_fma_f32 v[4:5], v[2:3], v[70:71], v[4:5] neg_lo:[0,1,0] neg_hi:[0,1,0]
	ds_read_b128 v[24:27], v88 offset:43264
	v_pk_mul_f32 v[8:9], v[64:65], v[18:19] op_sel_hi:[1,0]
	v_add_f32_e32 v4, v4, v5
	ds_read_b128 v[20:23], v88 offset:43008
	v_pk_mul_f32 v[10:11], v[66:67], v[18:19] op_sel_hi:[1,0]
	v_add_f32_dpp v4, v4, v4 quad_perm:[1,0,3,2] row_mask:0xf bank_mask:0xf bound_ctrl:1
	ds_read_b128 v[32:35], v88 offset:43776
	v_pk_fma_f32 v[8:9], v[0:1], v[60:61], v[8:9]
	v_add_f32_dpp v4, v4, v4 quad_perm:[2,3,0,1] row_mask:0xf bank_mask:0xf bound_ctrl:1
	v_pk_fma_f32 v[10:11], v[2:3], v[62:63], v[10:11]
	s_nop 0
	v_add_f32_dpp v4, v4, v4 row_ror:4 row_mask:0xf bank_mask:0xf bound_ctrl:1
	ds_read_b128 v[36:39], v88 offset:44032
	s_nop 0
	v_add_f32_dpp v4, v4, v4 row_ror:8 row_mask:0xf bank_mask:0xf bound_ctrl:1
	v_pk_fma_f32 v[0:1], v[4:5], v[72:73], v[8:9] op_sel_hi:[0,1,1]
	v_pk_fma_f32 v[2:3], v[4:5], v[74:75], v[10:11] op_sel_hi:[0,1,1]
	v_pk_mul_f32 v[6:7], v[0:1], v[76:77]
	v_pk_fma_f32 v[6:7], v[2:3], v[78:79], v[6:7]
	v_add_f32_e32 v208, v6, v7
	ds_read2st64_b32 v[16:17], v90 offset0:173 offset1:179
	v_and_b32_e32 v179, 0xffff0000, v161
	ds_write_b128 v91, v[176:179] offset:512
	s_waitcnt lgkmcnt(7)
	v_pk_mul_f32 v[4:5], v[0:1], v[92:93] neg_lo:[0,1] neg_hi:[0,1]
	ds_read_b128 v[48:51], v88 offset:45056
	v_pk_fma_f32 v[4:5], v[2:3], v[94:95], v[4:5] neg_lo:[0,1,0] neg_hi:[0,1,0]
	ds_read_b128 v[44:47], v88 offset:44800
	v_pk_mul_f32 v[8:9], v[84:85], v[18:19] op_sel:[0,1] op_sel_hi:[1,1]
	v_add_f32_e32 v4, v4, v5
	ds_read_b128 v[40:43], v88 offset:44544
	v_pk_mul_f32 v[10:11], v[86:87], v[18:19] op_sel:[0,1] op_sel_hi:[1,1]
	v_add_f32_dpp v4, v4, v4 quad_perm:[1,0,3,2] row_mask:0xf bank_mask:0xf bound_ctrl:1
	ds_read_b128 v[52:55], v88 offset:45312
	v_pk_fma_f32 v[8:9], v[0:1], v[80:81], v[8:9]
	v_add_f32_dpp v4, v4, v4 quad_perm:[2,3,0,1] row_mask:0xf bank_mask:0xf bound_ctrl:1
	v_pk_fma_f32 v[10:11], v[2:3], v[82:83], v[10:11]
	s_nop 0
	v_add_f32_dpp v4, v4, v4 row_ror:4 row_mask:0xf bank_mask:0xf bound_ctrl:1
	ds_read_b128 v[56:59], v88 offset:45568
	s_nop 0
	v_add_f32_dpp v4, v4, v4 row_ror:8 row_mask:0xf bank_mask:0xf bound_ctrl:1
	v_pk_fma_f32 v[0:1], v[4:5], v[96:97], v[8:9] op_sel_hi:[0,1,1]
	v_pk_fma_f32 v[2:3], v[4:5], v[98:99], v[10:11] op_sel_hi:[0,1,1]
	v_pk_mul_f32 v[6:7], v[0:1], v[100:101]
	v_pk_fma_f32 v[6:7], v[2:3], v[102:103], v[6:7]
	v_add_f32_e32 v209, v6, v7
	v_lshlrev_b32_e32 v176, 16, v162
	v_and_b32_e32 v177, 0xffff0000, v162
	s_waitcnt lgkmcnt(6)
	v_pk_mul_f32 v[4:5], v[0:1], v[28:29] neg_lo:[0,1] neg_hi:[0,1]
	ds_read_b128 v[68:71], v88 offset:46592
	v_pk_fma_f32 v[4:5], v[2:3], v[30:31], v[4:5] neg_lo:[0,1,0] neg_hi:[0,1,0]
	ds_read_b128 v[64:67], v88 offset:46336
	v_pk_mul_f32 v[8:9], v[24:25], v[16:17] op_sel_hi:[1,0]
	v_add_f32_e32 v4, v4, v5
	ds_read_b128 v[60:63], v88 offset:46080
	v_pk_mul_f32 v[10:11], v[26:27], v[16:17] op_sel_hi:[1,0]
	v_add_f32_dpp v4, v4, v4 quad_perm:[1,0,3,2] row_mask:0xf bank_mask:0xf bound_ctrl:1
	ds_read_b128 v[72:75], v88 offset:46848
	v_pk_fma_f32 v[8:9], v[0:1], v[20:21], v[8:9]
	v_add_f32_dpp v4, v4, v4 quad_perm:[2,3,0,1] row_mask:0xf bank_mask:0xf bound_ctrl:1
	v_pk_fma_f32 v[10:11], v[2:3], v[22:23], v[10:11]
	s_nop 0
	v_add_f32_dpp v4, v4, v4 row_ror:4 row_mask:0xf bank_mask:0xf bound_ctrl:1
	ds_read_b128 v[76:79], v88 offset:47104
	s_nop 0
	v_add_f32_dpp v4, v4, v4 row_ror:8 row_mask:0xf bank_mask:0xf bound_ctrl:1
	v_pk_fma_f32 v[0:1], v[4:5], v[32:33], v[8:9] op_sel_hi:[0,1,1]
	v_pk_fma_f32 v[2:3], v[4:5], v[34:35], v[10:11] op_sel_hi:[0,1,1]
	v_pk_mul_f32 v[6:7], v[0:1], v[36:37]
	v_pk_fma_f32 v[6:7], v[2:3], v[38:39], v[6:7]
	v_add_f32_e32 v210, v6, v7
	ds_read2st64_b32 v[18:19], v90 offset0:185 offset1:191
	v_lshlrev_b32_e32 v178, 16, v163
	v_and_b32_e32 v179, 0xffff0000, v163
	ds_write_b128 v91, v[176:179] offset:768
	s_waitcnt lgkmcnt(7)
	v_pk_mul_f32 v[4:5], v[0:1], v[48:49] neg_lo:[0,1] neg_hi:[0,1]
	ds_read_b128 v[92:95], v88 offset:48128
	v_pk_fma_f32 v[4:5], v[2:3], v[50:51], v[4:5] neg_lo:[0,1,0] neg_hi:[0,1,0]
	ds_read_b128 v[84:87], v88 offset:47872
	v_pk_mul_f32 v[8:9], v[44:45], v[16:17] op_sel:[0,1] op_sel_hi:[1,1]
	v_add_f32_e32 v4, v4, v5
	ds_read_b128 v[80:83], v88 offset:47616
	v_pk_mul_f32 v[10:11], v[46:47], v[16:17] op_sel:[0,1] op_sel_hi:[1,1]
	v_add_f32_dpp v4, v4, v4 quad_perm:[1,0,3,2] row_mask:0xf bank_mask:0xf bound_ctrl:1
	ds_read_b128 v[96:99], v88 offset:48384
	v_pk_fma_f32 v[8:9], v[0:1], v[40:41], v[8:9]
	v_add_f32_dpp v4, v4, v4 quad_perm:[2,3,0,1] row_mask:0xf bank_mask:0xf bound_ctrl:1
	v_pk_fma_f32 v[10:11], v[2:3], v[42:43], v[10:11]
	s_nop 0
	v_add_f32_dpp v4, v4, v4 row_ror:4 row_mask:0xf bank_mask:0xf bound_ctrl:1
	ds_read_b128 v[100:103], v88 offset:48640
	s_nop 0
	v_add_f32_dpp v4, v4, v4 row_ror:8 row_mask:0xf bank_mask:0xf bound_ctrl:1
	v_pk_fma_f32 v[0:1], v[4:5], v[52:53], v[8:9] op_sel_hi:[0,1,1]
	v_pk_fma_f32 v[2:3], v[4:5], v[54:55], v[10:11] op_sel_hi:[0,1,1]
	v_pk_mul_f32 v[6:7], v[0:1], v[56:57]
	v_pk_fma_f32 v[6:7], v[2:3], v[58:59], v[6:7]
	v_add_f32_e32 v211, v6, v7
	s_waitcnt lgkmcnt(0)
	s_barrier
	v_pk_mul_f32 v[4:5], v[0:1], v[68:69] neg_lo:[0,1] neg_hi:[0,1]
	ds_read_b128 v[28:31], v88 offset:512
	v_pk_fma_f32 v[4:5], v[2:3], v[70:71], v[4:5] neg_lo:[0,1,0] neg_hi:[0,1,0]
	ds_read_b128 v[24:27], v88 offset:256
	v_pk_mul_f32 v[8:9], v[64:65], v[18:19] op_sel_hi:[1,0]
	v_add_f32_e32 v4, v4, v5
	ds_read_b128 v[20:23], v88 offset:0
	v_pk_mul_f32 v[10:11], v[66:67], v[18:19] op_sel_hi:[1,0]
	v_add_f32_dpp v4, v4, v4 quad_perm:[1,0,3,2] row_mask:0xf bank_mask:0xf bound_ctrl:1
	ds_read_b128 v[32:35], v88 offset:768
	v_pk_fma_f32 v[8:9], v[0:1], v[60:61], v[8:9]
	v_add_f32_dpp v4, v4, v4 quad_perm:[2,3,0,1] row_mask:0xf bank_mask:0xf bound_ctrl:1
	v_pk_fma_f32 v[10:11], v[2:3], v[62:63], v[10:11]
	s_nop 0
	v_add_f32_dpp v4, v4, v4 row_ror:4 row_mask:0xf bank_mask:0xf bound_ctrl:1
	ds_read_b128 v[36:39], v88 offset:1024
	s_nop 0
	v_add_f32_dpp v4, v4, v4 row_ror:8 row_mask:0xf bank_mask:0xf bound_ctrl:1
	v_pk_fma_f32 v[0:1], v[4:5], v[72:73], v[8:9] op_sel_hi:[0,1,1]
	v_pk_fma_f32 v[2:3], v[4:5], v[74:75], v[10:11] op_sel_hi:[0,1,1]
	v_pk_mul_f32 v[6:7], v[0:1], v[76:77]
	v_pk_fma_f32 v[6:7], v[2:3], v[78:79], v[6:7]
	v_add_f32_e32 v212, v6, v7
	ds_read2st64_b32 v[16:17], v90 offset0:5 offset1:11
	s_waitcnt lgkmcnt(6)
	v_pk_mul_f32 v[4:5], v[0:1], v[92:93] neg_lo:[0,1] neg_hi:[0,1]
	ds_read_b128 v[48:51], v88 offset:2048
	v_pk_fma_f32 v[4:5], v[2:3], v[94:95], v[4:5] neg_lo:[0,1,0] neg_hi:[0,1,0]
	ds_read_b128 v[44:47], v88 offset:1792
	v_pk_mul_f32 v[8:9], v[84:85], v[18:19] op_sel:[0,1] op_sel_hi:[1,1]
	v_add_f32_e32 v4, v4, v5
	ds_read_b128 v[40:43], v88 offset:1536
	v_pk_mul_f32 v[10:11], v[86:87], v[18:19] op_sel:[0,1] op_sel_hi:[1,1]
	v_add_f32_dpp v4, v4, v4 quad_perm:[1,0,3,2] row_mask:0xf bank_mask:0xf bound_ctrl:1
	ds_read_b128 v[52:55], v88 offset:2304
	v_pk_fma_f32 v[8:9], v[0:1], v[80:81], v[8:9]
	v_add_f32_dpp v4, v4, v4 quad_perm:[2,3,0,1] row_mask:0xf bank_mask:0xf bound_ctrl:1
	v_pk_fma_f32 v[10:11], v[2:3], v[82:83], v[10:11]
	s_nop 0
	v_add_f32_dpp v4, v4, v4 row_ror:4 row_mask:0xf bank_mask:0xf bound_ctrl:1
	ds_read_b128 v[56:59], v88 offset:2560
	s_nop 0
	v_add_f32_dpp v4, v4, v4 row_ror:8 row_mask:0xf bank_mask:0xf bound_ctrl:1
	v_pk_fma_f32 v[0:1], v[4:5], v[96:97], v[8:9] op_sel_hi:[0,1,1]
	v_pk_fma_f32 v[2:3], v[4:5], v[98:99], v[10:11] op_sel_hi:[0,1,1]
	v_pk_mul_f32 v[6:7], v[0:1], v[100:101]
	v_pk_fma_f32 v[6:7], v[2:3], v[102:103], v[6:7]
	v_add_f32_e32 v213, v6, v7
	s_waitcnt lgkmcnt(5)
	v_pk_mul_f32 v[4:5], v[0:1], v[28:29] neg_lo:[0,1] neg_hi:[0,1]
	ds_read_b128 v[68:71], v88 offset:3584
	v_pk_fma_f32 v[4:5], v[2:3], v[30:31], v[4:5] neg_lo:[0,1,0] neg_hi:[0,1,0]
	ds_read_b128 v[64:67], v88 offset:3328
	v_pk_mul_f32 v[8:9], v[24:25], v[16:17] op_sel_hi:[1,0]
	v_add_f32_e32 v4, v4, v5
	ds_read_b128 v[60:63], v88 offset:3072
	v_pk_mul_f32 v[10:11], v[26:27], v[16:17] op_sel_hi:[1,0]
	v_add_f32_dpp v4, v4, v4 quad_perm:[1,0,3,2] row_mask:0xf bank_mask:0xf bound_ctrl:1
	ds_read_b128 v[72:75], v88 offset:3840
	v_pk_fma_f32 v[8:9], v[0:1], v[20:21], v[8:9]
	v_add_f32_dpp v4, v4, v4 quad_perm:[2,3,0,1] row_mask:0xf bank_mask:0xf bound_ctrl:1
	v_pk_fma_f32 v[10:11], v[2:3], v[22:23], v[10:11]
	v_add_f32_dpp v198, v198, v198 row_ror:8 row_mask:0xf bank_mask:0x3 bound_ctrl:1
	v_add_f32_dpp v4, v4, v4 row_ror:4 row_mask:0xf bank_mask:0xf bound_ctrl:1
	ds_read_b128 v[76:79], v88 offset:4096
	v_add_f32_dpp v198, v206, v206 row_ror:8 row_mask:0xf bank_mask:0xc bound_ctrl:1
	v_add_f32_dpp v4, v4, v4 row_ror:8 row_mask:0xf bank_mask:0xf bound_ctrl:1
	v_pk_fma_f32 v[0:1], v[4:5], v[32:33], v[8:9] op_sel_hi:[0,1,1]
	v_pk_fma_f32 v[2:3], v[4:5], v[34:35], v[10:11] op_sel_hi:[0,1,1]
	v_pk_mul_f32 v[6:7], v[0:1], v[36:37]
	v_pk_fma_f32 v[6:7], v[2:3], v[38:39], v[6:7]
	v_add_f32_e32 v182, v6, v7
	ds_read2st64_b32 v[18:19], v90 offset0:17 offset1:23
	s_cmp_lt_u32 s28, 15
	s_cbranch_scc0 .Lls0_skip2
	global_load_dwordx4 v[120:123], v174, s[12:13]
	global_load_dwordx2 v[158:159], v175, s[14:15]
	global_load_dwordx2 v[160:161], v175, s[16:17]
	global_load_dwordx2 v[162:163], v175, s[18:19]
	global_load_dwordx4 v[124:127], v180, s[20:21]
	global_load_dword v172, v181, s[20:21]
	v_add_u32_e32 v174, s25, v174
	v_add_u32_e32 v175, s26, v175
	v_add_u32_e32 v180, s27, v180
	v_add_u32_e32 v181, s27, v181
.Lls0_back2:
	v_add_f32_dpp v199, v199, v199 row_ror:8 row_mask:0xf bank_mask:0x3 bound_ctrl:1
	v_add_f32_dpp v199, v207, v207 row_ror:8 row_mask:0xf bank_mask:0xc bound_ctrl:1
	s_waitcnt lgkmcnt(6)
	v_pk_mul_f32 v[4:5], v[0:1], v[48:49] neg_lo:[0,1] neg_hi:[0,1]
	ds_read_b128 v[92:95], v88 offset:5120
	v_pk_fma_f32 v[4:5], v[2:3], v[50:51], v[4:5] neg_lo:[0,1,0] neg_hi:[0,1,0]
	ds_read_b128 v[84:87], v88 offset:4864
	v_pk_mul_f32 v[8:9], v[44:45], v[16:17] op_sel:[0,1] op_sel_hi:[1,1]
	v_add_f32_e32 v4, v4, v5
	ds_read_b128 v[80:83], v88 offset:4608
	v_pk_mul_f32 v[10:11], v[46:47], v[16:17] op_sel:[0,1] op_sel_hi:[1,1]
	v_add_f32_dpp v4, v4, v4 quad_perm:[1,0,3,2] row_mask:0xf bank_mask:0xf bound_ctrl:1
	ds_read_b128 v[96:99], v88 offset:5376
	v_pk_fma_f32 v[8:9], v[0:1], v[40:41], v[8:9]
	v_add_f32_dpp v4, v4, v4 quad_perm:[2,3,0,1] row_mask:0xf bank_mask:0xf bound_ctrl:1
	v_pk_fma_f32 v[10:11], v[2:3], v[42:43], v[10:11]
	v_add_f32_dpp v200, v200, v200 row_ror:8 row_mask:0xf bank_mask:0x3 bound_ctrl:1
	v_add_f32_dpp v4, v4, v4 row_ror:4 row_mask:0xf bank_mask:0xf bound_ctrl:1
	ds_read_b128 v[100:103], v88 offset:5632
	v_add_f32_dpp v200, v208, v208 row_ror:8 row_mask:0xf bank_mask:0xc bound_ctrl:1
	v_add_f32_dpp v4, v4, v4 row_ror:8 row_mask:0xf bank_mask:0xf bound_ctrl:1
	v_pk_fma_f32 v[0:1], v[4:5], v[52:53], v[8:9] op_sel_hi:[0,1,1]
	v_pk_fma_f32 v[2:3], v[4:5], v[54:55], v[10:11] op_sel_hi:[0,1,1]
	v_pk_mul_f32 v[6:7], v[0:1], v[56:57]
	v_pk_fma_f32 v[6:7], v[2:3], v[58:59], v[6:7]
	v_add_f32_e32 v183, v6, v7
	v_add_f32_dpp v201, v201, v201 row_ror:8 row_mask:0xf bank_mask:0x3 bound_ctrl:1
	v_add_f32_dpp v201, v209, v209 row_ror:8 row_mask:0xf bank_mask:0xc bound_ctrl:1
	s_waitcnt lgkmcnt(5)
	v_pk_mul_f32 v[4:5], v[0:1], v[68:69] neg_lo:[0,1] neg_hi:[0,1]
	ds_read_b128 v[28:31], v88 offset:6656
	v_pk_fma_f32 v[4:5], v[2:3], v[70:71], v[4:5] neg_lo:[0,1,0] neg_hi:[0,1,0]
	ds_read_b128 v[24:27], v88 offset:6400
	v_pk_mul_f32 v[8:9], v[64:65], v[18:19] op_sel_hi:[1,0]
	v_add_f32_e32 v4, v4, v5
	ds_read_b128 v[20:23], v88 offset:6144
	v_pk_mul_f32 v[10:11], v[66:67], v[18:19] op_sel_hi:[1,0]
	v_add_f32_dpp v4, v4, v4 quad_perm:[1,0,3,2] row_mask:0xf bank_mask:0xf bound_ctrl:1
	ds_read_b128 v[32:35], v88 offset:6912
	v_pk_fma_f32 v[8:9], v[0:1], v[60:61], v[8:9]
	v_add_f32_dpp v4, v4, v4 quad_perm:[2,3,0,1] row_mask:0xf bank_mask:0xf bound_ctrl:1
	v_pk_fma_f32 v[10:11], v[2:3], v[62:63], v[10:11]
	v_add_f32_dpp v202, v202, v202 row_ror:8 row_mask:0xf bank_mask:0x3 bound_ctrl:1
	v_add_f32_dpp v4, v4, v4 row_ror:4 row_mask:0xf bank_mask:0xf bound_ctrl:1
	ds_read_b128 v[36:39], v88 offset:7168
	v_add_f32_dpp v202, v210, v210 row_ror:8 row_mask:0xf bank_mask:0xc bound_ctrl:1
	v_add_f32_dpp v4, v4, v4 row_ror:8 row_mask:0xf bank_mask:0xf bound_ctrl:1
	v_pk_fma_f32 v[0:1], v[4:5], v[72:73], v[8:9] op_sel_hi:[0,1,1]
	v_pk_fma_f32 v[2:3], v[4:5], v[74:75], v[10:11] op_sel_hi:[0,1,1]
	v_pk_mul_f32 v[6:7], v[0:1], v[76:77]
	v_pk_fma_f32 v[6:7], v[2:3], v[78:79], v[6:7]
	v_add_f32_e32 v184, v6, v7
	ds_read2st64_b32 v[16:17], v90 offset0:29 offset1:35
	v_add_f32_dpp v203, v203, v203 row_ror:8 row_mask:0xf bank_mask:0x3 bound_ctrl:1
	v_add_f32_dpp v203, v211, v211 row_ror:8 row_mask:0xf bank_mask:0xc bound_ctrl:1
	s_waitcnt lgkmcnt(6)
	v_pk_mul_f32 v[4:5], v[0:1], v[92:93] neg_lo:[0,1] neg_hi:[0,1]
	ds_read_b128 v[48:51], v88 offset:8192
	v_pk_fma_f32 v[4:5], v[2:3], v[94:95], v[4:5] neg_lo:[0,1,0] neg_hi:[0,1,0]
	ds_read_b128 v[44:47], v88 offset:7936
	v_pk_mul_f32 v[8:9], v[84:85], v[18:19] op_sel:[0,1] op_sel_hi:[1,1]
	v_add_f32_e32 v4, v4, v5
	ds_read_b128 v[40:43], v88 offset:7680
	v_pk_mul_f32 v[10:11], v[86:87], v[18:19] op_sel:[0,1] op_sel_hi:[1,1]
	v_add_f32_dpp v4, v4, v4 quad_perm:[1,0,3,2] row_mask:0xf bank_mask:0xf bound_ctrl:1
	ds_read_b128 v[52:55], v88 offset:8448
	v_pk_fma_f32 v[8:9], v[0:1], v[80:81], v[8:9]
	v_add_f32_dpp v4, v4, v4 quad_perm:[2,3,0,1] row_mask:0xf bank_mask:0xf bound_ctrl:1
	v_pk_fma_f32 v[10:11], v[2:3], v[82:83], v[10:11]
	v_add_f32_dpp v204, v204, v204 row_ror:8 row_mask:0xf bank_mask:0x3 bound_ctrl:1
	v_add_f32_dpp v4, v4, v4 row_ror:4 row_mask:0xf bank_mask:0xf bound_ctrl:1
	ds_read_b128 v[56:59], v88 offset:8704
	v_add_f32_dpp v204, v212, v212 row_ror:8 row_mask:0xf bank_mask:0xc bound_ctrl:1
	v_add_f32_dpp v4, v4, v4 row_ror:8 row_mask:0xf bank_mask:0xf bound_ctrl:1
	v_pk_fma_f32 v[0:1], v[4:5], v[96:97], v[8:9] op_sel_hi:[0,1,1]
	v_pk_fma_f32 v[2:3], v[4:5], v[98:99], v[10:11] op_sel_hi:[0,1,1]
	v_pk_mul_f32 v[6:7], v[0:1], v[100:101]
	v_pk_fma_f32 v[6:7], v[2:3], v[102:103], v[6:7]
	v_add_f32_e32 v185, v6, v7
	v_add_f32_dpp v205, v205, v205 row_ror:8 row_mask:0xf bank_mask:0x3 bound_ctrl:1
	v_add_f32_dpp v205, v213, v213 row_ror:8 row_mask:0xf bank_mask:0xc bound_ctrl:1
	s_waitcnt lgkmcnt(5)
	v_pk_mul_f32 v[4:5], v[0:1], v[28:29] neg_lo:[0,1] neg_hi:[0,1]
	ds_read_b128 v[68:71], v88 offset:9728
	v_pk_fma_f32 v[4:5], v[2:3], v[30:31], v[4:5] neg_lo:[0,1,0] neg_hi:[0,1,0]
	ds_read_b128 v[64:67], v88 offset:9472
	v_pk_mul_f32 v[8:9], v[24:25], v[16:17] op_sel_hi:[1,0]
	v_add_f32_e32 v4, v4, v5
	ds_read_b128 v[60:63], v88 offset:9216
	v_pk_mul_f32 v[10:11], v[26:27], v[16:17] op_sel_hi:[1,0]
	v_add_f32_dpp v4, v4, v4 quad_perm:[1,0,3,2] row_mask:0xf bank_mask:0xf bound_ctrl:1
	ds_read_b128 v[72:75], v88 offset:9984
	v_pk_fma_f32 v[8:9], v[0:1], v[20:21], v[8:9]
	v_add_f32_dpp v4, v4, v4 quad_perm:[2,3,0,1] row_mask:0xf bank_mask:0xf bound_ctrl:1
	v_pk_fma_f32 v[10:11], v[2:3], v[22:23], v[10:11]
	v_add_f32_dpp v198, v198, v198 row_shl:4 row_mask:0xf bank_mask:0x5 bound_ctrl:1
	v_add_f32_dpp v4, v4, v4 row_ror:4 row_mask:0xf bank_mask:0xf bound_ctrl:1
	ds_read_b128 v[76:79], v88 offset:10240
	v_add_f32_dpp v198, v202, v202 row_shr:4 row_mask:0xf bank_mask:0xa bound_ctrl:1
	v_add_f32_dpp v4, v4, v4 row_ror:8 row_mask:0xf bank_mask:0xf bound_ctrl:1
	v_pk_fma_f32 v[0:1], v[4:5], v[32:33], v[8:9] op_sel_hi:[0,1,1]
	v_pk_fma_f32 v[2:3], v[4:5], v[34:35], v[10:11] op_sel_hi:[0,1,1]
	v_pk_mul_f32 v[6:7], v[0:1], v[36:37]
	v_pk_fma_f32 v[6:7], v[2:3], v[38:39], v[6:7]
	v_add_f32_e32 v186, v6, v7
	ds_read2st64_b32 v[18:19], v90 offset0:41 offset1:47
	v_add_f32_dpp v199, v199, v199 row_shl:4 row_mask:0xf bank_mask:0x5 bound_ctrl:1
	v_add_f32_dpp v199, v203, v203 row_shr:4 row_mask:0xf bank_mask:0xa bound_ctrl:1
	s_waitcnt vmcnt(19)
	ds_write_b128 v91, v[128:131] offset:24576
	s_waitcnt lgkmcnt(7)
	v_pk_mul_f32 v[4:5], v[0:1], v[48:49] neg_lo:[0,1] neg_hi:[0,1]
	ds_read_b128 v[92:95], v88 offset:11264
	v_pk_fma_f32 v[4:5], v[2:3], v[50:51], v[4:5] neg_lo:[0,1,0] neg_hi:[0,1,0]
	ds_read_b128 v[84:87], v88 offset:11008
	v_pk_mul_f32 v[8:9], v[44:45], v[16:17] op_sel:[0,1] op_sel_hi:[1,1]
	v_add_f32_e32 v4, v4, v5
	ds_read_b128 v[80:83], v88 offset:10752
	v_pk_mul_f32 v[10:11], v[46:47], v[16:17] op_sel:[0,1] op_sel_hi:[1,1]
	v_add_f32_dpp v4, v4, v4 quad_perm:[1,0,3,2] row_mask:0xf bank_mask:0xf bound_ctrl:1
	ds_read_b128 v[96:99], v88 offset:11520
	v_pk_fma_f32 v[8:9], v[0:1], v[40:41], v[8:9]
	v_add_f32_dpp v4, v4, v4 quad_perm:[2,3,0,1] row_mask:0xf bank_mask:0xf bound_ctrl:1
	v_pk_fma_f32 v[10:11], v[2:3], v[42:43], v[10:11]
	v_add_f32_dpp v200, v200, v200 row_shl:4 row_mask:0xf bank_mask:0x5 bound_ctrl:1
	v_add_f32_dpp v4, v4, v4 row_ror:4 row_mask:0xf bank_mask:0xf bound_ctrl:1
	ds_read_b128 v[100:103], v88 offset:11776
	v_add_f32_dpp v200, v204, v204 row_shr:4 row_mask:0xf bank_mask:0xa bound_ctrl:1
	v_add_f32_dpp v4, v4, v4 row_ror:8 row_mask:0xf bank_mask:0xf bound_ctrl:1
	v_pk_fma_f32 v[0:1], v[4:5], v[52:53], v[8:9] op_sel_hi:[0,1,1]
	v_pk_fma_f32 v[2:3], v[4:5], v[54:55], v[10:11] op_sel_hi:[0,1,1]
	v_pk_mul_f32 v[6:7], v[0:1], v[56:57]
	v_pk_fma_f32 v[6:7], v[2:3], v[58:59], v[6:7]
	v_add_f32_e32 v187, v6, v7
	v_add_f32_dpp v201, v201, v201 row_shl:4 row_mask:0xf bank_mask:0x5 bound_ctrl:1
	v_add_f32_dpp v201, v205, v205 row_shr:4 row_mask:0xf bank_mask:0xa bound_ctrl:1
	ds_write_b128 v91, v[132:135] offset:25600
	ds_write_b32 v91, v173 offset:25856
	s_waitcnt lgkmcnt(8)
	v_pk_mul_f32 v[4:5], v[0:1], v[68:69] neg_lo:[0,1] neg_hi:[0,1]
	ds_read_b128 v[28:31], v88 offset:12800
	v_pk_fma_f32 v[4:5], v[2:3], v[70:71], v[4:5] neg_lo:[0,1,0] neg_hi:[0,1,0]
	ds_read_b128 v[24:27], v88 offset:12544
	v_pk_mul_f32 v[8:9], v[64:65], v[18:19] op_sel_hi:[1,0]
	v_add_f32_e32 v4, v4, v5
	ds_read_b128 v[20:23], v88 offset:12288
	v_pk_mul_f32 v[10:11], v[66:67], v[18:19] op_sel_hi:[1,0]
	v_add_f32_dpp v4, v4, v4 quad_perm:[1,0,3,2] row_mask:0xf bank_mask:0xf bound_ctrl:1
	ds_read_b128 v[32:35], v88 offset:13056
	v_pk_fma_f32 v[8:9], v[0:1], v[60:61], v[8:9]
	v_add_f32_dpp v4, v4, v4 quad_perm:[2,3,0,1] row_mask:0xf bank_mask:0xf bound_ctrl:1
	v_pk_fma_f32 v[10:11], v[2:3], v[62:63], v[10:11]
	v_add_f32_dpp v198, v198, v198 quad_perm:[1,0,3,2] row_mask:0xf bank_mask:0xf bound_ctrl:1
	v_add_f32_dpp v4, v4, v4 row_ror:4 row_mask:0xf bank_mask:0xf bound_ctrl:1
	ds_read_b128 v[36:39], v88 offset:13312
	v_add_f32_dpp v199, v199, v199 quad_perm:[1,0,3,2] row_mask:0xf bank_mask:0xf bound_ctrl:1
	v_add_f32_dpp v4, v4, v4 row_ror:8 row_mask:0xf bank_mask:0xf bound_ctrl:1
	v_pk_fma_f32 v[0:1], v[4:5], v[72:73], v[8:9] op_sel_hi:[0,1,1]
	v_pk_fma_f32 v[2:3], v[4:5], v[74:75], v[10:11] op_sel_hi:[0,1,1]
	v_pk_mul_f32 v[6:7], v[0:1], v[76:77]
	v_pk_fma_f32 v[6:7], v[2:3], v[78:79], v[6:7]
	v_add_f32_e32 v188, v6, v7
	ds_read2st64_b32 v[16:17], v90 offset0:53 offset1:59
	v_cndmask_b32_e64 v198, v198, v199, s[30:31]
	v_lshlrev_b32_e32 v176, 16, v164
	v_and_b32_e32 v177, 0xffff0000, v164
	s_waitcnt lgkmcnt(8)
	v_pk_mul_f32 v[4:5], v[0:1], v[92:93] neg_lo:[0,1] neg_hi:[0,1]
	ds_read_b128 v[48:51], v88 offset:14336
	v_pk_fma_f32 v[4:5], v[2:3], v[94:95], v[4:5] neg_lo:[0,1,0] neg_hi:[0,1,0]
	ds_read_b128 v[44:47], v88 offset:14080
	v_pk_mul_f32 v[8:9], v[84:85], v[18:19] op_sel:[0,1] op_sel_hi:[1,1]
	v_add_f32_e32 v4, v4, v5
	ds_read_b128 v[40:43], v88 offset:13824
	v_pk_mul_f32 v[10:11], v[86:87], v[18:19] op_sel:[0,1] op_sel_hi:[1,1]
	v_add_f32_dpp v4, v4, v4 quad_perm:[1,0,3,2] row_mask:0xf bank_mask:0xf bound_ctrl:1
	ds_read_b128 v[52:55], v88 offset:14592
	v_pk_fma_f32 v[8:9], v[0:1], v[80:81], v[8:9]
	v_add_f32_dpp v4, v4, v4 quad_perm:[2,3,0,1] row_mask:0xf bank_mask:0xf bound_ctrl:1
	v_pk_fma_f32 v[10:11], v[2:3], v[82:83], v[10:11]
	v_add_f32_dpp v200, v200, v200 quad_perm:[1,0,3,2] row_mask:0xf bank_mask:0xf bound_ctrl:1
	v_add_f32_dpp v4, v4, v4 row_ror:4 row_mask:0xf bank_mask:0xf bound_ctrl:1
	ds_read_b128 v[56:59], v88 offset:14848
	v_add_f32_dpp v201, v201, v201 quad_perm:[1,0,3,2] row_mask:0xf bank_mask:0xf bound_ctrl:1
	v_add_f32_dpp v4, v4, v4 row_ror:8 row_mask:0xf bank_mask:0xf bound_ctrl:1
	v_pk_fma_f32 v[0:1], v[4:5], v[96:97], v[8:9] op_sel_hi:[0,1,1]
	v_pk_fma_f32 v[2:3], v[4:5], v[98:99], v[10:11] op_sel_hi:[0,1,1]
	v_pk_mul_f32 v[6:7], v[0:1], v[100:101]
	v_pk_fma_f32 v[6:7], v[2:3], v[102:103], v[6:7]
	v_add_f32_e32 v189, v6, v7
	v_cndmask_b32_e64 v200, v200, v201, s[30:31]
	v_lshlrev_b32_e32 v178, 16, v165
	v_and_b32_e32 v179, 0xffff0000, v165
	s_waitcnt lgkmcnt(5)
	v_pk_mul_f32 v[4:5], v[0:1], v[28:29] neg_lo:[0,1] neg_hi:[0,1]
	ds_read_b128 v[68:71], v88 offset:15872
	v_pk_fma_f32 v[4:5], v[2:3], v[30:31], v[4:5] neg_lo:[0,1,0] neg_hi:[0,1,0]
	ds_read_b128 v[64:67], v88 offset:15616
	v_pk_mul_f32 v[8:9], v[24:25], v[16:17] op_sel_hi:[1,0]
	v_add_f32_e32 v4, v4, v5
	ds_read_b128 v[60:63], v88 offset:15360
	v_pk_mul_f32 v[10:11], v[26:27], v[16:17] op_sel_hi:[1,0]
	v_add_f32_dpp v4, v4, v4 quad_perm:[1,0,3,2] row_mask:0xf bank_mask:0xf bound_ctrl:1
	ds_read_b128 v[72:75], v88 offset:16128
	v_pk_fma_f32 v[8:9], v[0:1], v[20:21], v[8:9]
	v_add_f32_dpp v4, v4, v4 quad_perm:[2,3,0,1] row_mask:0xf bank_mask:0xf bound_ctrl:1
	v_pk_fma_f32 v[10:11], v[2:3], v[22:23], v[10:11]
	v_add_f32_dpp v198, v198, v198 quad_perm:[2,3,0,1] row_mask:0xf bank_mask:0xf bound_ctrl:1
	v_add_f32_dpp v4, v4, v4 row_ror:4 row_mask:0xf bank_mask:0xf bound_ctrl:1
	ds_read_b128 v[76:79], v88 offset:16384
	v_add_f32_dpp v200, v200, v200 quad_perm:[2,3,0,1] row_mask:0xf bank_mask:0xf bound_ctrl:1
	v_add_f32_dpp v4, v4, v4 row_ror:8 row_mask:0xf bank_mask:0xf bound_ctrl:1
	v_pk_fma_f32 v[0:1], v[4:5], v[32:33], v[8:9] op_sel_hi:[0,1,1]
	v_pk_fma_f32 v[2:3], v[4:5], v[34:35], v[10:11] op_sel_hi:[0,1,1]
	v_pk_mul_f32 v[6:7], v[0:1], v[36:37]
	v_pk_fma_f32 v[6:7], v[2:3], v[38:39], v[6:7]
	v_add_f32_e32 v190, v6, v7
	ds_read2st64_b32 v[18:19], v90 offset0:65 offset1:71
	v_cndmask_b32_e64 v214, v198, v200, s[34:35]
	v_cvt_pk_bf16_f32 v214, v214, v214
	ds_write_b128 v91, v[176:179] offset:24832
	v_lshlrev_b32_e32 v176, 16, v166
	s_waitcnt lgkmcnt(7)
	v_pk_mul_f32 v[4:5], v[0:1], v[48:49] neg_lo:[0,1] neg_hi:[0,1]
	ds_read_b128 v[92:95], v88 offset:17408
	v_pk_fma_f32 v[4:5], v[2:3], v[50:51], v[4:5] neg_lo:[0,1,0] neg_hi:[0,1,0]
	ds_read_b128 v[84:87], v88 offset:17152
	v_pk_mul_f32 v[8:9], v[44:45], v[16:17] op_sel:[0,1] op_sel_hi:[1,1]
	v_add_f32_e32 v4, v4, v5
	ds_read_b128 v[80:83], v88 offset:16896
	v_pk_mul_f32 v[10:11], v[46:47], v[16:17] op_sel:[0,1] op_sel_hi:[1,1]
	v_add_f32_dpp v4, v4, v4 quad_perm:[1,0,3,2] row_mask:0xf bank_mask:0xf bound_ctrl:1
	ds_read_b128 v[96:99], v88 offset:17664
	v_pk_fma_f32 v[8:9], v[0:1], v[40:41], v[8:9]
	v_add_f32_dpp v4, v4, v4 quad_perm:[2,3,0,1] row_mask:0xf bank_mask:0xf bound_ctrl:1
	v_pk_fma_f32 v[10:11], v[2:3], v[42:43], v[10:11]
	s_nop 0
	v_add_f32_dpp v4, v4, v4 row_ror:4 row_mask:0xf bank_mask:0xf bound_ctrl:1
	ds_read_b128 v[100:103], v88 offset:17920
	s_nop 0
	v_add_f32_dpp v4, v4, v4 row_ror:8 row_mask:0xf bank_mask:0xf bound_ctrl:1
	v_pk_fma_f32 v[0:1], v[4:5], v[52:53], v[8:9] op_sel_hi:[0,1,1]
	v_pk_fma_f32 v[2:3], v[4:5], v[54:55], v[10:11] op_sel_hi:[0,1,1]
	v_pk_mul_f32 v[6:7], v[0:1], v[56:57]
	v_pk_fma_f32 v[6:7], v[2:3], v[58:59], v[6:7]
	v_add_f32_e32 v191, v6, v7
	global_store_short v145, v214, s[22:23]
	v_add_u32_e32 v145, s26, v145
	v_and_b32_e32 v177, 0xffff0000, v166
	v_lshlrev_b32_e32 v178, 16, v167
	s_waitcnt lgkmcnt(6)
	v_pk_mul_f32 v[4:5], v[0:1], v[68:69] neg_lo:[0,1] neg_hi:[0,1]
	ds_read_b128 v[28:31], v88 offset:18944
	v_pk_fma_f32 v[4:5], v[2:3], v[70:71], v[4:5] neg_lo:[0,1,0] neg_hi:[0,1,0]
	ds_read_b128 v[24:27], v88 offset:18688
	v_pk_mul_f32 v[8:9], v[64:65], v[18:19] op_sel_hi:[1,0]
	v_add_f32_e32 v4, v4, v5
	ds_read_b128 v[20:23], v88 offset:18432
	v_pk_mul_f32 v[10:11], v[66:67], v[18:19] op_sel_hi:[1,0]
	v_add_f32_dpp v4, v4, v4 quad_perm:[1,0,3,2] row_mask:0xf bank_mask:0xf bound_ctrl:1
	ds_read_b128 v[32:35], v88 offset:19200
	v_pk_fma_f32 v[8:9], v[0:1], v[60:61], v[8:9]
	v_add_f32_dpp v4, v4, v4 quad_perm:[2,3,0,1] row_mask:0xf bank_mask:0xf bound_ctrl:1
	v_pk_fma_f32 v[10:11], v[2:3], v[62:63], v[10:11]
	s_nop 0
	v_add_f32_dpp v4, v4, v4 row_ror:4 row_mask:0xf bank_mask:0xf bound_ctrl:1
	ds_read_b128 v[36:39], v88 offset:19456
	s_nop 0
	v_add_f32_dpp v4, v4, v4 row_ror:8 row_mask:0xf bank_mask:0xf bound_ctrl:1
	v_pk_fma_f32 v[0:1], v[4:5], v[72:73], v[8:9] op_sel_hi:[0,1,1]
	v_pk_fma_f32 v[2:3], v[4:5], v[74:75], v[10:11] op_sel_hi:[0,1,1]
	v_pk_mul_f32 v[6:7], v[0:1], v[76:77]
	v_pk_fma_f32 v[6:7], v[2:3], v[78:79], v[6:7]
	v_add_f32_e32 v192, v6, v7
	ds_read2st64_b32 v[16:17], v90 offset0:77 offset1:83
	v_and_b32_e32 v179, 0xffff0000, v167
	ds_write_b128 v91, v[176:179] offset:25088
	s_waitcnt lgkmcnt(7)
	v_pk_mul_f32 v[4:5], v[0:1], v[92:93] neg_lo:[0,1] neg_hi:[0,1]
	ds_read_b128 v[48:51], v88 offset:20480
	v_pk_fma_f32 v[4:5], v[2:3], v[94:95], v[4:5] neg_lo:[0,1,0] neg_hi:[0,1,0]
	ds_read_b128 v[44:47], v88 offset:20224
	v_pk_mul_f32 v[8:9], v[84:85], v[18:19] op_sel:[0,1] op_sel_hi:[1,1]
	v_add_f32_e32 v4, v4, v5
	ds_read_b128 v[40:43], v88 offset:19968
	v_pk_mul_f32 v[10:11], v[86:87], v[18:19] op_sel:[0,1] op_sel_hi:[1,1]
	v_add_f32_dpp v4, v4, v4 quad_perm:[1,0,3,2] row_mask:0xf bank_mask:0xf bound_ctrl:1
	ds_read_b128 v[52:55], v88 offset:20736
	v_pk_fma_f32 v[8:9], v[0:1], v[80:81], v[8:9]
	v_add_f32_dpp v4, v4, v4 quad_perm:[2,3,0,1] row_mask:0xf bank_mask:0xf bound_ctrl:1
	v_pk_fma_f32 v[10:11], v[2:3], v[82:83], v[10:11]
	s_nop 0
	v_add_f32_dpp v4, v4, v4 row_ror:4 row_mask:0xf bank_mask:0xf bound_ctrl:1
	ds_read_b128 v[56:59], v88 offset:20992
	s_nop 0
	v_add_f32_dpp v4, v4, v4 row_ror:8 row_mask:0xf bank_mask:0xf bound_ctrl:1
	v_pk_fma_f32 v[0:1], v[4:5], v[96:97], v[8:9] op_sel_hi:[0,1,1]
	v_pk_fma_f32 v[2:3], v[4:5], v[98:99], v[10:11] op_sel_hi:[0,1,1]
	v_pk_mul_f32 v[6:7], v[0:1], v[100:101]
	v_pk_fma_f32 v[6:7], v[2:3], v[102:103], v[6:7]
	v_add_f32_e32 v193, v6, v7
	v_lshlrev_b32_e32 v176, 16, v168
	v_and_b32_e32 v177, 0xffff0000, v168
	s_waitcnt lgkmcnt(6)
	v_pk_mul_f32 v[4:5], v[0:1], v[28:29] neg_lo:[0,1] neg_hi:[0,1]
	ds_read_b128 v[68:71], v88 offset:22016
	v_pk_fma_f32 v[4:5], v[2:3], v[30:31], v[4:5] neg_lo:[0,1,0] neg_hi:[0,1,0]
	ds_read_b128 v[64:67], v88 offset:21760
	v_pk_mul_f32 v[8:9], v[24:25], v[16:17] op_sel_hi:[1,0]
	v_add_f32_e32 v4, v4, v5
	ds_read_b128 v[60:63], v88 offset:21504
	v_pk_mul_f32 v[10:11], v[26:27], v[16:17] op_sel_hi:[1,0]
	v_add_f32_dpp v4, v4, v4 quad_perm:[1,0,3,2] row_mask:0xf bank_mask:0xf bound_ctrl:1
	ds_read_b128 v[72:75], v88 offset:22272
	v_pk_fma_f32 v[8:9], v[0:1], v[20:21], v[8:9]
	v_add_f32_dpp v4, v4, v4 quad_perm:[2,3,0,1] row_mask:0xf bank_mask:0xf bound_ctrl:1
	v_pk_fma_f32 v[10:11], v[2:3], v[22:23], v[10:11]
	s_nop 0
	v_add_f32_dpp v4, v4, v4 row_ror:4 row_mask:0xf bank_mask:0xf bound_ctrl:1
	ds_read_b128 v[76:79], v88 offset:22528
	s_nop 0
	v_add_f32_dpp v4, v4, v4 row_ror:8 row_mask:0xf bank_mask:0xf bound_ctrl:1
	v_pk_fma_f32 v[0:1], v[4:5], v[32:33], v[8:9] op_sel_hi:[0,1,1]
	v_pk_fma_f32 v[2:3], v[4:5], v[34:35], v[10:11] op_sel_hi:[0,1,1]
	v_pk_mul_f32 v[6:7], v[0:1], v[36:37]
	v_pk_fma_f32 v[6:7], v[2:3], v[38:39], v[6:7]
	v_add_f32_e32 v194, v6, v7
	ds_read2st64_b32 v[18:19], v90 offset0:89 offset1:95
	v_lshlrev_b32_e32 v178, 16, v169
	v_and_b32_e32 v179, 0xffff0000, v169
	ds_write_b128 v91, v[176:179] offset:25344
	s_waitcnt lgkmcnt(7)
	v_pk_mul_f32 v[4:5], v[0:1], v[48:49] neg_lo:[0,1] neg_hi:[0,1]
	ds_read_b128 v[92:95], v88 offset:23552
	v_pk_fma_f32 v[4:5], v[2:3], v[50:51], v[4:5] neg_lo:[0,1,0] neg_hi:[0,1,0]
	ds_read_b128 v[84:87], v88 offset:23296
	v_pk_mul_f32 v[8:9], v[44:45], v[16:17] op_sel:[0,1] op_sel_hi:[1,1]
	v_add_f32_e32 v4, v4, v5
	ds_read_b128 v[80:83], v88 offset:23040
	v_pk_mul_f32 v[10:11], v[46:47], v[16:17] op_sel:[0,1] op_sel_hi:[1,1]
	v_add_f32_dpp v4, v4, v4 quad_perm:[1,0,3,2] row_mask:0xf bank_mask:0xf bound_ctrl:1
	ds_read_b128 v[96:99], v88 offset:23808
	v_pk_fma_f32 v[8:9], v[0:1], v[40:41], v[8:9]
	v_add_f32_dpp v4, v4, v4 quad_perm:[2,3,0,1] row_mask:0xf bank_mask:0xf bound_ctrl:1
	v_pk_fma_f32 v[10:11], v[2:3], v[42:43], v[10:11]
	s_nop 0
	v_add_f32_dpp v4, v4, v4 row_ror:4 row_mask:0xf bank_mask:0xf bound_ctrl:1
	ds_read_b128 v[100:103], v88 offset:24064
	s_nop 0
	v_add_f32_dpp v4, v4, v4 row_ror:8 row_mask:0xf bank_mask:0xf bound_ctrl:1
	v_pk_fma_f32 v[0:1], v[4:5], v[52:53], v[8:9] op_sel_hi:[0,1,1]
	v_pk_fma_f32 v[2:3], v[4:5], v[54:55], v[10:11] op_sel_hi:[0,1,1]
	v_pk_mul_f32 v[6:7], v[0:1], v[56:57]
	v_pk_fma_f32 v[6:7], v[2:3], v[58:59], v[6:7]
	v_add_f32_e32 v195, v6, v7
	s_waitcnt lgkmcnt(0)
	s_barrier
	v_pk_mul_f32 v[4:5], v[0:1], v[68:69] neg_lo:[0,1] neg_hi:[0,1]
	ds_read_b128 v[28:31], v88 offset:25088
	v_pk_fma_f32 v[4:5], v[2:3], v[70:71], v[4:5] neg_lo:[0,1,0] neg_hi:[0,1,0]
	ds_read_b128 v[24:27], v88 offset:24832
	v_pk_mul_f32 v[8:9], v[64:65], v[18:19] op_sel_hi:[1,0]
	v_add_f32_e32 v4, v4, v5
	ds_read_b128 v[20:23], v88 offset:24576
	v_pk_mul_f32 v[10:11], v[66:67], v[18:19] op_sel_hi:[1,0]
	v_add_f32_dpp v4, v4, v4 quad_perm:[1,0,3,2] row_mask:0xf bank_mask:0xf bound_ctrl:1
	ds_read_b128 v[32:35], v88 offset:25344
	v_pk_fma_f32 v[8:9], v[0:1], v[60:61], v[8:9]
	v_add_f32_dpp v4, v4, v4 quad_perm:[2,3,0,1] row_mask:0xf bank_mask:0xf bound_ctrl:1
	v_pk_fma_f32 v[10:11], v[2:3], v[62:63], v[10:11]
	s_nop 0
	v_add_f32_dpp v4, v4, v4 row_ror:4 row_mask:0xf bank_mask:0xf bound_ctrl:1
	ds_read_b128 v[36:39], v88 offset:25600
	s_nop 0
	v_add_f32_dpp v4, v4, v4 row_ror:8 row_mask:0xf bank_mask:0xf bound_ctrl:1
	v_pk_fma_f32 v[0:1], v[4:5], v[72:73], v[8:9] op_sel_hi:[0,1,1]
	v_pk_fma_f32 v[2:3], v[4:5], v[74:75], v[10:11] op_sel_hi:[0,1,1]
	v_pk_mul_f32 v[6:7], v[0:1], v[76:77]
	v_pk_fma_f32 v[6:7], v[2:3], v[78:79], v[6:7]
	v_add_f32_e32 v196, v6, v7
	ds_read2st64_b32 v[16:17], v90 offset0:101 offset1:107
	s_waitcnt lgkmcnt(6)
	v_pk_mul_f32 v[4:5], v[0:1], v[92:93] neg_lo:[0,1] neg_hi:[0,1]
	ds_read_b128 v[48:51], v88 offset:26624
	v_pk_fma_f32 v[4:5], v[2:3], v[94:95], v[4:5] neg_lo:[0,1,0] neg_hi:[0,1,0]
	ds_read_b128 v[44:47], v88 offset:26368
	v_pk_mul_f32 v[8:9], v[84:85], v[18:19] op_sel:[0,1] op_sel_hi:[1,1]
	v_add_f32_e32 v4, v4, v5
	ds_read_b128 v[40:43], v88 offset:26112
	v_pk_mul_f32 v[10:11], v[86:87], v[18:19] op_sel:[0,1] op_sel_hi:[1,1]
	v_add_f32_dpp v4, v4, v4 quad_perm:[1,0,3,2] row_mask:0xf bank_mask:0xf bound_ctrl:1
	ds_read_b128 v[52:55], v88 offset:26880
	v_pk_fma_f32 v[8:9], v[0:1], v[80:81], v[8:9]
	v_add_f32_dpp v4, v4, v4 quad_perm:[2,3,0,1] row_mask:0xf bank_mask:0xf bound_ctrl:1
	v_pk_fma_f32 v[10:11], v[2:3], v[82:83], v[10:11]
	s_nop 0
	v_add_f32_dpp v4, v4, v4 row_ror:4 row_mask:0xf bank_mask:0xf bound_ctrl:1
	ds_read_b128 v[56:59], v88 offset:27136
	s_nop 0
	v_add_f32_dpp v4, v4, v4 row_ror:8 row_mask:0xf bank_mask:0xf bound_ctrl:1
	v_pk_fma_f32 v[0:1], v[4:5], v[96:97], v[8:9] op_sel_hi:[0,1,1]
	v_pk_fma_f32 v[2:3], v[4:5], v[98:99], v[10:11] op_sel_hi:[0,1,1]
	v_pk_mul_f32 v[6:7], v[0:1], v[100:101]
	v_pk_fma_f32 v[6:7], v[2:3], v[102:103], v[6:7]
	v_add_f32_e32 v197, v6, v7
	s_waitcnt lgkmcnt(5)
	v_pk_mul_f32 v[4:5], v[0:1], v[28:29] neg_lo:[0,1] neg_hi:[0,1]
	ds_read_b128 v[68:71], v88 offset:28160
	v_pk_fma_f32 v[4:5], v[2:3], v[30:31], v[4:5] neg_lo:[0,1,0] neg_hi:[0,1,0]
	ds_read_b128 v[64:67], v88 offset:27904
	v_pk_mul_f32 v[8:9], v[24:25], v[16:17] op_sel_hi:[1,0]
	v_add_f32_e32 v4, v4, v5
	ds_read_b128 v[60:63], v88 offset:27648
	v_pk_mul_f32 v[10:11], v[26:27], v[16:17] op_sel_hi:[1,0]
	v_add_f32_dpp v4, v4, v4 quad_perm:[1,0,3,2] row_mask:0xf bank_mask:0xf bound_ctrl:1
	ds_read_b128 v[72:75], v88 offset:28416
	v_pk_fma_f32 v[8:9], v[0:1], v[20:21], v[8:9]
	v_add_f32_dpp v4, v4, v4 quad_perm:[2,3,0,1] row_mask:0xf bank_mask:0xf bound_ctrl:1
	v_pk_fma_f32 v[10:11], v[2:3], v[22:23], v[10:11]
	v_add_f32_dpp v182, v182, v182 row_ror:8 row_mask:0xf bank_mask:0x3 bound_ctrl:1
	v_add_f32_dpp v4, v4, v4 row_ror:4 row_mask:0xf bank_mask:0xf bound_ctrl:1
	ds_read_b128 v[76:79], v88 offset:28672
	v_add_f32_dpp v182, v190, v190 row_ror:8 row_mask:0xf bank_mask:0xc bound_ctrl:1
	v_add_f32_dpp v4, v4, v4 row_ror:8 row_mask:0xf bank_mask:0xf bound_ctrl:1
	v_pk_fma_f32 v[0:1], v[4:5], v[32:33], v[8:9] op_sel_hi:[0,1,1]
	v_pk_fma_f32 v[2:3], v[4:5], v[34:35], v[10:11] op_sel_hi:[0,1,1]
	v_pk_mul_f32 v[6:7], v[0:1], v[36:37]
	v_pk_fma_f32 v[6:7], v[2:3], v[38:39], v[6:7]
	v_add_f32_e32 v198, v6, v7
	ds_read2st64_b32 v[18:19], v90 offset0:113 offset1:119
	s_cmp_lt_u32 s28, 15
	s_cbranch_scc0 .Lls0_skip3
	global_load_dwordx4 v[128:131], v174, s[12:13]
	global_load_dwordx2 v[164:165], v175, s[14:15]
	global_load_dwordx2 v[166:167], v175, s[16:17]
	global_load_dwordx2 v[168:169], v175, s[18:19]
	global_load_dwordx4 v[132:135], v180, s[20:21]
	global_load_dword v173, v181, s[20:21]
	v_add_u32_e32 v174, s25, v174
	v_add_u32_e32 v175, s26, v175
	v_add_u32_e32 v180, s27, v180
	v_add_u32_e32 v181, s27, v181
.Lls0_back3:
	v_add_f32_dpp v183, v183, v183 row_ror:8 row_mask:0xf bank_mask:0x3 bound_ctrl:1
	v_add_f32_dpp v183, v191, v191 row_ror:8 row_mask:0xf bank_mask:0xc bound_ctrl:1
	s_waitcnt lgkmcnt(6)
	v_pk_mul_f32 v[4:5], v[0:1], v[48:49] neg_lo:[0,1] neg_hi:[0,1]
	ds_read_b128 v[92:95], v88 offset:29696
	v_pk_fma_f32 v[4:5], v[2:3], v[50:51], v[4:5] neg_lo:[0,1,0] neg_hi:[0,1,0]
	ds_read_b128 v[84:87], v88 offset:29440
	v_pk_mul_f32 v[8:9], v[44:45], v[16:17] op_sel:[0,1] op_sel_hi:[1,1]
	v_add_f32_e32 v4, v4, v5
	ds_read_b128 v[80:83], v88 offset:29184
	v_pk_mul_f32 v[10:11], v[46:47], v[16:17] op_sel:[0,1] op_sel_hi:[1,1]
	v_add_f32_dpp v4, v4, v4 quad_perm:[1,0,3,2] row_mask:0xf bank_mask:0xf bound_ctrl:1
	ds_read_b128 v[96:99], v88 offset:29952
	v_pk_fma_f32 v[8:9], v[0:1], v[40:41], v[8:9]
	v_add_f32_dpp v4, v4, v4 quad_perm:[2,3,0,1] row_mask:0xf bank_mask:0xf bound_ctrl:1
	v_pk_fma_f32 v[10:11], v[2:3], v[42:43], v[10:11]
	v_add_f32_dpp v184, v184, v184 row_ror:8 row_mask:0xf bank_mask:0x3 bound_ctrl:1
	v_add_f32_dpp v4, v4, v4 row_ror:4 row_mask:0xf bank_mask:0xf bound_ctrl:1
	ds_read_b128 v[100:103], v88 offset:30208
	v_add_f32_dpp v184, v192, v192 row_ror:8 row_mask:0xf bank_mask:0xc bound_ctrl:1
	v_add_f32_dpp v4, v4, v4 row_ror:8 row_mask:0xf bank_mask:0xf bound_ctrl:1
	v_pk_fma_f32 v[0:1], v[4:5], v[52:53], v[8:9] op_sel_hi:[0,1,1]
	v_pk_fma_f32 v[2:3], v[4:5], v[54:55], v[10:11] op_sel_hi:[0,1,1]
	v_pk_mul_f32 v[6:7], v[0:1], v[56:57]
	v_pk_fma_f32 v[6:7], v[2:3], v[58:59], v[6:7]
	v_add_f32_e32 v199, v6, v7
	v_add_f32_dpp v185, v185, v185 row_ror:8 row_mask:0xf bank_mask:0x3 bound_ctrl:1
	v_add_f32_dpp v185, v193, v193 row_ror:8 row_mask:0xf bank_mask:0xc bound_ctrl:1
	s_waitcnt lgkmcnt(5)
	v_pk_mul_f32 v[4:5], v[0:1], v[68:69] neg_lo:[0,1] neg_hi:[0,1]
	ds_read_b128 v[28:31], v88 offset:31232
	v_pk_fma_f32 v[4:5], v[2:3], v[70:71], v[4:5] neg_lo:[0,1,0] neg_hi:[0,1,0]
	ds_read_b128 v[24:27], v88 offset:30976
	v_pk_mul_f32 v[8:9], v[64:65], v[18:19] op_sel_hi:[1,0]
	v_add_f32_e32 v4, v4, v5
	ds_read_b128 v[20:23], v88 offset:30720
	v_pk_mul_f32 v[10:11], v[66:67], v[18:19] op_sel_hi:[1,0]
	v_add_f32_dpp v4, v4, v4 quad_perm:[1,0,3,2] row_mask:0xf bank_mask:0xf bound_ctrl:1
	ds_read_b128 v[32:35], v88 offset:31488
	v_pk_fma_f32 v[8:9], v[0:1], v[60:61], v[8:9]
	v_add_f32_dpp v4, v4, v4 quad_perm:[2,3,0,1] row_mask:0xf bank_mask:0xf bound_ctrl:1
	v_pk_fma_f32 v[10:11], v[2:3], v[62:63], v[10:11]
	v_add_f32_dpp v186, v186, v186 row_ror:8 row_mask:0xf bank_mask:0x3 bound_ctrl:1
	v_add_f32_dpp v4, v4, v4 row_ror:4 row_mask:0xf bank_mask:0xf bound_ctrl:1
	ds_read_b128 v[36:39], v88 offset:31744
	v_add_f32_dpp v186, v194, v194 row_ror:8 row_mask:0xf bank_mask:0xc bound_ctrl:1
	v_add_f32_dpp v4, v4, v4 row_ror:8 row_mask:0xf bank_mask:0xf bound_ctrl:1
	v_pk_fma_f32 v[0:1], v[4:5], v[72:73], v[8:9] op_sel_hi:[0,1,1]
	v_pk_fma_f32 v[2:3], v[4:5], v[74:75], v[10:11] op_sel_hi:[0,1,1]
	v_pk_mul_f32 v[6:7], v[0:1], v[76:77]
	v_pk_fma_f32 v[6:7], v[2:3], v[78:79], v[6:7]
	v_add_f32_e32 v200, v6, v7
	ds_read2st64_b32 v[16:17], v90 offset0:125 offset1:131
	v_add_f32_dpp v187, v187, v187 row_ror:8 row_mask:0xf bank_mask:0x3 bound_ctrl:1
	v_add_f32_dpp v187, v195, v195 row_ror:8 row_mask:0xf bank_mask:0xc bound_ctrl:1
	s_waitcnt lgkmcnt(6)
	v_pk_mul_f32 v[4:5], v[0:1], v[92:93] neg_lo:[0,1] neg_hi:[0,1]
	ds_read_b128 v[48:51], v88 offset:32768
	v_pk_fma_f32 v[4:5], v[2:3], v[94:95], v[4:5] neg_lo:[0,1,0] neg_hi:[0,1,0]
	ds_read_b128 v[44:47], v88 offset:32512
	v_pk_mul_f32 v[8:9], v[84:85], v[18:19] op_sel:[0,1] op_sel_hi:[1,1]
	v_add_f32_e32 v4, v4, v5
	ds_read_b128 v[40:43], v88 offset:32256
	v_pk_mul_f32 v[10:11], v[86:87], v[18:19] op_sel:[0,1] op_sel_hi:[1,1]
	v_add_f32_dpp v4, v4, v4 quad_perm:[1,0,3,2] row_mask:0xf bank_mask:0xf bound_ctrl:1
	ds_read_b128 v[52:55], v88 offset:33024
	v_pk_fma_f32 v[8:9], v[0:1], v[80:81], v[8:9]
	v_add_f32_dpp v4, v4, v4 quad_perm:[2,3,0,1] row_mask:0xf bank_mask:0xf bound_ctrl:1
	v_pk_fma_f32 v[10:11], v[2:3], v[82:83], v[10:11]
	v_add_f32_dpp v188, v188, v188 row_ror:8 row_mask:0xf bank_mask:0x3 bound_ctrl:1
	v_add_f32_dpp v4, v4, v4 row_ror:4 row_mask:0xf bank_mask:0xf bound_ctrl:1
	ds_read_b128 v[56:59], v88 offset:33280
	v_add_f32_dpp v188, v196, v196 row_ror:8 row_mask:0xf bank_mask:0xc bound_ctrl:1
	v_add_f32_dpp v4, v4, v4 row_ror:8 row_mask:0xf bank_mask:0xf bound_ctrl:1
	v_pk_fma_f32 v[0:1], v[4:5], v[96:97], v[8:9] op_sel_hi:[0,1,1]
	v_pk_fma_f32 v[2:3], v[4:5], v[98:99], v[10:11] op_sel_hi:[0,1,1]
	v_pk_mul_f32 v[6:7], v[0:1], v[100:101]
	v_pk_fma_f32 v[6:7], v[2:3], v[102:103], v[6:7]
	v_add_f32_e32 v201, v6, v7
	v_add_f32_dpp v189, v189, v189 row_ror:8 row_mask:0xf bank_mask:0x3 bound_ctrl:1
	v_add_f32_dpp v189, v197, v197 row_ror:8 row_mask:0xf bank_mask:0xc bound_ctrl:1
	s_waitcnt lgkmcnt(5)
	v_pk_mul_f32 v[4:5], v[0:1], v[28:29] neg_lo:[0,1] neg_hi:[0,1]
	ds_read_b128 v[68:71], v88 offset:34304
	v_pk_fma_f32 v[4:5], v[2:3], v[30:31], v[4:5] neg_lo:[0,1,0] neg_hi:[0,1,0]
	ds_read_b128 v[64:67], v88 offset:34048
	v_pk_mul_f32 v[8:9], v[24:25], v[16:17] op_sel_hi:[1,0]
	v_add_f32_e32 v4, v4, v5
	ds_read_b128 v[60:63], v88 offset:33792
	v_pk_mul_f32 v[10:11], v[26:27], v[16:17] op_sel_hi:[1,0]
	v_add_f32_dpp v4, v4, v4 quad_perm:[1,0,3,2] row_mask:0xf bank_mask:0xf bound_ctrl:1
	ds_read_b128 v[72:75], v88 offset:34560
	v_pk_fma_f32 v[8:9], v[0:1], v[20:21], v[8:9]
	v_add_f32_dpp v4, v4, v4 quad_perm:[2,3,0,1] row_mask:0xf bank_mask:0xf bound_ctrl:1
	v_pk_fma_f32 v[10:11], v[2:3], v[22:23], v[10:11]
	v_add_f32_dpp v182, v182, v182 row_shl:4 row_mask:0xf bank_mask:0x5 bound_ctrl:1
	v_add_f32_dpp v4, v4, v4 row_ror:4 row_mask:0xf bank_mask:0xf bound_ctrl:1
	ds_read_b128 v[76:79], v88 offset:34816
	v_add_f32_dpp v182, v186, v186 row_shr:4 row_mask:0xf bank_mask:0xa bound_ctrl:1
	v_add_f32_dpp v4, v4, v4 row_ror:8 row_mask:0xf bank_mask:0xf bound_ctrl:1
	v_pk_fma_f32 v[0:1], v[4:5], v[32:33], v[8:9] op_sel_hi:[0,1,1]
	v_pk_fma_f32 v[2:3], v[4:5], v[34:35], v[10:11] op_sel_hi:[0,1,1]
	v_pk_mul_f32 v[6:7], v[0:1], v[36:37]
	v_pk_fma_f32 v[6:7], v[2:3], v[38:39], v[6:7]
	v_add_f32_e32 v202, v6, v7
	ds_read2st64_b32 v[18:19], v90 offset0:137 offset1:143
	v_add_f32_dpp v183, v183, v183 row_shl:4 row_mask:0xf bank_mask:0x5 bound_ctrl:1
	v_add_f32_dpp v183, v187, v187 row_shr:4 row_mask:0xf bank_mask:0xa bound_ctrl:1
	s_waitcnt vmcnt(20)
	ds_write_b128 v91, v[104:107] offset:0
	s_waitcnt lgkmcnt(7)
	v_pk_mul_f32 v[4:5], v[0:1], v[48:49] neg_lo:[0,1] neg_hi:[0,1]
	ds_read_b128 v[92:95], v88 offset:35840
	v_pk_fma_f32 v[4:5], v[2:3], v[50:51], v[4:5] neg_lo:[0,1,0] neg_hi:[0,1,0]
	ds_read_b128 v[84:87], v88 offset:35584
	v_pk_mul_f32 v[8:9], v[44:45], v[16:17] op_sel:[0,1] op_sel_hi:[1,1]
	v_add_f32_e32 v4, v4, v5
	ds_read_b128 v[80:83], v88 offset:35328
	v_pk_mul_f32 v[10:11], v[46:47], v[16:17] op_sel:[0,1] op_sel_hi:[1,1]
	v_add_f32_dpp v4, v4, v4 quad_perm:[1,0,3,2] row_mask:0xf bank_mask:0xf bound_ctrl:1
	ds_read_b128 v[96:99], v88 offset:36096
	v_pk_fma_f32 v[8:9], v[0:1], v[40:41], v[8:9]
	v_add_f32_dpp v4, v4, v4 quad_perm:[2,3,0,1] row_mask:0xf bank_mask:0xf bound_ctrl:1
	v_pk_fma_f32 v[10:11], v[2:3], v[42:43], v[10:11]
	v_add_f32_dpp v184, v184, v184 row_shl:4 row_mask:0xf bank_mask:0x5 bound_ctrl:1
	v_add_f32_dpp v4, v4, v4 row_ror:4 row_mask:0xf bank_mask:0xf bound_ctrl:1
	ds_read_b128 v[100:103], v88 offset:36352
	v_add_f32_dpp v184, v188, v188 row_shr:4 row_mask:0xf bank_mask:0xa bound_ctrl:1
	v_add_f32_dpp v4, v4, v4 row_ror:8 row_mask:0xf bank_mask:0xf bound_ctrl:1
	v_pk_fma_f32 v[0:1], v[4:5], v[52:53], v[8:9] op_sel_hi:[0,1,1]
	v_pk_fma_f32 v[2:3], v[4:5], v[54:55], v[10:11] op_sel_hi:[0,1,1]
	v_pk_mul_f32 v[6:7], v[0:1], v[56:57]
	v_pk_fma_f32 v[6:7], v[2:3], v[58:59], v[6:7]
	v_add_f32_e32 v203, v6, v7
	v_add_f32_dpp v185, v185, v185 row_shl:4 row_mask:0xf bank_mask:0x5 bound_ctrl:1
	v_add_f32_dpp v185, v189, v189 row_shr:4 row_mask:0xf bank_mask:0xa bound_ctrl:1
	ds_write_b128 v91, v[108:111] offset:1024
	ds_write_b32 v91, v170 offset:1280
	s_waitcnt lgkmcnt(8)
	v_pk_mul_f32 v[4:5], v[0:1], v[68:69] neg_lo:[0,1] neg_hi:[0,1]
	ds_read_b128 v[28:31], v88 offset:37376
	v_pk_fma_f32 v[4:5], v[2:3], v[70:71], v[4:5] neg_lo:[0,1,0] neg_hi:[0,1,0]
	ds_read_b128 v[24:27], v88 offset:37120
	v_pk_mul_f32 v[8:9], v[64:65], v[18:19] op_sel_hi:[1,0]
	v_add_f32_e32 v4, v4, v5
	ds_read_b128 v[20:23], v88 offset:36864
	v_pk_mul_f32 v[10:11], v[66:67], v[18:19] op_sel_hi:[1,0]
	v_add_f32_dpp v4, v4, v4 quad_perm:[1,0,3,2] row_mask:0xf bank_mask:0xf bound_ctrl:1
	ds_read_b128 v[32:35], v88 offset:37632
	v_pk_fma_f32 v[8:9], v[0:1], v[60:61], v[8:9]
	v_add_f32_dpp v4, v4, v4 quad_perm:[2,3,0,1] row_mask:0xf bank_mask:0xf bound_ctrl:1
	v_pk_fma_f32 v[10:11], v[2:3], v[62:63], v[10:11]
	v_add_f32_dpp v182, v182, v182 quad_perm:[1,0,3,2] row_mask:0xf bank_mask:0xf bound_ctrl:1
	v_add_f32_dpp v4, v4, v4 row_ror:4 row_mask:0xf bank_mask:0xf bound_ctrl:1
	ds_read_b128 v[36:39], v88 offset:37888
	v_add_f32_dpp v183, v183, v183 quad_perm:[1,0,3,2] row_mask:0xf bank_mask:0xf bound_ctrl:1
	v_add_f32_dpp v4, v4, v4 row_ror:8 row_mask:0xf bank_mask:0xf bound_ctrl:1
	v_pk_fma_f32 v[0:1], v[4:5], v[72:73], v[8:9] op_sel_hi:[0,1,1]
	v_pk_fma_f32 v[2:3], v[4:5], v[74:75], v[10:11] op_sel_hi:[0,1,1]
	v_pk_mul_f32 v[6:7], v[0:1], v[76:77]
	v_pk_fma_f32 v[6:7], v[2:3], v[78:79], v[6:7]
	v_add_f32_e32 v204, v6, v7
	ds_read2st64_b32 v[16:17], v90 offset0:149 offset1:155
	v_cndmask_b32_e64 v182, v182, v183, s[30:31]
	v_lshlrev_b32_e32 v176, 16, v146
	v_and_b32_e32 v177, 0xffff0000, v146
	s_waitcnt lgkmcnt(8)
	v_pk_mul_f32 v[4:5], v[0:1], v[92:93] neg_lo:[0,1] neg_hi:[0,1]
	ds_read_b128 v[48:51], v88 offset:38912
	v_pk_fma_f32 v[4:5], v[2:3], v[94:95], v[4:5] neg_lo:[0,1,0] neg_hi:[0,1,0]
	ds_read_b128 v[44:47], v88 offset:38656
	v_pk_mul_f32 v[8:9], v[84:85], v[18:19] op_sel:[0,1] op_sel_hi:[1,1]
	v_add_f32_e32 v4, v4, v5
	ds_read_b128 v[40:43], v88 offset:38400
	v_pk_mul_f32 v[10:11], v[86:87], v[18:19] op_sel:[0,1] op_sel_hi:[1,1]
	v_add_f32_dpp v4, v4, v4 quad_perm:[1,0,3,2] row_mask:0xf bank_mask:0xf bound_ctrl:1
	ds_read_b128 v[52:55], v88 offset:39168
	v_pk_fma_f32 v[8:9], v[0:1], v[80:81], v[8:9]
	v_add_f32_dpp v4, v4, v4 quad_perm:[2,3,0,1] row_mask:0xf bank_mask:0xf bound_ctrl:1
	v_pk_fma_f32 v[10:11], v[2:3], v[82:83], v[10:11]
	v_add_f32_dpp v184, v184, v184 quad_perm:[1,0,3,2] row_mask:0xf bank_mask:0xf bound_ctrl:1
	v_add_f32_dpp v4, v4, v4 row_ror:4 row_mask:0xf bank_mask:0xf bound_ctrl:1
	ds_read_b128 v[56:59], v88 offset:39424
	v_add_f32_dpp v185, v185, v185 quad_perm:[1,0,3,2] row_mask:0xf bank_mask:0xf bound_ctrl:1
	v_add_f32_dpp v4, v4, v4 row_ror:8 row_mask:0xf bank_mask:0xf bound_ctrl:1
	v_pk_fma_f32 v[0:1], v[4:5], v[96:97], v[8:9] op_sel_hi:[0,1,1]
	v_pk_fma_f32 v[2:3], v[4:5], v[98:99], v[10:11] op_sel_hi:[0,1,1]
	v_pk_mul_f32 v[6:7], v[0:1], v[100:101]
	v_pk_fma_f32 v[6:7], v[2:3], v[102:103], v[6:7]
	v_add_f32_e32 v205, v6, v7
	v_cndmask_b32_e64 v184, v184, v185, s[30:31]
	v_lshlrev_b32_e32 v178, 16, v147
	v_and_b32_e32 v179, 0xffff0000, v147
	s_waitcnt lgkmcnt(5)
	v_pk_mul_f32 v[4:5], v[0:1], v[28:29] neg_lo:[0,1] neg_hi:[0,1]
	ds_read_b128 v[68:71], v88 offset:40448
	v_pk_fma_f32 v[4:5], v[2:3], v[30:31], v[4:5] neg_lo:[0,1,0] neg_hi:[0,1,0]
	ds_read_b128 v[64:67], v88 offset:40192
	v_pk_mul_f32 v[8:9], v[24:25], v[16:17] op_sel_hi:[1,0]
	v_add_f32_e32 v4, v4, v5
	ds_read_b128 v[60:63], v88 offset:39936
	v_pk_mul_f32 v[10:11], v[26:27], v[16:17] op_sel_hi:[1,0]
	v_add_f32_dpp v4, v4, v4 quad_perm:[1,0,3,2] row_mask:0xf bank_mask:0xf bound_ctrl:1
	ds_read_b128 v[72:75], v88 offset:40704
	v_pk_fma_f32 v[8:9], v[0:1], v[20:21], v[8:9]
	v_add_f32_dpp v4, v4, v4 quad_perm:[2,3,0,1] row_mask:0xf bank_mask:0xf bound_ctrl:1
	v_pk_fma_f32 v[10:11], v[2:3], v[22:23], v[10:11]
	v_add_f32_dpp v182, v182, v182 quad_perm:[2,3,0,1] row_mask:0xf bank_mask:0xf bound_ctrl:1
	v_add_f32_dpp v4, v4, v4 row_ror:4 row_mask:0xf bank_mask:0xf bound_ctrl:1
	ds_read_b128 v[76:79], v88 offset:40960
	v_add_f32_dpp v184, v184, v184 quad_perm:[2,3,0,1] row_mask:0xf bank_mask:0xf bound_ctrl:1
	v_add_f32_dpp v4, v4, v4 row_ror:8 row_mask:0xf bank_mask:0xf bound_ctrl:1
	v_pk_fma_f32 v[0:1], v[4:5], v[32:33], v[8:9] op_sel_hi:[0,1,1]
	v_pk_fma_f32 v[2:3], v[4:5], v[34:35], v[10:11] op_sel_hi:[0,1,1]
	v_pk_mul_f32 v[6:7], v[0:1], v[36:37]
	v_pk_fma_f32 v[6:7], v[2:3], v[38:39], v[6:7]
	v_add_f32_e32 v206, v6, v7
	ds_read2st64_b32 v[18:19], v90 offset0:161 offset1:167
	v_cndmask_b32_e64 v214, v182, v184, s[34:35]
	v_cvt_pk_bf16_f32 v214, v214, v214
	ds_write_b128 v91, v[176:179] offset:256
	v_lshlrev_b32_e32 v176, 16, v148
	s_waitcnt lgkmcnt(7)
	v_pk_mul_f32 v[4:5], v[0:1], v[48:49] neg_lo:[0,1] neg_hi:[0,1]
	ds_read_b128 v[92:95], v88 offset:41984
	v_pk_fma_f32 v[4:5], v[2:3], v[50:51], v[4:5] neg_lo:[0,1,0] neg_hi:[0,1,0]
	ds_read_b128 v[84:87], v88 offset:41728
	v_pk_mul_f32 v[8:9], v[44:45], v[16:17] op_sel:[0,1] op_sel_hi:[1,1]
	v_add_f32_e32 v4, v4, v5
	ds_read_b128 v[80:83], v88 offset:41472
	v_pk_mul_f32 v[10:11], v[46:47], v[16:17] op_sel:[0,1] op_sel_hi:[1,1]
	v_add_f32_dpp v4, v4, v4 quad_perm:[1,0,3,2] row_mask:0xf bank_mask:0xf bound_ctrl:1
	ds_read_b128 v[96:99], v88 offset:42240
	v_pk_fma_f32 v[8:9], v[0:1], v[40:41], v[8:9]
	v_add_f32_dpp v4, v4, v4 quad_perm:[2,3,0,1] row_mask:0xf bank_mask:0xf bound_ctrl:1
	v_pk_fma_f32 v[10:11], v[2:3], v[42:43], v[10:11]
	s_nop 0
	v_add_f32_dpp v4, v4, v4 row_ror:4 row_mask:0xf bank_mask:0xf bound_ctrl:1
	ds_read_b128 v[100:103], v88 offset:42496
	s_nop 0
	v_add_f32_dpp v4, v4, v4 row_ror:8 row_mask:0xf bank_mask:0xf bound_ctrl:1
	v_pk_fma_f32 v[0:1], v[4:5], v[52:53], v[8:9] op_sel_hi:[0,1,1]
	v_pk_fma_f32 v[2:3], v[4:5], v[54:55], v[10:11] op_sel_hi:[0,1,1]
	v_pk_mul_f32 v[6:7], v[0:1], v[56:57]
	v_pk_fma_f32 v[6:7], v[2:3], v[58:59], v[6:7]
	v_add_f32_e32 v207, v6, v7
	global_store_short v145, v214, s[22:23]
	v_add_u32_e32 v145, s26, v145
	v_and_b32_e32 v177, 0xffff0000, v148
	v_lshlrev_b32_e32 v178, 16, v149
	s_waitcnt lgkmcnt(6)
	v_pk_mul_f32 v[4:5], v[0:1], v[68:69] neg_lo:[0,1] neg_hi:[0,1]
	ds_read_b128 v[28:31], v88 offset:43520
	v_pk_fma_f32 v[4:5], v[2:3], v[70:71], v[4:5] neg_lo:[0,1,0] neg_hi:[0,1,0]
	ds_read_b128 v[24:27], v88 offset:43264
	v_pk_mul_f32 v[8:9], v[64:65], v[18:19] op_sel_hi:[1,0]
	v_add_f32_e32 v4, v4, v5
	ds_read_b128 v[20:23], v88 offset:43008
	v_pk_mul_f32 v[10:11], v[66:67], v[18:19] op_sel_hi:[1,0]
	v_add_f32_dpp v4, v4, v4 quad_perm:[1,0,3,2] row_mask:0xf bank_mask:0xf bound_ctrl:1
	ds_read_b128 v[32:35], v88 offset:43776
	v_pk_fma_f32 v[8:9], v[0:1], v[60:61], v[8:9]
	v_add_f32_dpp v4, v4, v4 quad_perm:[2,3,0,1] row_mask:0xf bank_mask:0xf bound_ctrl:1
	v_pk_fma_f32 v[10:11], v[2:3], v[62:63], v[10:11]
	s_nop 0
	v_add_f32_dpp v4, v4, v4 row_ror:4 row_mask:0xf bank_mask:0xf bound_ctrl:1
	ds_read_b128 v[36:39], v88 offset:44032
	s_nop 0
	v_add_f32_dpp v4, v4, v4 row_ror:8 row_mask:0xf bank_mask:0xf bound_ctrl:1
	v_pk_fma_f32 v[0:1], v[4:5], v[72:73], v[8:9] op_sel_hi:[0,1,1]
	v_pk_fma_f32 v[2:3], v[4:5], v[74:75], v[10:11] op_sel_hi:[0,1,1]
	v_pk_mul_f32 v[6:7], v[0:1], v[76:77]
	v_pk_fma_f32 v[6:7], v[2:3], v[78:79], v[6:7]
	v_add_f32_e32 v208, v6, v7
	ds_read2st64_b32 v[16:17], v90 offset0:173 offset1:179
	v_and_b32_e32 v179, 0xffff0000, v149
	ds_write_b128 v91, v[176:179] offset:512
	s_waitcnt lgkmcnt(7)
	v_pk_mul_f32 v[4:5], v[0:1], v[92:93] neg_lo:[0,1] neg_hi:[0,1]
	ds_read_b128 v[48:51], v88 offset:45056
	v_pk_fma_f32 v[4:5], v[2:3], v[94:95], v[4:5] neg_lo:[0,1,0] neg_hi:[0,1,0]
	ds_read_b128 v[44:47], v88 offset:44800
	v_pk_mul_f32 v[8:9], v[84:85], v[18:19] op_sel:[0,1] op_sel_hi:[1,1]
	v_add_f32_e32 v4, v4, v5
	ds_read_b128 v[40:43], v88 offset:44544
	v_pk_mul_f32 v[10:11], v[86:87], v[18:19] op_sel:[0,1] op_sel_hi:[1,1]
	v_add_f32_dpp v4, v4, v4 quad_perm:[1,0,3,2] row_mask:0xf bank_mask:0xf bound_ctrl:1
	ds_read_b128 v[52:55], v88 offset:45312
	v_pk_fma_f32 v[8:9], v[0:1], v[80:81], v[8:9]
	v_add_f32_dpp v4, v4, v4 quad_perm:[2,3,0,1] row_mask:0xf bank_mask:0xf bound_ctrl:1
	v_pk_fma_f32 v[10:11], v[2:3], v[82:83], v[10:11]
	s_nop 0
	v_add_f32_dpp v4, v4, v4 row_ror:4 row_mask:0xf bank_mask:0xf bound_ctrl:1
	ds_read_b128 v[56:59], v88 offset:45568
	s_nop 0
	v_add_f32_dpp v4, v4, v4 row_ror:8 row_mask:0xf bank_mask:0xf bound_ctrl:1
	v_pk_fma_f32 v[0:1], v[4:5], v[96:97], v[8:9] op_sel_hi:[0,1,1]
	v_pk_fma_f32 v[2:3], v[4:5], v[98:99], v[10:11] op_sel_hi:[0,1,1]
	v_pk_mul_f32 v[6:7], v[0:1], v[100:101]
	v_pk_fma_f32 v[6:7], v[2:3], v[102:103], v[6:7]
	v_add_f32_e32 v209, v6, v7
	v_lshlrev_b32_e32 v176, 16, v150
	v_and_b32_e32 v177, 0xffff0000, v150
	s_waitcnt lgkmcnt(6)
	v_pk_mul_f32 v[4:5], v[0:1], v[28:29] neg_lo:[0,1] neg_hi:[0,1]
	ds_read_b128 v[68:71], v88 offset:46592
	v_pk_fma_f32 v[4:5], v[2:3], v[30:31], v[4:5] neg_lo:[0,1,0] neg_hi:[0,1,0]
	ds_read_b128 v[64:67], v88 offset:46336
	v_pk_mul_f32 v[8:9], v[24:25], v[16:17] op_sel_hi:[1,0]
	v_add_f32_e32 v4, v4, v5
	ds_read_b128 v[60:63], v88 offset:46080
	v_pk_mul_f32 v[10:11], v[26:27], v[16:17] op_sel_hi:[1,0]
	v_add_f32_dpp v4, v4, v4 quad_perm:[1,0,3,2] row_mask:0xf bank_mask:0xf bound_ctrl:1
	ds_read_b128 v[72:75], v88 offset:46848
	v_pk_fma_f32 v[8:9], v[0:1], v[20:21], v[8:9]
	v_add_f32_dpp v4, v4, v4 quad_perm:[2,3,0,1] row_mask:0xf bank_mask:0xf bound_ctrl:1
	v_pk_fma_f32 v[10:11], v[2:3], v[22:23], v[10:11]
	s_nop 0
	v_add_f32_dpp v4, v4, v4 row_ror:4 row_mask:0xf bank_mask:0xf bound_ctrl:1
	ds_read_b128 v[76:79], v88 offset:47104
	s_nop 0
	v_add_f32_dpp v4, v4, v4 row_ror:8 row_mask:0xf bank_mask:0xf bound_ctrl:1
	v_pk_fma_f32 v[0:1], v[4:5], v[32:33], v[8:9] op_sel_hi:[0,1,1]
	v_pk_fma_f32 v[2:3], v[4:5], v[34:35], v[10:11] op_sel_hi:[0,1,1]
	v_pk_mul_f32 v[6:7], v[0:1], v[36:37]
	v_pk_fma_f32 v[6:7], v[2:3], v[38:39], v[6:7]
	v_add_f32_e32 v210, v6, v7
	ds_read2st64_b32 v[18:19], v90 offset0:185 offset1:191
	v_lshlrev_b32_e32 v178, 16, v151
	v_and_b32_e32 v179, 0xffff0000, v151
	ds_write_b128 v91, v[176:179] offset:768
	s_waitcnt lgkmcnt(7)
	v_pk_mul_f32 v[4:5], v[0:1], v[48:49] neg_lo:[0,1] neg_hi:[0,1]
	ds_read_b128 v[92:95], v88 offset:48128
	v_pk_fma_f32 v[4:5], v[2:3], v[50:51], v[4:5] neg_lo:[0,1,0] neg_hi:[0,1,0]
	ds_read_b128 v[84:87], v88 offset:47872
	v_pk_mul_f32 v[8:9], v[44:45], v[16:17] op_sel:[0,1] op_sel_hi:[1,1]
	v_add_f32_e32 v4, v4, v5
	ds_read_b128 v[80:83], v88 offset:47616
	v_pk_mul_f32 v[10:11], v[46:47], v[16:17] op_sel:[0,1] op_sel_hi:[1,1]
	v_add_f32_dpp v4, v4, v4 quad_perm:[1,0,3,2] row_mask:0xf bank_mask:0xf bound_ctrl:1
	ds_read_b128 v[96:99], v88 offset:48384
	v_pk_fma_f32 v[8:9], v[0:1], v[40:41], v[8:9]
	v_add_f32_dpp v4, v4, v4 quad_perm:[2,3,0,1] row_mask:0xf bank_mask:0xf bound_ctrl:1
	v_pk_fma_f32 v[10:11], v[2:3], v[42:43], v[10:11]
	s_nop 0
	v_add_f32_dpp v4, v4, v4 row_ror:4 row_mask:0xf bank_mask:0xf bound_ctrl:1
	ds_read_b128 v[100:103], v88 offset:48640
	s_nop 0
	v_add_f32_dpp v4, v4, v4 row_ror:8 row_mask:0xf bank_mask:0xf bound_ctrl:1
	v_pk_fma_f32 v[0:1], v[4:5], v[52:53], v[8:9] op_sel_hi:[0,1,1]
	v_pk_fma_f32 v[2:3], v[4:5], v[54:55], v[10:11] op_sel_hi:[0,1,1]
	v_pk_mul_f32 v[6:7], v[0:1], v[56:57]
	v_pk_fma_f32 v[6:7], v[2:3], v[58:59], v[6:7]
	v_add_f32_e32 v211, v6, v7
	s_waitcnt lgkmcnt(0)
	s_barrier
	v_pk_mul_f32 v[4:5], v[0:1], v[68:69] neg_lo:[0,1] neg_hi:[0,1]
	ds_read_b128 v[28:31], v88 offset:512
	v_pk_fma_f32 v[4:5], v[2:3], v[70:71], v[4:5] neg_lo:[0,1,0] neg_hi:[0,1,0]
	ds_read_b128 v[24:27], v88 offset:256
	v_pk_mul_f32 v[8:9], v[64:65], v[18:19] op_sel_hi:[1,0]
	v_add_f32_e32 v4, v4, v5
	ds_read_b128 v[20:23], v88 offset:0
	v_pk_mul_f32 v[10:11], v[66:67], v[18:19] op_sel_hi:[1,0]
	v_add_f32_dpp v4, v4, v4 quad_perm:[1,0,3,2] row_mask:0xf bank_mask:0xf bound_ctrl:1
	ds_read_b128 v[32:35], v88 offset:768
	v_pk_fma_f32 v[8:9], v[0:1], v[60:61], v[8:9]
	v_add_f32_dpp v4, v4, v4 quad_perm:[2,3,0,1] row_mask:0xf bank_mask:0xf bound_ctrl:1
	v_pk_fma_f32 v[10:11], v[2:3], v[62:63], v[10:11]
	s_nop 0
	v_add_f32_dpp v4, v4, v4 row_ror:4 row_mask:0xf bank_mask:0xf bound_ctrl:1
	ds_read_b128 v[36:39], v88 offset:1024
	s_nop 0
	v_add_f32_dpp v4, v4, v4 row_ror:8 row_mask:0xf bank_mask:0xf bound_ctrl:1
	v_pk_fma_f32 v[0:1], v[4:5], v[72:73], v[8:9] op_sel_hi:[0,1,1]
	v_pk_fma_f32 v[2:3], v[4:5], v[74:75], v[10:11] op_sel_hi:[0,1,1]
	v_pk_mul_f32 v[6:7], v[0:1], v[76:77]
	v_pk_fma_f32 v[6:7], v[2:3], v[78:79], v[6:7]
	v_add_f32_e32 v212, v6, v7
	ds_read2st64_b32 v[16:17], v90 offset0:5 offset1:11
	s_waitcnt lgkmcnt(6)
	v_pk_mul_f32 v[4:5], v[0:1], v[92:93] neg_lo:[0,1] neg_hi:[0,1]
	ds_read_b128 v[48:51], v88 offset:2048
	v_pk_fma_f32 v[4:5], v[2:3], v[94:95], v[4:5] neg_lo:[0,1,0] neg_hi:[0,1,0]
	ds_read_b128 v[44:47], v88 offset:1792
	v_pk_mul_f32 v[8:9], v[84:85], v[18:19] op_sel:[0,1] op_sel_hi:[1,1]
	v_add_f32_e32 v4, v4, v5
	ds_read_b128 v[40:43], v88 offset:1536
	v_pk_mul_f32 v[10:11], v[86:87], v[18:19] op_sel:[0,1] op_sel_hi:[1,1]
	v_add_f32_dpp v4, v4, v4 quad_perm:[1,0,3,2] row_mask:0xf bank_mask:0xf bound_ctrl:1
	ds_read_b128 v[52:55], v88 offset:2304
	v_pk_fma_f32 v[8:9], v[0:1], v[80:81], v[8:9]
	v_add_f32_dpp v4, v4, v4 quad_perm:[2,3,0,1] row_mask:0xf bank_mask:0xf bound_ctrl:1
	v_pk_fma_f32 v[10:11], v[2:3], v[82:83], v[10:11]
	s_nop 0
	v_add_f32_dpp v4, v4, v4 row_ror:4 row_mask:0xf bank_mask:0xf bound_ctrl:1
	ds_read_b128 v[56:59], v88 offset:2560
	s_nop 0
	v_add_f32_dpp v4, v4, v4 row_ror:8 row_mask:0xf bank_mask:0xf bound_ctrl:1
	v_pk_fma_f32 v[0:1], v[4:5], v[96:97], v[8:9] op_sel_hi:[0,1,1]
	v_pk_fma_f32 v[2:3], v[4:5], v[98:99], v[10:11] op_sel_hi:[0,1,1]
	v_pk_mul_f32 v[6:7], v[0:1], v[100:101]
	v_pk_fma_f32 v[6:7], v[2:3], v[102:103], v[6:7]
	v_add_f32_e32 v213, v6, v7
	s_add_i32 s28, s28, 1
	s_cmp_lt_u32 s28, 16
	s_cbranch_scc1 .Lls0_loop
	s_nop 1
	s_nop 1
	v_add_f32_dpp v198, v198, v198 row_ror:8 row_mask:0xf bank_mask:0x3 bound_ctrl:1
	s_nop 1
	v_add_f32_dpp v198, v206, v206 row_ror:8 row_mask:0xf bank_mask:0xc bound_ctrl:1
	s_nop 1
	v_add_f32_dpp v199, v199, v199 row_ror:8 row_mask:0xf bank_mask:0x3 bound_ctrl:1
	s_nop 1
	v_add_f32_dpp v199, v207, v207 row_ror:8 row_mask:0xf bank_mask:0xc bound_ctrl:1
	s_nop 1
	v_add_f32_dpp v200, v200, v200 row_ror:8 row_mask:0xf bank_mask:0x3 bound_ctrl:1
	s_nop 1
	v_add_f32_dpp v200, v208, v208 row_ror:8 row_mask:0xf bank_mask:0xc bound_ctrl:1
	s_nop 1
	v_add_f32_dpp v201, v201, v201 row_ror:8 row_mask:0xf bank_mask:0x3 bound_ctrl:1
	s_nop 1
	v_add_f32_dpp v201, v209, v209 row_ror:8 row_mask:0xf bank_mask:0xc bound_ctrl:1
	s_nop 1
	v_add_f32_dpp v202, v202, v202 row_ror:8 row_mask:0xf bank_mask:0x3 bound_ctrl:1
	s_nop 1
	v_add_f32_dpp v202, v210, v210 row_ror:8 row_mask:0xf bank_mask:0xc bound_ctrl:1
	s_nop 1
	v_add_f32_dpp v203, v203, v203 row_ror:8 row_mask:0xf bank_mask:0x3 bound_ctrl:1
	s_nop 1
	v_add_f32_dpp v203, v211, v211 row_ror:8 row_mask:0xf bank_mask:0xc bound_ctrl:1
	s_nop 1
	v_add_f32_dpp v204, v204, v204 row_ror:8 row_mask:0xf bank_mask:0x3 bound_ctrl:1
	s_nop 1
	v_add_f32_dpp v204, v212, v212 row_ror:8 row_mask:0xf bank_mask:0xc bound_ctrl:1
	s_nop 1
	v_add_f32_dpp v205, v205, v205 row_ror:8 row_mask:0xf bank_mask:0x3 bound_ctrl:1
	s_nop 1
	v_add_f32_dpp v205, v213, v213 row_ror:8 row_mask:0xf bank_mask:0xc bound_ctrl:1
	s_nop 1
	v_add_f32_dpp v198, v198, v198 row_shl:4 row_mask:0xf bank_mask:0x5 bound_ctrl:1
	s_nop 1
	v_add_f32_dpp v198, v202, v202 row_shr:4 row_mask:0xf bank_mask:0xa bound_ctrl:1
	s_nop 1
	v_add_f32_dpp v199, v199, v199 row_shl:4 row_mask:0xf bank_mask:0x5 bound_ctrl:1
	s_nop 1
	v_add_f32_dpp v199, v203, v203 row_shr:4 row_mask:0xf bank_mask:0xa bound_ctrl:1
	s_nop 1
	v_add_f32_dpp v200, v200, v200 row_shl:4 row_mask:0xf bank_mask:0x5 bound_ctrl:1
	s_nop 1
	v_add_f32_dpp v200, v204, v204 row_shr:4 row_mask:0xf bank_mask:0xa bound_ctrl:1
	s_nop 1
	v_add_f32_dpp v201, v201, v201 row_shl:4 row_mask:0xf bank_mask:0x5 bound_ctrl:1
	s_nop 1
	v_add_f32_dpp v201, v205, v205 row_shr:4 row_mask:0xf bank_mask:0xa bound_ctrl:1
	s_nop 1
	v_add_f32_dpp v198, v198, v198 quad_perm:[1,0,3,2] row_mask:0xf bank_mask:0xf bound_ctrl:1
	s_nop 1
	v_add_f32_dpp v199, v199, v199 quad_perm:[1,0,3,2] row_mask:0xf bank_mask:0xf bound_ctrl:1
	v_cndmask_b32_e64 v198, v198, v199, s[30:31]
	s_nop 1
	v_add_f32_dpp v200, v200, v200 quad_perm:[1,0,3,2] row_mask:0xf bank_mask:0xf bound_ctrl:1
	s_nop 1
	v_add_f32_dpp v201, v201, v201 quad_perm:[1,0,3,2] row_mask:0xf bank_mask:0xf bound_ctrl:1
	v_cndmask_b32_e64 v200, v200, v201, s[30:31]
	s_nop 1
	v_add_f32_dpp v198, v198, v198 quad_perm:[2,3,0,1] row_mask:0xf bank_mask:0xf bound_ctrl:1
	s_nop 1
	v_add_f32_dpp v200, v200, v200 quad_perm:[2,3,0,1] row_mask:0xf bank_mask:0xf bound_ctrl:1
	v_cndmask_b32_e64 v214, v198, v200, s[34:35]
	v_cvt_pk_bf16_f32 v214, v214, v214
	global_store_short v145, v214, s[22:23]
	s_waitcnt lgkmcnt(0)
	s_branch .LBB0_906

.LBB0_1903:
	s_or_b64 exec, exec, s[0:1]
	v_readlane_b32 s0, v242, 1
	v_readlane_b32 s2, v242, 3
	v_readlane_b32 s3, v242, 4
	s_add_u32 s48, s2, 0x30f4040
	v_mbcnt_hi_u32_b32 v136, -1, v136
	s_addc_u32 s49, s3, 0
	s_add_i32 s33, 0, 0x12000
	s_waitcnt lgkmcnt(0)
	v_and_b32_e32 v0, 64, v136
	v_readlane_b32 s99, v242, 0
	s_mov_b32 s100, -1
	s_cmpk_lt_u32 s99, 96
	s_cselect_b32 s100, s99, s100
	v_mov_b32_e32 v143, s100
	s_mov_b32 s59, 0
	v_mov_b32_e32 v89, 0
	v_mov_b32_e32 v138, s33
	s_mov_b32 s40, 0x1c000
	s_movk_i32 s41, 0xfefe
	s_movk_i32 s50, 0x180
	s_movk_i32 s51, 0x580
	s_movk_i32 s45, 0x600
	v_xor_b32_e32 v139, 16, v136
	v_add_u32_e32 v140, 64, v0
	v_xor_b32_e32 v141, 32, v136
	v_mov_b32_e32 v142, 0xf149f2ca
	v_readfirstlane_b32 s99, v137
	s_cmp_lg_u32 s99, 64
	s_cbranch_scc1 .Lxbi12_skip
	buffer_inv sc1
	s_waitcnt vmcnt(0)

.LBB0_1911:
	s_or_b64 exec, exec, s[4:5]
	s_waitcnt vmcnt(0)
	v_readfirstlane_b32 s4, v1
	s_nop 1
	v_add_u32_e32 v143, s4, v0
	v_add_u32_e32 v143, 0x60, v143

.LBB0_1920:
	s_or_b64 exec, exec, s[2:3]
	s_waitcnt vmcnt(0)
	v_readfirstlane_b32 s2, v1
	s_nop 1
	v_add_u32_e32 v143, s2, v0
	v_add_u32_e32 v143, 0x60, v143
